# GATE GEMM epilogues: h and PLE-projection loads issued two row-groups ahead (counted vmcnt), row-rstd inputs loaded upfront
# speedup vs baseline: 1.0280x; 1.0006x over previous
.LBB0_747:
	ds_read_b128 v[144:147], v162
	ds_read_b128 v[148:151], v162 offset:1024
	ds_read_b128 v[152:155], v162 offset:2048
	ds_read_b128 v[156:159], v162 offset:3072
	s_add_u32 s67, s20, 0xfff80080
	s_addc_u32 s72, s21, -1
	s_cmp_eq_u32 s63, 28
	s_cselect_b32 s75, s17, s72
	s_cselect_b32 s74, s19, s67
	s_cselect_b32 s73, s54, s57
	s_cselect_b32 s72, s55, s56
	v_lshl_add_u64 v[198:199], s[20:21], 0, v[134:135]
	s_add_i32 m0, s6, 0xc000
	ds_read_b128 v[166:169], v163
	ds_read_b128 v[170:173], v163 offset:1024
	ds_read_b128 v[174:177], v163 offset:2048
	ds_read_b128 v[178:181], v163 offset:3072
	ds_read_b128 v[182:185], v163 offset:4096
	ds_read_b128 v[186:189], v163 offset:5120
	ds_read_b128 v[190:193], v163 offset:6144
	ds_read_b128 v[194:197], v163 offset:7168
	global_load_lds_dwordx4 v[198:199], off
	v_lshl_add_u64 v[198:199], s[20:21], 0, v[138:139]
	s_add_i32 m0, s6, 0xe000
	s_nop 0
	global_load_lds_dwordx4 v[198:199], off
	s_waitcnt lgkmcnt(8)
	s_barrier
	s_waitcnt lgkmcnt(0)
	s_setprio 1
	s_waitcnt lgkmcnt(0)
	v_mfma_f32_16x16x32_bf16 v[124:127], v[144:147], v[166:169], v[124:127]
	v_mfma_f32_16x16x32_bf16 v[120:123], v[152:155], v[166:169], v[120:123]
	v_mfma_f32_16x16x32_bf16 v[108:111], v[144:147], v[174:177], v[108:111]
	v_mfma_f32_16x16x32_bf16 v[104:107], v[152:155], v[174:177], v[104:107]
	v_mfma_f32_16x16x32_bf16 v[92:95], v[144:147], v[182:185], v[92:95]
	v_mfma_f32_16x16x32_bf16 v[88:91], v[152:155], v[182:185], v[88:91]
	v_mfma_f32_16x16x32_bf16 v[76:79], v[144:147], v[190:193], v[76:79]
	v_mfma_f32_16x16x32_bf16 v[72:75], v[152:155], v[190:193], v[72:75]
	v_mfma_f32_16x16x32_bf16 v[124:127], v[148:151], v[170:173], v[124:127]
	v_mfma_f32_16x16x32_bf16 v[120:123], v[156:159], v[170:173], v[120:123]
	v_mfma_f32_16x16x32_bf16 v[108:111], v[148:151], v[178:181], v[108:111]
	v_mfma_f32_16x16x32_bf16 v[104:107], v[156:159], v[178:181], v[104:107]
	v_mfma_f32_16x16x32_bf16 v[92:95], v[148:151], v[186:189], v[92:95]
	v_mfma_f32_16x16x32_bf16 v[88:91], v[156:159], v[186:189], v[88:91]
	v_mfma_f32_16x16x32_bf16 v[76:79], v[148:151], v[194:197], v[76:79]
	v_mfma_f32_16x16x32_bf16 v[72:75], v[156:159], v[194:197], v[72:75]
	s_setprio 0
	s_barrier
	s_add_i32 s67, s45, s5
	v_lshl_add_u64 v[214:215], s[72:73], 0, v[128:129]
	s_mov_b32 m0, s67
	ds_read_b128 v[198:201], v164
	ds_read_b128 v[202:205], v164 offset:1024
	ds_read_b128 v[206:209], v164 offset:2048
	ds_read_b128 v[210:213], v164 offset:3072
	global_load_lds_dwordx4 v[214:215], off
	v_lshl_add_u64 v[216:217], s[72:73], 0, v[130:131]
	s_add_i32 m0, s67, 0x2000
	s_nop 0
	global_load_lds_dwordx4 v[216:217], off
	s_barrier
	s_waitcnt lgkmcnt(0)
	s_setprio 1
	s_waitcnt lgkmcnt(0)
	v_mfma_f32_16x16x32_bf16 v[116:119], v[198:201], v[166:169], v[116:119]
	v_mfma_f32_16x16x32_bf16 v[112:115], v[206:209], v[166:169], v[112:115]
	v_mfma_f32_16x16x32_bf16 v[100:103], v[198:201], v[174:177], v[100:103]
	v_mfma_f32_16x16x32_bf16 v[96:99], v[206:209], v[174:177], v[96:99]
	v_mfma_f32_16x16x32_bf16 v[84:87], v[198:201], v[182:185], v[84:87]
	v_mfma_f32_16x16x32_bf16 v[80:83], v[206:209], v[182:185], v[80:83]
	v_mfma_f32_16x16x32_bf16 v[68:71], v[198:201], v[190:193], v[68:71]
	v_mfma_f32_16x16x32_bf16 v[64:67], v[206:209], v[190:193], v[64:67]
	v_mfma_f32_16x16x32_bf16 v[116:119], v[202:205], v[170:173], v[116:119]
	v_mfma_f32_16x16x32_bf16 v[112:115], v[210:213], v[170:173], v[112:115]
	v_mfma_f32_16x16x32_bf16 v[100:103], v[202:205], v[178:181], v[100:103]
	v_mfma_f32_16x16x32_bf16 v[96:99], v[210:213], v[178:181], v[96:99]
	v_mfma_f32_16x16x32_bf16 v[84:87], v[202:205], v[186:189], v[84:87]
	v_mfma_f32_16x16x32_bf16 v[80:83], v[210:213], v[186:189], v[80:83]
	v_mfma_f32_16x16x32_bf16 v[68:71], v[202:205], v[194:197], v[68:71]
	v_mfma_f32_16x16x32_bf16 v[64:67], v[210:213], v[194:197], v[64:67]
	s_setprio 0
	s_mov_b32 m0, s6
	v_lshl_add_u64 v[218:219], s[74:75], 0, v[128:129]
	s_barrier
	ds_read_b128 v[166:169], v163 offset:16384
	ds_read_b128 v[170:173], v163 offset:17408
	ds_read_b128 v[174:177], v163 offset:18432
	ds_read_b128 v[178:181], v163 offset:19456
	ds_read_b128 v[182:185], v163 offset:20480
	ds_read_b128 v[186:189], v163 offset:21504
	ds_read_b128 v[190:193], v163 offset:22528
	ds_read_b128 v[194:197], v163 offset:23552
	global_load_lds_dwordx4 v[218:219], off
	v_lshl_add_u64 v[220:221], s[74:75], 0, v[130:131]
	s_mov_b32 m0, s7
	s_nop 0
	global_load_lds_dwordx4 v[220:221], off
	s_barrier
	s_waitcnt lgkmcnt(0)
	s_setprio 1
	s_waitcnt lgkmcnt(0)
	v_mfma_f32_16x16x32_bf16 v[60:63], v[144:147], v[166:169], v[60:63]
	v_mfma_f32_16x16x32_bf16 v[56:59], v[152:155], v[166:169], v[56:59]
	v_mfma_f32_16x16x32_bf16 v[44:47], v[144:147], v[174:177], v[44:47]
	v_mfma_f32_16x16x32_bf16 v[40:43], v[152:155], v[174:177], v[40:43]
	v_mfma_f32_16x16x32_bf16 v[28:31], v[144:147], v[182:185], v[28:31]
	v_mfma_f32_16x16x32_bf16 v[24:27], v[152:155], v[182:185], v[24:27]
	v_mfma_f32_16x16x32_bf16 v[12:15], v[144:147], v[190:193], v[12:15]
	v_mfma_f32_16x16x32_bf16 v[8:11], v[152:155], v[190:193], v[8:11]
	v_mfma_f32_16x16x32_bf16 v[60:63], v[148:151], v[170:173], v[60:63]
	v_mfma_f32_16x16x32_bf16 v[56:59], v[156:159], v[170:173], v[56:59]
	v_mfma_f32_16x16x32_bf16 v[44:47], v[148:151], v[178:181], v[44:47]
	v_mfma_f32_16x16x32_bf16 v[40:43], v[156:159], v[178:181], v[40:43]
	v_mfma_f32_16x16x32_bf16 v[28:31], v[148:151], v[186:189], v[28:31]
	v_mfma_f32_16x16x32_bf16 v[24:27], v[156:159], v[186:189], v[24:27]
	v_mfma_f32_16x16x32_bf16 v[12:15], v[148:151], v[194:197], v[12:15]
	v_mfma_f32_16x16x32_bf16 v[8:11], v[156:159], v[194:197], v[8:11]
	s_setprio 0
	s_barrier
	s_add_u32 s76, s72, 0x80000
	s_addc_u32 s77, s73, 0
	s_add_i32 s67, s46, s5
	v_lshl_add_u64 v[144:145], s[76:77], 0, v[128:129]
	s_mov_b32 m0, s67
	s_nop 0
	global_load_lds_dwordx4 v[144:145], off
	v_lshl_add_u64 v[144:145], s[76:77], 0, v[130:131]
	s_add_i32 m0, s67, 0x2000
	s_nop 0
	global_load_lds_dwordx4 v[144:145], off
	s_waitcnt vmcnt(6)
	s_barrier
	s_setprio 1
	v_mfma_f32_16x16x32_bf16 v[52:55], v[198:201], v[166:169], v[52:55]
	v_mfma_f32_16x16x32_bf16 v[48:51], v[206:209], v[166:169], v[48:51]
	v_mfma_f32_16x16x32_bf16 v[36:39], v[198:201], v[174:177], v[36:39]
	v_mfma_f32_16x16x32_bf16 v[32:35], v[206:209], v[174:177], v[32:35]
	v_mfma_f32_16x16x32_bf16 v[20:23], v[198:201], v[182:185], v[20:23]
	v_mfma_f32_16x16x32_bf16 v[16:19], v[206:209], v[182:185], v[16:19]
	v_mfma_f32_16x16x32_bf16 v[4:7], v[198:201], v[190:193], v[4:7]
	v_mfma_f32_16x16x32_bf16 v[0:3], v[206:209], v[190:193], v[0:3]
	v_mfma_f32_16x16x32_bf16 v[52:55], v[202:205], v[170:173], v[52:55]
	v_mfma_f32_16x16x32_bf16 v[48:51], v[210:213], v[170:173], v[48:51]
	v_mfma_f32_16x16x32_bf16 v[36:39], v[202:205], v[178:181], v[36:39]
	v_mfma_f32_16x16x32_bf16 v[32:35], v[210:213], v[178:181], v[32:35]
	v_mfma_f32_16x16x32_bf16 v[20:23], v[202:205], v[186:189], v[20:23]
	v_mfma_f32_16x16x32_bf16 v[16:19], v[210:213], v[186:189], v[16:19]
	v_mfma_f32_16x16x32_bf16 v[4:7], v[202:205], v[194:197], v[4:7]
	v_mfma_f32_16x16x32_bf16 v[0:3], v[210:213], v[194:197], v[0:3]
	s_setprio 0
	s_add_i32 s67, 16, 0x18000
	v_add_u32_e32 v156, s67, v161
	s_barrier
	ds_read_b128 v[144:147], v156
	ds_read_b128 v[148:151], v156 offset:1024
	ds_read_b128 v[152:155], v156 offset:2048
	ds_read_b128 v[156:159], v156 offset:3072
	s_add_u32 s74, s74, 0x80000
	s_addc_u32 s75, s75, 0
	s_mov_b32 m0, s8
	v_lshl_add_u64 v[198:199], s[74:75], 0, v[128:129]
	ds_read_b128 v[166:169], v163 offset:32768
	ds_read_b128 v[170:173], v163 offset:33792
	ds_read_b128 v[174:177], v163 offset:34816
	ds_read_b128 v[178:181], v163 offset:35840
	ds_read_b128 v[182:185], v163 offset:36864
	ds_read_b128 v[186:189], v163 offset:37888
	ds_read_b128 v[190:193], v163 offset:38912
	ds_read_b128 v[194:197], v163 offset:39936
	global_load_lds_dwordx4 v[198:199], off
	v_lshl_add_u64 v[198:199], s[74:75], 0, v[130:131]
	s_mov_b32 m0, s9
	s_nop 0
	global_load_lds_dwordx4 v[198:199], off
	s_waitcnt lgkmcnt(8)
	s_barrier
	s_waitcnt lgkmcnt(0)
	s_setprio 1
	s_waitcnt lgkmcnt(0)
	v_mfma_f32_16x16x32_bf16 v[124:127], v[144:147], v[166:169], v[124:127]
	v_mfma_f32_16x16x32_bf16 v[120:123], v[152:155], v[166:169], v[120:123]
	v_mfma_f32_16x16x32_bf16 v[108:111], v[144:147], v[174:177], v[108:111]
	v_mfma_f32_16x16x32_bf16 v[104:107], v[152:155], v[174:177], v[104:107]
	v_mfma_f32_16x16x32_bf16 v[92:95], v[144:147], v[182:185], v[92:95]
	v_mfma_f32_16x16x32_bf16 v[88:91], v[152:155], v[182:185], v[88:91]
	v_mfma_f32_16x16x32_bf16 v[76:79], v[144:147], v[190:193], v[76:79]
	v_mfma_f32_16x16x32_bf16 v[72:75], v[152:155], v[190:193], v[72:75]
	v_mfma_f32_16x16x32_bf16 v[124:127], v[148:151], v[170:173], v[124:127]
	v_mfma_f32_16x16x32_bf16 v[120:123], v[156:159], v[170:173], v[120:123]
	v_mfma_f32_16x16x32_bf16 v[108:111], v[148:151], v[178:181], v[108:111]
	v_mfma_f32_16x16x32_bf16 v[104:107], v[156:159], v[178:181], v[104:107]
	v_mfma_f32_16x16x32_bf16 v[92:95], v[148:151], v[186:189], v[92:95]
	v_mfma_f32_16x16x32_bf16 v[88:91], v[156:159], v[186:189], v[88:91]
	v_mfma_f32_16x16x32_bf16 v[76:79], v[148:151], v[194:197], v[76:79]
	v_mfma_f32_16x16x32_bf16 v[72:75], v[156:159], v[194:197], v[72:75]
	s_setprio 0
	s_barrier
	s_add_i32 s74, 16, 0x1c000
	s_add_i32 s67, s67, s5
	v_add_u32_e32 v160, s74, v161
	v_lshl_add_u64 v[214:215], v[214:215], 0, s[60:61]
	s_mov_b32 m0, s67
	ds_read_b128 v[198:201], v160
	ds_read_b128 v[202:205], v160 offset:1024
	ds_read_b128 v[206:209], v160 offset:2048
	ds_read_b128 v[210:213], v160 offset:3072
	global_load_lds_dwordx4 v[214:215], off
	v_lshl_add_u64 v[214:215], v[216:217], 0, s[60:61]
	s_add_i32 m0, s67, 0x2000
	s_nop 0
	global_load_lds_dwordx4 v[214:215], off
	s_barrier
	s_waitcnt lgkmcnt(0)
	s_setprio 1
	s_waitcnt lgkmcnt(0)
	v_mfma_f32_16x16x32_bf16 v[116:119], v[198:201], v[166:169], v[116:119]
	v_mfma_f32_16x16x32_bf16 v[112:115], v[206:209], v[166:169], v[112:115]
	v_mfma_f32_16x16x32_bf16 v[100:103], v[198:201], v[174:177], v[100:103]
	v_mfma_f32_16x16x32_bf16 v[96:99], v[206:209], v[174:177], v[96:99]
	v_mfma_f32_16x16x32_bf16 v[84:87], v[198:201], v[182:185], v[84:87]
	v_mfma_f32_16x16x32_bf16 v[80:83], v[206:209], v[182:185], v[80:83]
	v_mfma_f32_16x16x32_bf16 v[68:71], v[198:201], v[190:193], v[68:71]
	v_mfma_f32_16x16x32_bf16 v[64:67], v[206:209], v[190:193], v[64:67]
	v_mfma_f32_16x16x32_bf16 v[116:119], v[202:205], v[170:173], v[116:119]
	v_mfma_f32_16x16x32_bf16 v[112:115], v[210:213], v[170:173], v[112:115]
	v_mfma_f32_16x16x32_bf16 v[100:103], v[202:205], v[178:181], v[100:103]
	v_mfma_f32_16x16x32_bf16 v[96:99], v[210:213], v[178:181], v[96:99]
	v_mfma_f32_16x16x32_bf16 v[84:87], v[202:205], v[186:189], v[84:87]
	v_mfma_f32_16x16x32_bf16 v[80:83], v[210:213], v[186:189], v[80:83]
	v_mfma_f32_16x16x32_bf16 v[68:71], v[202:205], v[194:197], v[68:71]
	v_mfma_f32_16x16x32_bf16 v[64:67], v[210:213], v[194:197], v[64:67]
	s_setprio 0
	s_mov_b32 m0, s26
	v_lshl_add_u64 v[214:215], v[218:219], 0, s[60:61]
	s_barrier
	ds_read_b128 v[166:169], v163 offset:49152
	ds_read_b128 v[170:173], v163 offset:50176
	ds_read_b128 v[174:177], v163 offset:51200
	ds_read_b128 v[178:181], v163 offset:52224
	ds_read_b128 v[182:185], v163 offset:53248
	ds_read_b128 v[186:189], v163 offset:54272
	ds_read_b128 v[190:193], v163 offset:55296
	ds_read_b128 v[194:197], v163 offset:56320
	global_load_lds_dwordx4 v[214:215], off
	v_lshl_add_u64 v[214:215], v[220:221], 0, s[60:61]
	s_mov_b32 m0, s27
	s_nop 0
	global_load_lds_dwordx4 v[214:215], off
	s_barrier
	s_waitcnt lgkmcnt(0)
	s_setprio 1
	s_waitcnt lgkmcnt(0)
	v_mfma_f32_16x16x32_bf16 v[60:63], v[144:147], v[166:169], v[60:63]
	v_mfma_f32_16x16x32_bf16 v[56:59], v[152:155], v[166:169], v[56:59]
	v_mfma_f32_16x16x32_bf16 v[44:47], v[144:147], v[174:177], v[44:47]
	v_mfma_f32_16x16x32_bf16 v[40:43], v[152:155], v[174:177], v[40:43]
	v_mfma_f32_16x16x32_bf16 v[28:31], v[144:147], v[182:185], v[28:31]
	v_mfma_f32_16x16x32_bf16 v[24:27], v[152:155], v[182:185], v[24:27]
	v_mfma_f32_16x16x32_bf16 v[12:15], v[144:147], v[190:193], v[12:15]
	v_mfma_f32_16x16x32_bf16 v[8:11], v[152:155], v[190:193], v[8:11]
	v_mfma_f32_16x16x32_bf16 v[60:63], v[148:151], v[170:173], v[60:63]
	v_mfma_f32_16x16x32_bf16 v[56:59], v[156:159], v[170:173], v[56:59]
	v_mfma_f32_16x16x32_bf16 v[44:47], v[148:151], v[178:181], v[44:47]
	v_mfma_f32_16x16x32_bf16 v[40:43], v[156:159], v[178:181], v[40:43]
	v_mfma_f32_16x16x32_bf16 v[28:31], v[148:151], v[186:189], v[28:31]
	v_mfma_f32_16x16x32_bf16 v[24:27], v[156:159], v[186:189], v[24:27]
	v_mfma_f32_16x16x32_bf16 v[12:15], v[148:151], v[194:197], v[12:15]
	v_mfma_f32_16x16x32_bf16 v[8:11], v[156:159], v[194:197], v[8:11]
	s_setprio 0
	s_barrier
	s_add_u32 s72, s72, 0x80080
	s_addc_u32 s73, s73, 0
	s_add_i32 s67, s74, s5
	v_lshl_add_u64 v[144:145], s[72:73], 0, v[128:129]
	s_mov_b32 m0, s67
	s_nop 0
	global_load_lds_dwordx4 v[144:145], off
	v_lshl_add_u64 v[144:145], s[72:73], 0, v[130:131]
	s_add_i32 m0, s67, 0x2000
	s_nop 0
	global_load_lds_dwordx4 v[144:145], off
	s_waitcnt vmcnt(6)
	s_barrier
	s_setprio 1
	v_mfma_f32_16x16x32_bf16 v[52:55], v[198:201], v[166:169], v[52:55]
	v_mfma_f32_16x16x32_bf16 v[48:51], v[206:209], v[166:169], v[48:51]
	v_mfma_f32_16x16x32_bf16 v[36:39], v[198:201], v[174:177], v[36:39]
	v_mfma_f32_16x16x32_bf16 v[32:35], v[206:209], v[174:177], v[32:35]
	v_mfma_f32_16x16x32_bf16 v[20:23], v[198:201], v[182:185], v[20:23]
	v_mfma_f32_16x16x32_bf16 v[16:19], v[206:209], v[182:185], v[16:19]
	v_mfma_f32_16x16x32_bf16 v[4:7], v[198:201], v[190:193], v[4:7]
	v_mfma_f32_16x16x32_bf16 v[0:3], v[206:209], v[190:193], v[0:3]
	v_mfma_f32_16x16x32_bf16 v[52:55], v[202:205], v[170:173], v[52:55]
	v_mfma_f32_16x16x32_bf16 v[48:51], v[210:213], v[170:173], v[48:51]
	v_mfma_f32_16x16x32_bf16 v[36:39], v[202:205], v[178:181], v[36:39]
	v_mfma_f32_16x16x32_bf16 v[32:35], v[210:213], v[178:181], v[32:35]
	v_mfma_f32_16x16x32_bf16 v[20:23], v[202:205], v[186:189], v[20:23]
	v_mfma_f32_16x16x32_bf16 v[16:19], v[210:213], v[186:189], v[16:19]
	v_mfma_f32_16x16x32_bf16 v[4:7], v[202:205], v[194:197], v[4:7]
	v_mfma_f32_16x16x32_bf16 v[0:3], v[210:213], v[194:197], v[0:3]
	s_setprio 0
	s_add_i32 s63, s63, 2
	s_add_u32 s20, s20, 0x100
	s_addc_u32 s21, s21, 0
	s_add_u32 s56, s56, 0x100
	s_addc_u32 s57, s57, 0
	s_cmp_gt_u32 s63, 29
	s_barrier
	s_cbranch_scc0 .LBB0_747
	v_lshl_add_u32 v154, s18, 8, v133
	v_ashrrev_i32_e32 v155, 31, v154
	s_lshl_b32 s16, s16, 8
	s_ashr_i32 s17, s16, 31
	v_mov_b32_e32 v147, s17
	v_or_b32_e32 v146, s16, v132
	v_mov_b32_e32 v144, v154
	v_mov_b32_e32 v145, v155
	v_lshl_add_u64 v[148:149], v[144:145], 2, s[64:65]
	global_load_dword v216, v[148:149], off
	v_add_u32_e32 v144, 0x10, v154
	v_mov_b32_e32 v145, v155
	v_lshl_add_u64 v[148:149], v[144:145], 2, s[64:65]
	global_load_dword v217, v[148:149], off
	v_add_u32_e32 v144, 0x20, v154
	v_mov_b32_e32 v145, v155
	v_lshl_add_u64 v[148:149], v[144:145], 2, s[64:65]
	global_load_dword v218, v[148:149], off
	v_add_u32_e32 v144, 0x30, v154
	v_mov_b32_e32 v145, v155
	v_lshl_add_u64 v[148:149], v[144:145], 2, s[64:65]
	global_load_dword v219, v[148:149], off
	v_add_u32_e32 v144, 0x80, v154
	v_mov_b32_e32 v145, v155
	v_lshl_add_u64 v[148:149], v[144:145], 2, s[64:65]
	global_load_dword v220, v[148:149], off
	v_add_u32_e32 v144, 0x90, v154
	v_mov_b32_e32 v145, v155
	v_lshl_add_u64 v[148:149], v[144:145], 2, s[64:65]
	global_load_dword v221, v[148:149], off
	v_add_u32_e32 v144, 0xa0, v154
	v_mov_b32_e32 v145, v155
	v_lshl_add_u64 v[148:149], v[144:145], 2, s[64:65]
	global_load_dword v222, v[148:149], off
	v_add_u32_e32 v144, 0xb0, v154
	v_mov_b32_e32 v145, v155
	v_lshl_add_u64 v[148:149], v[144:145], 2, s[64:65]
	global_load_dword v223, v[148:149], off
	v_mov_b32_e32 v144, v154
	v_mov_b32_e32 v145, v155
	v_lshlrev_b64 v[148:149], 11, v[144:145]
	v_lshl_add_u64 v[148:149], v[148:149], 0, v[146:147]
	v_lshl_add_u64 v[150:151], v[148:149], 2, s[28:29]
	v_lshl_add_u64 v[152:153], v[148:149], 1, s[42:43]
	global_load_dwordx2 v[184:185], v[152:153], off
	global_load_dwordx4 v[168:171], v[150:151], off
	global_load_dwordx2 v[186:187], v[152:153], off offset:32
	global_load_dwordx4 v[172:175], v[150:151], off offset:64
	global_load_dwordx2 v[188:189], v[152:153], off offset:256
	global_load_dwordx4 v[176:179], v[150:151], off offset:512
	global_load_dwordx2 v[190:191], v[152:153], off offset:288
	global_load_dwordx4 v[180:183], v[150:151], off offset:576
	v_add_u32_e32 v144, 0x10, v154
	v_mov_b32_e32 v145, v155
	v_lshlrev_b64 v[148:149], 11, v[144:145]
	v_lshl_add_u64 v[148:149], v[148:149], 0, v[146:147]
	v_lshl_add_u64 v[150:151], v[148:149], 2, s[28:29]
	v_lshl_add_u64 v[152:153], v[148:149], 1, s[42:43]
	global_load_dwordx2 v[208:209], v[152:153], off
	global_load_dwordx4 v[192:195], v[150:151], off
	global_load_dwordx2 v[210:211], v[152:153], off offset:32
	global_load_dwordx4 v[196:199], v[150:151], off offset:64
	global_load_dwordx2 v[212:213], v[152:153], off offset:256
	global_load_dwordx4 v[200:203], v[150:151], off offset:512
	global_load_dwordx2 v[214:215], v[152:153], off offset:288
	global_load_dwordx4 v[204:207], v[150:151], off offset:576
	s_waitcnt vmcnt(8)
	v_fmamk_f32 v216, v216, 0x3a000000, v165
	v_mul_f32_e32 v235, 0x4b800000, v216
	v_cmp_gt_f32_e32 vcc, s47, v216
	s_nop 1
	v_cndmask_b32_e32 v216, v216, v235, vcc
	v_rsq_f32_e32 v216, v216
	s_nop 0
	v_mul_f32_e32 v235, 0x45800000, v216
	v_cndmask_b32_e32 v234, v216, v235, vcc
	v_mov_b32_e32 v144, v154
	v_mov_b32_e32 v145, v155
	v_lshlrev_b64 v[148:149], 11, v[144:145]
	v_lshl_add_u64 v[148:149], v[148:149], 0, v[146:147]
	v_lshl_add_u64 v[150:151], v[148:149], 2, s[28:29]
	v_lshl_add_u64 v[156:157], v[148:149], 1, s[24:25]
	v_pk_mul_f32 v[124:125], v[124:125], v[234:235] op_sel_hi:[1,0]
	v_pk_mul_f32 v[126:127], v[126:127], v[234:235] op_sel_hi:[1,0]
	v_mul_f32_e32 v124, 0xbfb8aa3b, v124
	v_mul_f32_e32 v125, 0xbfb8aa3b, v125
	v_mul_f32_e32 v126, 0xbfb8aa3b, v126
	v_mul_f32_e32 v127, 0xbfb8aa3b, v127
	v_exp_f32_e32 v124, v124
	v_exp_f32_e32 v125, v125
	v_exp_f32_e32 v126, v126
	v_exp_f32_e32 v127, v127
	v_pk_add_f32 v[124:125], v[124:125], 1.0 op_sel_hi:[1,0]
	v_pk_add_f32 v[126:127], v[126:127], 1.0 op_sel_hi:[1,0]
	v_div_scale_f32 v224, s[16:17], v124, v124, 1.0
	v_rcp_f32_e32 v225, v224
	s_nop 0
	v_fma_f32 v226, -v224, v225, 1.0
	v_fmac_f32_e32 v225, v226, v225
	v_div_scale_f32 v226, vcc, 1.0, v124, 1.0
	v_mul_f32_e32 v227, v226, v225
	v_fma_f32 v228, -v224, v227, v226
	v_fmac_f32_e32 v227, v228, v225
	v_fma_f32 v224, -v224, v227, v226
	v_div_fmas_f32 v224, v224, v225, v227
	v_div_fixup_f32 v124, v224, v124, 1.0
	v_div_scale_f32 v224, s[16:17], v125, v125, 1.0
	v_rcp_f32_e32 v225, v224
	s_nop 0
	v_fma_f32 v226, -v224, v225, 1.0
	v_fmac_f32_e32 v225, v226, v225
	v_div_scale_f32 v226, vcc, 1.0, v125, 1.0
	v_mul_f32_e32 v227, v226, v225
	v_fma_f32 v228, -v224, v227, v226
	v_fmac_f32_e32 v227, v228, v225
	v_fma_f32 v224, -v224, v227, v226
	v_div_fmas_f32 v224, v224, v225, v227
	v_div_fixup_f32 v125, v224, v125, 1.0
	v_div_scale_f32 v224, s[16:17], v126, v126, 1.0
	v_rcp_f32_e32 v225, v224
	s_nop 0
	v_fma_f32 v226, -v224, v225, 1.0
	v_fmac_f32_e32 v225, v226, v225
	v_div_scale_f32 v226, vcc, 1.0, v126, 1.0
	v_mul_f32_e32 v227, v226, v225
	v_fma_f32 v228, -v224, v227, v226
	v_fmac_f32_e32 v227, v228, v225
	v_fma_f32 v224, -v224, v227, v226
	v_div_fmas_f32 v224, v224, v225, v227
	v_div_fixup_f32 v126, v224, v126, 1.0
	v_div_scale_f32 v224, s[16:17], v127, v127, 1.0
	v_rcp_f32_e32 v225, v224
	s_nop 0
	v_fma_f32 v226, -v224, v225, 1.0
	v_fmac_f32_e32 v225, v226, v225
	v_div_scale_f32 v226, vcc, 1.0, v127, 1.0
	v_mul_f32_e32 v227, v226, v225
	v_fma_f32 v228, -v224, v227, v226
	v_fmac_f32_e32 v227, v228, v225
	v_fma_f32 v224, -v224, v227, v226
	v_div_fmas_f32 v224, v224, v225, v227
	v_div_fixup_f32 v127, v224, v127, 1.0
	v_lshlrev_b32_e32 v236, 16, v184
	v_and_b32_e32 v237, 0xffff0000, v184
	v_lshlrev_b32_e32 v238, 16, v185
	v_and_b32_e32 v239, 0xffff0000, v185
	v_pk_fma_f32 v[124:125], v[124:125], v[236:237], v[168:169]
	v_pk_fma_f32 v[126:127], v[126:127], v[238:239], v[170:171]
	v_cvt_pk_bf16_f32 v159, v126, v127
	v_cvt_pk_bf16_f32 v158, v124, v125
	global_store_dwordx4 v[150:151], v[124:127], off
	global_store_dwordx2 v[156:157], v[158:159], off
	s_nop 0
	v_mul_f32_e32 v125, v125, v125
	v_mul_f32_e32 v127, v127, v127
	v_fmac_f32_e32 v125, v124, v124
	v_fmac_f32_e32 v127, v126, v126
	v_add_f32_e32 v229, v125, v127
	v_pk_mul_f32 v[120:121], v[120:121], v[234:235] op_sel_hi:[1,0]
	v_pk_mul_f32 v[122:123], v[122:123], v[234:235] op_sel_hi:[1,0]
	v_mul_f32_e32 v120, 0xbfb8aa3b, v120
	v_mul_f32_e32 v121, 0xbfb8aa3b, v121
	v_mul_f32_e32 v122, 0xbfb8aa3b, v122
	v_mul_f32_e32 v123, 0xbfb8aa3b, v123
	v_exp_f32_e32 v120, v120
	v_exp_f32_e32 v121, v121
	v_exp_f32_e32 v122, v122
	v_exp_f32_e32 v123, v123
	v_pk_add_f32 v[120:121], v[120:121], 1.0 op_sel_hi:[1,0]
	v_pk_add_f32 v[122:123], v[122:123], 1.0 op_sel_hi:[1,0]
	v_div_scale_f32 v224, s[16:17], v120, v120, 1.0
	v_rcp_f32_e32 v225, v224
	s_nop 0
	v_fma_f32 v226, -v224, v225, 1.0
	v_fmac_f32_e32 v225, v226, v225
	v_div_scale_f32 v226, vcc, 1.0, v120, 1.0
	v_mul_f32_e32 v227, v226, v225
	v_fma_f32 v228, -v224, v227, v226
	v_fmac_f32_e32 v227, v228, v225
	v_fma_f32 v224, -v224, v227, v226
	v_div_fmas_f32 v224, v224, v225, v227
	v_div_fixup_f32 v120, v224, v120, 1.0
	v_div_scale_f32 v224, s[16:17], v121, v121, 1.0
	v_rcp_f32_e32 v225, v224
	s_nop 0
	v_fma_f32 v226, -v224, v225, 1.0
	v_fmac_f32_e32 v225, v226, v225
	v_div_scale_f32 v226, vcc, 1.0, v121, 1.0
	v_mul_f32_e32 v227, v226, v225
	v_fma_f32 v228, -v224, v227, v226
	v_fmac_f32_e32 v227, v228, v225
	v_fma_f32 v224, -v224, v227, v226
	v_div_fmas_f32 v224, v224, v225, v227
	v_div_fixup_f32 v121, v224, v121, 1.0
	v_div_scale_f32 v224, s[16:17], v122, v122, 1.0
	v_rcp_f32_e32 v225, v224
	s_nop 0
	v_fma_f32 v226, -v224, v225, 1.0
	v_fmac_f32_e32 v225, v226, v225
	v_div_scale_f32 v226, vcc, 1.0, v122, 1.0
	v_mul_f32_e32 v227, v226, v225
	v_fma_f32 v228, -v224, v227, v226
	v_fmac_f32_e32 v227, v228, v225
	v_fma_f32 v224, -v224, v227, v226
	v_div_fmas_f32 v224, v224, v225, v227
	v_div_fixup_f32 v122, v224, v122, 1.0
	v_div_scale_f32 v224, s[16:17], v123, v123, 1.0
	v_rcp_f32_e32 v225, v224
	s_nop 0
	v_fma_f32 v226, -v224, v225, 1.0
	v_fmac_f32_e32 v225, v226, v225
	v_div_scale_f32 v226, vcc, 1.0, v123, 1.0
	v_mul_f32_e32 v227, v226, v225
	v_fma_f32 v228, -v224, v227, v226
	v_fmac_f32_e32 v227, v228, v225
	v_fma_f32 v224, -v224, v227, v226
	v_div_fmas_f32 v224, v224, v225, v227
	v_div_fixup_f32 v123, v224, v123, 1.0
	v_lshlrev_b32_e32 v236, 16, v186
	v_and_b32_e32 v237, 0xffff0000, v186
	v_lshlrev_b32_e32 v238, 16, v187
	v_and_b32_e32 v239, 0xffff0000, v187
	v_pk_fma_f32 v[120:121], v[120:121], v[236:237], v[172:173]
	v_pk_fma_f32 v[122:123], v[122:123], v[238:239], v[174:175]
	v_cvt_pk_bf16_f32 v159, v122, v123
	v_cvt_pk_bf16_f32 v158, v120, v121
	global_store_dwordx4 v[150:151], v[120:123], off offset:64
	global_store_dwordx2 v[156:157], v[158:159], off offset:32
	s_nop 0
	v_mul_f32_e32 v121, v121, v121
	v_mul_f32_e32 v123, v123, v123
	v_fmac_f32_e32 v121, v120, v120
	v_fmac_f32_e32 v123, v122, v122
	v_add_f32_e32 v120, v121, v123
	v_add_f32_e32 v229, v229, v120
	v_pk_mul_f32 v[116:117], v[116:117], v[234:235] op_sel_hi:[1,0]
	v_pk_mul_f32 v[118:119], v[118:119], v[234:235] op_sel_hi:[1,0]
	v_mul_f32_e32 v116, 0xbfb8aa3b, v116
	v_mul_f32_e32 v117, 0xbfb8aa3b, v117
	v_mul_f32_e32 v118, 0xbfb8aa3b, v118
	v_mul_f32_e32 v119, 0xbfb8aa3b, v119
	v_exp_f32_e32 v116, v116
	v_exp_f32_e32 v117, v117
	v_exp_f32_e32 v118, v118
	v_exp_f32_e32 v119, v119
	v_pk_add_f32 v[116:117], v[116:117], 1.0 op_sel_hi:[1,0]
	v_pk_add_f32 v[118:119], v[118:119], 1.0 op_sel_hi:[1,0]
	v_div_scale_f32 v224, s[16:17], v116, v116, 1.0
	v_rcp_f32_e32 v225, v224
	s_nop 0
	v_fma_f32 v226, -v224, v225, 1.0
	v_fmac_f32_e32 v225, v226, v225
	v_div_scale_f32 v226, vcc, 1.0, v116, 1.0
	v_mul_f32_e32 v227, v226, v225
	v_fma_f32 v228, -v224, v227, v226
	v_fmac_f32_e32 v227, v228, v225
	v_fma_f32 v224, -v224, v227, v226
	v_div_fmas_f32 v224, v224, v225, v227
	v_div_fixup_f32 v116, v224, v116, 1.0
	v_div_scale_f32 v224, s[16:17], v117, v117, 1.0
	v_rcp_f32_e32 v225, v224
	s_nop 0
	v_fma_f32 v226, -v224, v225, 1.0
	v_fmac_f32_e32 v225, v226, v225
	v_div_scale_f32 v226, vcc, 1.0, v117, 1.0
	v_mul_f32_e32 v227, v226, v225
	v_fma_f32 v228, -v224, v227, v226
	v_fmac_f32_e32 v227, v228, v225
	v_fma_f32 v224, -v224, v227, v226
	v_div_fmas_f32 v224, v224, v225, v227
	v_div_fixup_f32 v117, v224, v117, 1.0
	v_div_scale_f32 v224, s[16:17], v118, v118, 1.0
	v_rcp_f32_e32 v225, v224
	s_nop 0
	v_fma_f32 v226, -v224, v225, 1.0
	v_fmac_f32_e32 v225, v226, v225
	v_div_scale_f32 v226, vcc, 1.0, v118, 1.0
	v_mul_f32_e32 v227, v226, v225
	v_fma_f32 v228, -v224, v227, v226
	v_fmac_f32_e32 v227, v228, v225
	v_fma_f32 v224, -v224, v227, v226
	v_div_fmas_f32 v224, v224, v225, v227
	v_div_fixup_f32 v118, v224, v118, 1.0
	v_div_scale_f32 v224, s[16:17], v119, v119, 1.0
	v_rcp_f32_e32 v225, v224
	s_nop 0
	v_fma_f32 v226, -v224, v225, 1.0
	v_fmac_f32_e32 v225, v226, v225
	v_div_scale_f32 v226, vcc, 1.0, v119, 1.0
	v_mul_f32_e32 v227, v226, v225
	v_fma_f32 v228, -v224, v227, v226
	v_fmac_f32_e32 v227, v228, v225
	v_fma_f32 v224, -v224, v227, v226
	v_div_fmas_f32 v224, v224, v225, v227
	v_div_fixup_f32 v119, v224, v119, 1.0
	v_lshlrev_b32_e32 v236, 16, v188
	v_and_b32_e32 v237, 0xffff0000, v188
	v_lshlrev_b32_e32 v238, 16, v189
	v_and_b32_e32 v239, 0xffff0000, v189
	v_pk_fma_f32 v[116:117], v[116:117], v[236:237], v[176:177]
	v_pk_fma_f32 v[118:119], v[118:119], v[238:239], v[178:179]
	v_cvt_pk_bf16_f32 v159, v118, v119
	v_cvt_pk_bf16_f32 v158, v116, v117
	global_store_dwordx4 v[150:151], v[116:119], off offset:512
	global_store_dwordx2 v[156:157], v[158:159], off offset:256
	s_nop 0
	v_mul_f32_e32 v117, v117, v117
	v_mul_f32_e32 v119, v119, v119
	v_fmac_f32_e32 v117, v116, v116
	v_fmac_f32_e32 v119, v118, v118
	v_add_f32_e32 v116, v117, v119
	v_add_f32_e32 v229, v229, v116
	v_pk_mul_f32 v[112:113], v[112:113], v[234:235] op_sel_hi:[1,0]
	v_pk_mul_f32 v[114:115], v[114:115], v[234:235] op_sel_hi:[1,0]
	v_mul_f32_e32 v112, 0xbfb8aa3b, v112
	v_mul_f32_e32 v113, 0xbfb8aa3b, v113
	v_mul_f32_e32 v114, 0xbfb8aa3b, v114
	v_mul_f32_e32 v115, 0xbfb8aa3b, v115
	v_exp_f32_e32 v112, v112
	v_exp_f32_e32 v113, v113
	v_exp_f32_e32 v114, v114
	v_exp_f32_e32 v115, v115
	v_pk_add_f32 v[112:113], v[112:113], 1.0 op_sel_hi:[1,0]
	v_pk_add_f32 v[114:115], v[114:115], 1.0 op_sel_hi:[1,0]
	v_div_scale_f32 v224, s[16:17], v112, v112, 1.0
	v_rcp_f32_e32 v225, v224
	s_nop 0
	v_fma_f32 v226, -v224, v225, 1.0
	v_fmac_f32_e32 v225, v226, v225
	v_div_scale_f32 v226, vcc, 1.0, v112, 1.0
	v_mul_f32_e32 v227, v226, v225
	v_fma_f32 v228, -v224, v227, v226
	v_fmac_f32_e32 v227, v228, v225
	v_fma_f32 v224, -v224, v227, v226
	v_div_fmas_f32 v224, v224, v225, v227
	v_div_fixup_f32 v112, v224, v112, 1.0
	v_div_scale_f32 v224, s[16:17], v113, v113, 1.0
	v_rcp_f32_e32 v225, v224
	s_nop 0
	v_fma_f32 v226, -v224, v225, 1.0
	v_fmac_f32_e32 v225, v226, v225
	v_div_scale_f32 v226, vcc, 1.0, v113, 1.0
	v_mul_f32_e32 v227, v226, v225
	v_fma_f32 v228, -v224, v227, v226
	v_fmac_f32_e32 v227, v228, v225
	v_fma_f32 v224, -v224, v227, v226
	v_div_fmas_f32 v224, v224, v225, v227
	v_div_fixup_f32 v113, v224, v113, 1.0
	v_div_scale_f32 v224, s[16:17], v114, v114, 1.0
	v_rcp_f32_e32 v225, v224
	s_nop 0
	v_fma_f32 v226, -v224, v225, 1.0
	v_fmac_f32_e32 v225, v226, v225
	v_div_scale_f32 v226, vcc, 1.0, v114, 1.0
	v_mul_f32_e32 v227, v226, v225
	v_fma_f32 v228, -v224, v227, v226
	v_fmac_f32_e32 v227, v228, v225
	v_fma_f32 v224, -v224, v227, v226
	v_div_fmas_f32 v224, v224, v225, v227
	v_div_fixup_f32 v114, v224, v114, 1.0
	v_div_scale_f32 v224, s[16:17], v115, v115, 1.0
	v_rcp_f32_e32 v225, v224
	s_nop 0
	v_fma_f32 v226, -v224, v225, 1.0
	v_fmac_f32_e32 v225, v226, v225
	v_div_scale_f32 v226, vcc, 1.0, v115, 1.0
	v_mul_f32_e32 v227, v226, v225
	v_fma_f32 v228, -v224, v227, v226
	v_fmac_f32_e32 v227, v228, v225
	v_fma_f32 v224, -v224, v227, v226
	v_div_fmas_f32 v224, v224, v225, v227
	v_div_fixup_f32 v115, v224, v115, 1.0
	v_lshlrev_b32_e32 v236, 16, v190
	v_and_b32_e32 v237, 0xffff0000, v190
	v_lshlrev_b32_e32 v238, 16, v191
	v_and_b32_e32 v239, 0xffff0000, v191
	v_pk_fma_f32 v[112:113], v[112:113], v[236:237], v[180:181]
	v_pk_fma_f32 v[114:115], v[114:115], v[238:239], v[182:183]
	v_cvt_pk_bf16_f32 v159, v114, v115
	v_cvt_pk_bf16_f32 v158, v112, v113
	global_store_dwordx4 v[150:151], v[112:115], off offset:576
	global_store_dwordx2 v[156:157], v[158:159], off offset:288
	s_nop 0
	v_mul_f32_e32 v113, v113, v113
	v_mul_f32_e32 v115, v115, v115
	v_fmac_f32_e32 v113, v112, v112
	v_fmac_f32_e32 v115, v114, v114
	v_add_f32_e32 v112, v113, v115
	v_add_f32_e32 v229, v229, v112
	v_mov_b32_e32 v230, v229
	s_nop 1
	v_permlane16_swap_b32_e32 v229, v230
	v_add_f32_e32 v229, v229, v230
	v_mov_b32_e32 v230, v229
	s_nop 1
	v_permlane32_swap_b32_e32 v229, v230
	s_and_saveexec_b64 s[16:17], s[10:11]
	v_lshl_add_u64 v[156:157], v[144:145], 2, s[22:23]
	v_add_f32_e32 v229, v229, v230
	global_atomic_add_f32 v[156:157], v229, off
	s_or_b64 exec, exec, s[16:17]
	v_add_u32_e32 v144, 0x20, v154
	v_mov_b32_e32 v145, v155
	v_lshlrev_b64 v[148:149], 11, v[144:145]
	v_lshl_add_u64 v[148:149], v[148:149], 0, v[146:147]
	v_lshl_add_u64 v[150:151], v[148:149], 2, s[28:29]
	v_lshl_add_u64 v[152:153], v[148:149], 1, s[42:43]
	global_load_dwordx2 v[184:185], v[152:153], off
	global_load_dwordx4 v[168:171], v[150:151], off
	global_load_dwordx2 v[186:187], v[152:153], off offset:32
	global_load_dwordx4 v[172:175], v[150:151], off offset:64
	global_load_dwordx2 v[188:189], v[152:153], off offset:256
	global_load_dwordx4 v[176:179], v[150:151], off offset:512
	global_load_dwordx2 v[190:191], v[152:153], off offset:288
	global_load_dwordx4 v[180:183], v[150:151], off offset:576
	s_waitcnt vmcnt(17)
	v_fmamk_f32 v217, v217, 0x3a000000, v165
	v_mul_f32_e32 v235, 0x4b800000, v217
	v_cmp_gt_f32_e32 vcc, s47, v217
	s_nop 1
	v_cndmask_b32_e32 v217, v217, v235, vcc
	v_rsq_f32_e32 v217, v217
	s_nop 0
	v_mul_f32_e32 v235, 0x45800000, v217
	v_cndmask_b32_e32 v234, v217, v235, vcc
	v_add_u32_e32 v144, 0x10, v154
	v_mov_b32_e32 v145, v155
	v_lshlrev_b64 v[148:149], 11, v[144:145]
	v_lshl_add_u64 v[148:149], v[148:149], 0, v[146:147]
	v_lshl_add_u64 v[150:151], v[148:149], 2, s[28:29]
	v_lshl_add_u64 v[156:157], v[148:149], 1, s[24:25]
	v_pk_mul_f32 v[108:109], v[108:109], v[234:235] op_sel_hi:[1,0]
	v_pk_mul_f32 v[110:111], v[110:111], v[234:235] op_sel_hi:[1,0]
	v_mul_f32_e32 v108, 0xbfb8aa3b, v108
	v_mul_f32_e32 v109, 0xbfb8aa3b, v109
	v_mul_f32_e32 v110, 0xbfb8aa3b, v110
	v_mul_f32_e32 v111, 0xbfb8aa3b, v111
	v_exp_f32_e32 v108, v108
	v_exp_f32_e32 v109, v109
	v_exp_f32_e32 v110, v110
	v_exp_f32_e32 v111, v111
	v_pk_add_f32 v[108:109], v[108:109], 1.0 op_sel_hi:[1,0]
	v_pk_add_f32 v[110:111], v[110:111], 1.0 op_sel_hi:[1,0]
	v_div_scale_f32 v224, s[16:17], v108, v108, 1.0
	v_rcp_f32_e32 v225, v224
	s_nop 0
	v_fma_f32 v226, -v224, v225, 1.0
	v_fmac_f32_e32 v225, v226, v225
	v_div_scale_f32 v226, vcc, 1.0, v108, 1.0
	v_mul_f32_e32 v227, v226, v225
	v_fma_f32 v228, -v224, v227, v226
	v_fmac_f32_e32 v227, v228, v225
	v_fma_f32 v224, -v224, v227, v226
	v_div_fmas_f32 v224, v224, v225, v227
	v_div_fixup_f32 v108, v224, v108, 1.0
	v_div_scale_f32 v224, s[16:17], v109, v109, 1.0
	v_rcp_f32_e32 v225, v224
	s_nop 0
	v_fma_f32 v226, -v224, v225, 1.0
	v_fmac_f32_e32 v225, v226, v225
	v_div_scale_f32 v226, vcc, 1.0, v109, 1.0
	v_mul_f32_e32 v227, v226, v225
	v_fma_f32 v228, -v224, v227, v226
	v_fmac_f32_e32 v227, v228, v225
	v_fma_f32 v224, -v224, v227, v226
	v_div_fmas_f32 v224, v224, v225, v227
	v_div_fixup_f32 v109, v224, v109, 1.0
	v_div_scale_f32 v224, s[16:17], v110, v110, 1.0
	v_rcp_f32_e32 v225, v224
	s_nop 0
	v_fma_f32 v226, -v224, v225, 1.0
	v_fmac_f32_e32 v225, v226, v225
	v_div_scale_f32 v226, vcc, 1.0, v110, 1.0
	v_mul_f32_e32 v227, v226, v225
	v_fma_f32 v228, -v224, v227, v226
	v_fmac_f32_e32 v227, v228, v225
	v_fma_f32 v224, -v224, v227, v226
	v_div_fmas_f32 v224, v224, v225, v227
	v_div_fixup_f32 v110, v224, v110, 1.0
	v_div_scale_f32 v224, s[16:17], v111, v111, 1.0
	v_rcp_f32_e32 v225, v224
	s_nop 0
	v_fma_f32 v226, -v224, v225, 1.0
	v_fmac_f32_e32 v225, v226, v225
	v_div_scale_f32 v226, vcc, 1.0, v111, 1.0
	v_mul_f32_e32 v227, v226, v225
	v_fma_f32 v228, -v224, v227, v226
	v_fmac_f32_e32 v227, v228, v225
	v_fma_f32 v224, -v224, v227, v226
	v_div_fmas_f32 v224, v224, v225, v227
	v_div_fixup_f32 v111, v224, v111, 1.0
	v_lshlrev_b32_e32 v236, 16, v208
	v_and_b32_e32 v237, 0xffff0000, v208
	v_lshlrev_b32_e32 v238, 16, v209
	v_and_b32_e32 v239, 0xffff0000, v209
	v_pk_fma_f32 v[108:109], v[108:109], v[236:237], v[192:193]
	v_pk_fma_f32 v[110:111], v[110:111], v[238:239], v[194:195]
	v_cvt_pk_bf16_f32 v159, v110, v111
	v_cvt_pk_bf16_f32 v158, v108, v109
	global_store_dwordx4 v[150:151], v[108:111], off
	global_store_dwordx2 v[156:157], v[158:159], off
	s_nop 0
	v_mul_f32_e32 v109, v109, v109
	v_mul_f32_e32 v111, v111, v111
	v_fmac_f32_e32 v109, v108, v108
	v_fmac_f32_e32 v111, v110, v110
	v_add_f32_e32 v229, v109, v111
	v_pk_mul_f32 v[104:105], v[104:105], v[234:235] op_sel_hi:[1,0]
	v_pk_mul_f32 v[106:107], v[106:107], v[234:235] op_sel_hi:[1,0]
	v_mul_f32_e32 v104, 0xbfb8aa3b, v104
	v_mul_f32_e32 v105, 0xbfb8aa3b, v105
	v_mul_f32_e32 v106, 0xbfb8aa3b, v106
	v_mul_f32_e32 v107, 0xbfb8aa3b, v107
	v_exp_f32_e32 v104, v104
	v_exp_f32_e32 v105, v105
	v_exp_f32_e32 v106, v106
	v_exp_f32_e32 v107, v107
	v_pk_add_f32 v[104:105], v[104:105], 1.0 op_sel_hi:[1,0]
	v_pk_add_f32 v[106:107], v[106:107], 1.0 op_sel_hi:[1,0]
	v_div_scale_f32 v224, s[16:17], v104, v104, 1.0
	v_rcp_f32_e32 v225, v224
	s_nop 0
	v_fma_f32 v226, -v224, v225, 1.0
	v_fmac_f32_e32 v225, v226, v225
	v_div_scale_f32 v226, vcc, 1.0, v104, 1.0
	v_mul_f32_e32 v227, v226, v225
	v_fma_f32 v228, -v224, v227, v226
	v_fmac_f32_e32 v227, v228, v225
	v_fma_f32 v224, -v224, v227, v226
	v_div_fmas_f32 v224, v224, v225, v227
	v_div_fixup_f32 v104, v224, v104, 1.0
	v_div_scale_f32 v224, s[16:17], v105, v105, 1.0
	v_rcp_f32_e32 v225, v224
	s_nop 0
	v_fma_f32 v226, -v224, v225, 1.0
	v_fmac_f32_e32 v225, v226, v225
	v_div_scale_f32 v226, vcc, 1.0, v105, 1.0
	v_mul_f32_e32 v227, v226, v225
	v_fma_f32 v228, -v224, v227, v226
	v_fmac_f32_e32 v227, v228, v225
	v_fma_f32 v224, -v224, v227, v226
	v_div_fmas_f32 v224, v224, v225, v227
	v_div_fixup_f32 v105, v224, v105, 1.0
	v_div_scale_f32 v224, s[16:17], v106, v106, 1.0
	v_rcp_f32_e32 v225, v224
	s_nop 0
	v_fma_f32 v226, -v224, v225, 1.0
	v_fmac_f32_e32 v225, v226, v225
	v_div_scale_f32 v226, vcc, 1.0, v106, 1.0
	v_mul_f32_e32 v227, v226, v225
	v_fma_f32 v228, -v224, v227, v226
	v_fmac_f32_e32 v227, v228, v225
	v_fma_f32 v224, -v224, v227, v226
	v_div_fmas_f32 v224, v224, v225, v227
	v_div_fixup_f32 v106, v224, v106, 1.0
	v_div_scale_f32 v224, s[16:17], v107, v107, 1.0
	v_rcp_f32_e32 v225, v224
	s_nop 0
	v_fma_f32 v226, -v224, v225, 1.0
	v_fmac_f32_e32 v225, v226, v225
	v_div_scale_f32 v226, vcc, 1.0, v107, 1.0
	v_mul_f32_e32 v227, v226, v225
	v_fma_f32 v228, -v224, v227, v226
	v_fmac_f32_e32 v227, v228, v225
	v_fma_f32 v224, -v224, v227, v226
	v_div_fmas_f32 v224, v224, v225, v227
	v_div_fixup_f32 v107, v224, v107, 1.0
	v_lshlrev_b32_e32 v236, 16, v210
	v_and_b32_e32 v237, 0xffff0000, v210
	v_lshlrev_b32_e32 v238, 16, v211
	v_and_b32_e32 v239, 0xffff0000, v211
	v_pk_fma_f32 v[104:105], v[104:105], v[236:237], v[196:197]
	v_pk_fma_f32 v[106:107], v[106:107], v[238:239], v[198:199]
	v_cvt_pk_bf16_f32 v159, v106, v107
	v_cvt_pk_bf16_f32 v158, v104, v105
	global_store_dwordx4 v[150:151], v[104:107], off offset:64
	global_store_dwordx2 v[156:157], v[158:159], off offset:32
	s_nop 0
	v_mul_f32_e32 v105, v105, v105
	v_mul_f32_e32 v107, v107, v107
	v_fmac_f32_e32 v105, v104, v104
	v_fmac_f32_e32 v107, v106, v106
	v_add_f32_e32 v104, v105, v107
	v_add_f32_e32 v229, v229, v104
	v_pk_mul_f32 v[100:101], v[100:101], v[234:235] op_sel_hi:[1,0]
	v_pk_mul_f32 v[102:103], v[102:103], v[234:235] op_sel_hi:[1,0]
	v_mul_f32_e32 v100, 0xbfb8aa3b, v100
	v_mul_f32_e32 v101, 0xbfb8aa3b, v101
	v_mul_f32_e32 v102, 0xbfb8aa3b, v102
	v_mul_f32_e32 v103, 0xbfb8aa3b, v103
	v_exp_f32_e32 v100, v100
	v_exp_f32_e32 v101, v101
	v_exp_f32_e32 v102, v102
	v_exp_f32_e32 v103, v103
	v_pk_add_f32 v[100:101], v[100:101], 1.0 op_sel_hi:[1,0]
	v_pk_add_f32 v[102:103], v[102:103], 1.0 op_sel_hi:[1,0]
	v_div_scale_f32 v224, s[16:17], v100, v100, 1.0
	v_rcp_f32_e32 v225, v224
	s_nop 0
	v_fma_f32 v226, -v224, v225, 1.0
	v_fmac_f32_e32 v225, v226, v225
	v_div_scale_f32 v226, vcc, 1.0, v100, 1.0
	v_mul_f32_e32 v227, v226, v225
	v_fma_f32 v228, -v224, v227, v226
	v_fmac_f32_e32 v227, v228, v225
	v_fma_f32 v224, -v224, v227, v226
	v_div_fmas_f32 v224, v224, v225, v227
	v_div_fixup_f32 v100, v224, v100, 1.0
	v_div_scale_f32 v224, s[16:17], v101, v101, 1.0
	v_rcp_f32_e32 v225, v224
	s_nop 0
	v_fma_f32 v226, -v224, v225, 1.0
	v_fmac_f32_e32 v225, v226, v225
	v_div_scale_f32 v226, vcc, 1.0, v101, 1.0
	v_mul_f32_e32 v227, v226, v225
	v_fma_f32 v228, -v224, v227, v226
	v_fmac_f32_e32 v227, v228, v225
	v_fma_f32 v224, -v224, v227, v226
	v_div_fmas_f32 v224, v224, v225, v227
	v_div_fixup_f32 v101, v224, v101, 1.0
	v_div_scale_f32 v224, s[16:17], v102, v102, 1.0
	v_rcp_f32_e32 v225, v224
	s_nop 0
	v_fma_f32 v226, -v224, v225, 1.0
	v_fmac_f32_e32 v225, v226, v225
	v_div_scale_f32 v226, vcc, 1.0, v102, 1.0
	v_mul_f32_e32 v227, v226, v225
	v_fma_f32 v228, -v224, v227, v226
	v_fmac_f32_e32 v227, v228, v225
	v_fma_f32 v224, -v224, v227, v226
	v_div_fmas_f32 v224, v224, v225, v227
	v_div_fixup_f32 v102, v224, v102, 1.0
	v_div_scale_f32 v224, s[16:17], v103, v103, 1.0
	v_rcp_f32_e32 v225, v224
	s_nop 0
	v_fma_f32 v226, -v224, v225, 1.0
	v_fmac_f32_e32 v225, v226, v225
	v_div_scale_f32 v226, vcc, 1.0, v103, 1.0
	v_mul_f32_e32 v227, v226, v225
	v_fma_f32 v228, -v224, v227, v226
	v_fmac_f32_e32 v227, v228, v225
	v_fma_f32 v224, -v224, v227, v226
	v_div_fmas_f32 v224, v224, v225, v227
	v_div_fixup_f32 v103, v224, v103, 1.0
	v_lshlrev_b32_e32 v236, 16, v212
	v_and_b32_e32 v237, 0xffff0000, v212
	v_lshlrev_b32_e32 v238, 16, v213
	v_and_b32_e32 v239, 0xffff0000, v213
	v_pk_fma_f32 v[100:101], v[100:101], v[236:237], v[200:201]
	v_pk_fma_f32 v[102:103], v[102:103], v[238:239], v[202:203]
	v_cvt_pk_bf16_f32 v159, v102, v103
	v_cvt_pk_bf16_f32 v158, v100, v101
	global_store_dwordx4 v[150:151], v[100:103], off offset:512
	global_store_dwordx2 v[156:157], v[158:159], off offset:256
	s_nop 0
	v_mul_f32_e32 v101, v101, v101
	v_mul_f32_e32 v103, v103, v103
	v_fmac_f32_e32 v101, v100, v100
	v_fmac_f32_e32 v103, v102, v102
	v_add_f32_e32 v100, v101, v103
	v_add_f32_e32 v229, v229, v100
	v_pk_mul_f32 v[96:97], v[96:97], v[234:235] op_sel_hi:[1,0]
	v_pk_mul_f32 v[98:99], v[98:99], v[234:235] op_sel_hi:[1,0]
	v_mul_f32_e32 v96, 0xbfb8aa3b, v96
	v_mul_f32_e32 v97, 0xbfb8aa3b, v97
	v_mul_f32_e32 v98, 0xbfb8aa3b, v98
	v_mul_f32_e32 v99, 0xbfb8aa3b, v99
	v_exp_f32_e32 v96, v96
	v_exp_f32_e32 v97, v97
	v_exp_f32_e32 v98, v98
	v_exp_f32_e32 v99, v99
	v_pk_add_f32 v[96:97], v[96:97], 1.0 op_sel_hi:[1,0]
	v_pk_add_f32 v[98:99], v[98:99], 1.0 op_sel_hi:[1,0]
	v_div_scale_f32 v224, s[16:17], v96, v96, 1.0
	v_rcp_f32_e32 v225, v224
	s_nop 0
	v_fma_f32 v226, -v224, v225, 1.0
	v_fmac_f32_e32 v225, v226, v225
	v_div_scale_f32 v226, vcc, 1.0, v96, 1.0
	v_mul_f32_e32 v227, v226, v225
	v_fma_f32 v228, -v224, v227, v226
	v_fmac_f32_e32 v227, v228, v225
	v_fma_f32 v224, -v224, v227, v226
	v_div_fmas_f32 v224, v224, v225, v227
	v_div_fixup_f32 v96, v224, v96, 1.0
	v_div_scale_f32 v224, s[16:17], v97, v97, 1.0
	v_rcp_f32_e32 v225, v224
	s_nop 0
	v_fma_f32 v226, -v224, v225, 1.0
	v_fmac_f32_e32 v225, v226, v225
	v_div_scale_f32 v226, vcc, 1.0, v97, 1.0
	v_mul_f32_e32 v227, v226, v225
	v_fma_f32 v228, -v224, v227, v226
	v_fmac_f32_e32 v227, v228, v225
	v_fma_f32 v224, -v224, v227, v226
	v_div_fmas_f32 v224, v224, v225, v227
	v_div_fixup_f32 v97, v224, v97, 1.0
	v_div_scale_f32 v224, s[16:17], v98, v98, 1.0
	v_rcp_f32_e32 v225, v224
	s_nop 0
	v_fma_f32 v226, -v224, v225, 1.0
	v_fmac_f32_e32 v225, v226, v225
	v_div_scale_f32 v226, vcc, 1.0, v98, 1.0
	v_mul_f32_e32 v227, v226, v225
	v_fma_f32 v228, -v224, v227, v226
	v_fmac_f32_e32 v227, v228, v225
	v_fma_f32 v224, -v224, v227, v226
	v_div_fmas_f32 v224, v224, v225, v227
	v_div_fixup_f32 v98, v224, v98, 1.0
	v_div_scale_f32 v224, s[16:17], v99, v99, 1.0
	v_rcp_f32_e32 v225, v224
	s_nop 0
	v_fma_f32 v226, -v224, v225, 1.0
	v_fmac_f32_e32 v225, v226, v225
	v_div_scale_f32 v226, vcc, 1.0, v99, 1.0
	v_mul_f32_e32 v227, v226, v225
	v_fma_f32 v228, -v224, v227, v226
	v_fmac_f32_e32 v227, v228, v225
	v_fma_f32 v224, -v224, v227, v226
	v_div_fmas_f32 v224, v224, v225, v227
	v_div_fixup_f32 v99, v224, v99, 1.0
	v_lshlrev_b32_e32 v236, 16, v214
	v_and_b32_e32 v237, 0xffff0000, v214
	v_lshlrev_b32_e32 v238, 16, v215
	v_and_b32_e32 v239, 0xffff0000, v215
	v_pk_fma_f32 v[96:97], v[96:97], v[236:237], v[204:205]
	v_pk_fma_f32 v[98:99], v[98:99], v[238:239], v[206:207]
	v_cvt_pk_bf16_f32 v159, v98, v99
	v_cvt_pk_bf16_f32 v158, v96, v97
	global_store_dwordx4 v[150:151], v[96:99], off offset:576
	global_store_dwordx2 v[156:157], v[158:159], off offset:288
	s_nop 0
	v_mul_f32_e32 v97, v97, v97
	v_mul_f32_e32 v99, v99, v99
	v_fmac_f32_e32 v97, v96, v96
	v_fmac_f32_e32 v99, v98, v98
	v_add_f32_e32 v96, v97, v99
	v_add_f32_e32 v229, v229, v96
	v_mov_b32_e32 v230, v229
	s_nop 1
	v_permlane16_swap_b32_e32 v229, v230
	v_add_f32_e32 v229, v229, v230
	v_mov_b32_e32 v230, v229
	s_nop 1
	v_permlane32_swap_b32_e32 v229, v230
	s_and_saveexec_b64 s[16:17], s[10:11]
	v_lshl_add_u64 v[156:157], v[144:145], 2, s[22:23]
	v_add_f32_e32 v229, v229, v230
	global_atomic_add_f32 v[156:157], v229, off
	s_or_b64 exec, exec, s[16:17]
	v_add_u32_e32 v144, 0x30, v154
	v_mov_b32_e32 v145, v155
	v_lshlrev_b64 v[148:149], 11, v[144:145]
	v_lshl_add_u64 v[148:149], v[148:149], 0, v[146:147]
	v_lshl_add_u64 v[150:151], v[148:149], 2, s[28:29]
	v_lshl_add_u64 v[152:153], v[148:149], 1, s[42:43]
	global_load_dwordx2 v[208:209], v[152:153], off
	global_load_dwordx4 v[192:195], v[150:151], off
	global_load_dwordx2 v[210:211], v[152:153], off offset:32
	global_load_dwordx4 v[196:199], v[150:151], off offset:64
	global_load_dwordx2 v[212:213], v[152:153], off offset:256
	global_load_dwordx4 v[200:203], v[150:151], off offset:512
	global_load_dwordx2 v[214:215], v[152:153], off offset:288
	global_load_dwordx4 v[204:207], v[150:151], off offset:576
	s_waitcnt vmcnt(17)
	v_fmamk_f32 v218, v218, 0x3a000000, v165
	v_mul_f32_e32 v235, 0x4b800000, v218
	v_cmp_gt_f32_e32 vcc, s47, v218
	s_nop 1
	v_cndmask_b32_e32 v218, v218, v235, vcc
	v_rsq_f32_e32 v218, v218
	s_nop 0
	v_mul_f32_e32 v235, 0x45800000, v218
	v_cndmask_b32_e32 v234, v218, v235, vcc
	v_add_u32_e32 v144, 0x20, v154
	v_mov_b32_e32 v145, v155
	v_lshlrev_b64 v[148:149], 11, v[144:145]
	v_lshl_add_u64 v[148:149], v[148:149], 0, v[146:147]
	v_lshl_add_u64 v[150:151], v[148:149], 2, s[28:29]
	v_lshl_add_u64 v[156:157], v[148:149], 1, s[24:25]
	v_pk_mul_f32 v[92:93], v[92:93], v[234:235] op_sel_hi:[1,0]
	v_pk_mul_f32 v[94:95], v[94:95], v[234:235] op_sel_hi:[1,0]
	v_mul_f32_e32 v92, 0xbfb8aa3b, v92
	v_mul_f32_e32 v93, 0xbfb8aa3b, v93
	v_mul_f32_e32 v94, 0xbfb8aa3b, v94
	v_mul_f32_e32 v95, 0xbfb8aa3b, v95
	v_exp_f32_e32 v92, v92
	v_exp_f32_e32 v93, v93
	v_exp_f32_e32 v94, v94
	v_exp_f32_e32 v95, v95
	v_pk_add_f32 v[92:93], v[92:93], 1.0 op_sel_hi:[1,0]
	v_pk_add_f32 v[94:95], v[94:95], 1.0 op_sel_hi:[1,0]
	v_div_scale_f32 v224, s[16:17], v92, v92, 1.0
	v_rcp_f32_e32 v225, v224
	s_nop 0
	v_fma_f32 v226, -v224, v225, 1.0
	v_fmac_f32_e32 v225, v226, v225
	v_div_scale_f32 v226, vcc, 1.0, v92, 1.0
	v_mul_f32_e32 v227, v226, v225
	v_fma_f32 v228, -v224, v227, v226
	v_fmac_f32_e32 v227, v228, v225
	v_fma_f32 v224, -v224, v227, v226
	v_div_fmas_f32 v224, v224, v225, v227
	v_div_fixup_f32 v92, v224, v92, 1.0
	v_div_scale_f32 v224, s[16:17], v93, v93, 1.0
	v_rcp_f32_e32 v225, v224
	s_nop 0
	v_fma_f32 v226, -v224, v225, 1.0
	v_fmac_f32_e32 v225, v226, v225
	v_div_scale_f32 v226, vcc, 1.0, v93, 1.0
	v_mul_f32_e32 v227, v226, v225
	v_fma_f32 v228, -v224, v227, v226
	v_fmac_f32_e32 v227, v228, v225
	v_fma_f32 v224, -v224, v227, v226
	v_div_fmas_f32 v224, v224, v225, v227
	v_div_fixup_f32 v93, v224, v93, 1.0
	v_div_scale_f32 v224, s[16:17], v94, v94, 1.0
	v_rcp_f32_e32 v225, v224
	s_nop 0
	v_fma_f32 v226, -v224, v225, 1.0
	v_fmac_f32_e32 v225, v226, v225
	v_div_scale_f32 v226, vcc, 1.0, v94, 1.0
	v_mul_f32_e32 v227, v226, v225
	v_fma_f32 v228, -v224, v227, v226
	v_fmac_f32_e32 v227, v228, v225
	v_fma_f32 v224, -v224, v227, v226
	v_div_fmas_f32 v224, v224, v225, v227
	v_div_fixup_f32 v94, v224, v94, 1.0
	v_div_scale_f32 v224, s[16:17], v95, v95, 1.0
	v_rcp_f32_e32 v225, v224
	s_nop 0
	v_fma_f32 v226, -v224, v225, 1.0
	v_fmac_f32_e32 v225, v226, v225
	v_div_scale_f32 v226, vcc, 1.0, v95, 1.0
	v_mul_f32_e32 v227, v226, v225
	v_fma_f32 v228, -v224, v227, v226
	v_fmac_f32_e32 v227, v228, v225
	v_fma_f32 v224, -v224, v227, v226
	v_div_fmas_f32 v224, v224, v225, v227
	v_div_fixup_f32 v95, v224, v95, 1.0
	v_lshlrev_b32_e32 v236, 16, v184
	v_and_b32_e32 v237, 0xffff0000, v184
	v_lshlrev_b32_e32 v238, 16, v185
	v_and_b32_e32 v239, 0xffff0000, v185
	v_pk_fma_f32 v[92:93], v[92:93], v[236:237], v[168:169]
	v_pk_fma_f32 v[94:95], v[94:95], v[238:239], v[170:171]
	v_cvt_pk_bf16_f32 v159, v94, v95
	v_cvt_pk_bf16_f32 v158, v92, v93
	global_store_dwordx4 v[150:151], v[92:95], off
	global_store_dwordx2 v[156:157], v[158:159], off
	s_nop 0
	v_mul_f32_e32 v93, v93, v93
	v_mul_f32_e32 v95, v95, v95
	v_fmac_f32_e32 v93, v92, v92
	v_fmac_f32_e32 v95, v94, v94
	v_add_f32_e32 v229, v93, v95
	v_pk_mul_f32 v[88:89], v[88:89], v[234:235] op_sel_hi:[1,0]
	v_pk_mul_f32 v[90:91], v[90:91], v[234:235] op_sel_hi:[1,0]
	v_mul_f32_e32 v88, 0xbfb8aa3b, v88
	v_mul_f32_e32 v89, 0xbfb8aa3b, v89
	v_mul_f32_e32 v90, 0xbfb8aa3b, v90
	v_mul_f32_e32 v91, 0xbfb8aa3b, v91
	v_exp_f32_e32 v88, v88
	v_exp_f32_e32 v89, v89
	v_exp_f32_e32 v90, v90
	v_exp_f32_e32 v91, v91
	v_pk_add_f32 v[88:89], v[88:89], 1.0 op_sel_hi:[1,0]
	v_pk_add_f32 v[90:91], v[90:91], 1.0 op_sel_hi:[1,0]
	v_div_scale_f32 v224, s[16:17], v88, v88, 1.0
	v_rcp_f32_e32 v225, v224
	s_nop 0
	v_fma_f32 v226, -v224, v225, 1.0
	v_fmac_f32_e32 v225, v226, v225
	v_div_scale_f32 v226, vcc, 1.0, v88, 1.0
	v_mul_f32_e32 v227, v226, v225
	v_fma_f32 v228, -v224, v227, v226
	v_fmac_f32_e32 v227, v228, v225
	v_fma_f32 v224, -v224, v227, v226
	v_div_fmas_f32 v224, v224, v225, v227
	v_div_fixup_f32 v88, v224, v88, 1.0
	v_div_scale_f32 v224, s[16:17], v89, v89, 1.0
	v_rcp_f32_e32 v225, v224
	s_nop 0
	v_fma_f32 v226, -v224, v225, 1.0
	v_fmac_f32_e32 v225, v226, v225
	v_div_scale_f32 v226, vcc, 1.0, v89, 1.0
	v_mul_f32_e32 v227, v226, v225
	v_fma_f32 v228, -v224, v227, v226
	v_fmac_f32_e32 v227, v228, v225
	v_fma_f32 v224, -v224, v227, v226
	v_div_fmas_f32 v224, v224, v225, v227
	v_div_fixup_f32 v89, v224, v89, 1.0
	v_div_scale_f32 v224, s[16:17], v90, v90, 1.0
	v_rcp_f32_e32 v225, v224
	s_nop 0
	v_fma_f32 v226, -v224, v225, 1.0
	v_fmac_f32_e32 v225, v226, v225
	v_div_scale_f32 v226, vcc, 1.0, v90, 1.0
	v_mul_f32_e32 v227, v226, v225
	v_fma_f32 v228, -v224, v227, v226
	v_fmac_f32_e32 v227, v228, v225
	v_fma_f32 v224, -v224, v227, v226
	v_div_fmas_f32 v224, v224, v225, v227
	v_div_fixup_f32 v90, v224, v90, 1.0
	v_div_scale_f32 v224, s[16:17], v91, v91, 1.0
	v_rcp_f32_e32 v225, v224
	s_nop 0
	v_fma_f32 v226, -v224, v225, 1.0
	v_fmac_f32_e32 v225, v226, v225
	v_div_scale_f32 v226, vcc, 1.0, v91, 1.0
	v_mul_f32_e32 v227, v226, v225
	v_fma_f32 v228, -v224, v227, v226
	v_fmac_f32_e32 v227, v228, v225
	v_fma_f32 v224, -v224, v227, v226
	v_div_fmas_f32 v224, v224, v225, v227
	v_div_fixup_f32 v91, v224, v91, 1.0
	v_lshlrev_b32_e32 v236, 16, v186
	v_and_b32_e32 v237, 0xffff0000, v186
	v_lshlrev_b32_e32 v238, 16, v187
	v_and_b32_e32 v239, 0xffff0000, v187
	v_pk_fma_f32 v[88:89], v[88:89], v[236:237], v[172:173]
	v_pk_fma_f32 v[90:91], v[90:91], v[238:239], v[174:175]
	v_cvt_pk_bf16_f32 v159, v90, v91
	v_cvt_pk_bf16_f32 v158, v88, v89
	global_store_dwordx4 v[150:151], v[88:91], off offset:64
	global_store_dwordx2 v[156:157], v[158:159], off offset:32
	s_nop 0
	v_mul_f32_e32 v89, v89, v89
	v_mul_f32_e32 v91, v91, v91
	v_fmac_f32_e32 v89, v88, v88
	v_fmac_f32_e32 v91, v90, v90
	v_add_f32_e32 v88, v89, v91
	v_add_f32_e32 v229, v229, v88
	v_pk_mul_f32 v[84:85], v[84:85], v[234:235] op_sel_hi:[1,0]
	v_pk_mul_f32 v[86:87], v[86:87], v[234:235] op_sel_hi:[1,0]
	v_mul_f32_e32 v84, 0xbfb8aa3b, v84
	v_mul_f32_e32 v85, 0xbfb8aa3b, v85
	v_mul_f32_e32 v86, 0xbfb8aa3b, v86
	v_mul_f32_e32 v87, 0xbfb8aa3b, v87
	v_exp_f32_e32 v84, v84
	v_exp_f32_e32 v85, v85
	v_exp_f32_e32 v86, v86
	v_exp_f32_e32 v87, v87
	v_pk_add_f32 v[84:85], v[84:85], 1.0 op_sel_hi:[1,0]
	v_pk_add_f32 v[86:87], v[86:87], 1.0 op_sel_hi:[1,0]
	v_div_scale_f32 v224, s[16:17], v84, v84, 1.0
	v_rcp_f32_e32 v225, v224
	s_nop 0
	v_fma_f32 v226, -v224, v225, 1.0
	v_fmac_f32_e32 v225, v226, v225
	v_div_scale_f32 v226, vcc, 1.0, v84, 1.0
	v_mul_f32_e32 v227, v226, v225
	v_fma_f32 v228, -v224, v227, v226
	v_fmac_f32_e32 v227, v228, v225
	v_fma_f32 v224, -v224, v227, v226
	v_div_fmas_f32 v224, v224, v225, v227
	v_div_fixup_f32 v84, v224, v84, 1.0
	v_div_scale_f32 v224, s[16:17], v85, v85, 1.0
	v_rcp_f32_e32 v225, v224
	s_nop 0
	v_fma_f32 v226, -v224, v225, 1.0
	v_fmac_f32_e32 v225, v226, v225
	v_div_scale_f32 v226, vcc, 1.0, v85, 1.0
	v_mul_f32_e32 v227, v226, v225
	v_fma_f32 v228, -v224, v227, v226
	v_fmac_f32_e32 v227, v228, v225
	v_fma_f32 v224, -v224, v227, v226
	v_div_fmas_f32 v224, v224, v225, v227
	v_div_fixup_f32 v85, v224, v85, 1.0
	v_div_scale_f32 v224, s[16:17], v86, v86, 1.0
	v_rcp_f32_e32 v225, v224
	s_nop 0
	v_fma_f32 v226, -v224, v225, 1.0
	v_fmac_f32_e32 v225, v226, v225
	v_div_scale_f32 v226, vcc, 1.0, v86, 1.0
	v_mul_f32_e32 v227, v226, v225
	v_fma_f32 v228, -v224, v227, v226
	v_fmac_f32_e32 v227, v228, v225
	v_fma_f32 v224, -v224, v227, v226
	v_div_fmas_f32 v224, v224, v225, v227
	v_div_fixup_f32 v86, v224, v86, 1.0
	v_div_scale_f32 v224, s[16:17], v87, v87, 1.0
	v_rcp_f32_e32 v225, v224
	s_nop 0
	v_fma_f32 v226, -v224, v225, 1.0
	v_fmac_f32_e32 v225, v226, v225
	v_div_scale_f32 v226, vcc, 1.0, v87, 1.0
	v_mul_f32_e32 v227, v226, v225
	v_fma_f32 v228, -v224, v227, v226
	v_fmac_f32_e32 v227, v228, v225
	v_fma_f32 v224, -v224, v227, v226
	v_div_fmas_f32 v224, v224, v225, v227
	v_div_fixup_f32 v87, v224, v87, 1.0
	v_lshlrev_b32_e32 v236, 16, v188
	v_and_b32_e32 v237, 0xffff0000, v188
	v_lshlrev_b32_e32 v238, 16, v189
	v_and_b32_e32 v239, 0xffff0000, v189
	v_pk_fma_f32 v[84:85], v[84:85], v[236:237], v[176:177]
	v_pk_fma_f32 v[86:87], v[86:87], v[238:239], v[178:179]
	v_cvt_pk_bf16_f32 v159, v86, v87
	v_cvt_pk_bf16_f32 v158, v84, v85
	global_store_dwordx4 v[150:151], v[84:87], off offset:512
	global_store_dwordx2 v[156:157], v[158:159], off offset:256
	s_nop 0
	v_mul_f32_e32 v85, v85, v85
	v_mul_f32_e32 v87, v87, v87
	v_fmac_f32_e32 v85, v84, v84
	v_fmac_f32_e32 v87, v86, v86
	v_add_f32_e32 v84, v85, v87
	v_add_f32_e32 v229, v229, v84
	v_pk_mul_f32 v[80:81], v[80:81], v[234:235] op_sel_hi:[1,0]
	v_pk_mul_f32 v[82:83], v[82:83], v[234:235] op_sel_hi:[1,0]
	v_mul_f32_e32 v80, 0xbfb8aa3b, v80
	v_mul_f32_e32 v81, 0xbfb8aa3b, v81
	v_mul_f32_e32 v82, 0xbfb8aa3b, v82
	v_mul_f32_e32 v83, 0xbfb8aa3b, v83
	v_exp_f32_e32 v80, v80
	v_exp_f32_e32 v81, v81
	v_exp_f32_e32 v82, v82
	v_exp_f32_e32 v83, v83
	v_pk_add_f32 v[80:81], v[80:81], 1.0 op_sel_hi:[1,0]
	v_pk_add_f32 v[82:83], v[82:83], 1.0 op_sel_hi:[1,0]
	v_div_scale_f32 v224, s[16:17], v80, v80, 1.0
	v_rcp_f32_e32 v225, v224
	s_nop 0
	v_fma_f32 v226, -v224, v225, 1.0
	v_fmac_f32_e32 v225, v226, v225
	v_div_scale_f32 v226, vcc, 1.0, v80, 1.0
	v_mul_f32_e32 v227, v226, v225
	v_fma_f32 v228, -v224, v227, v226
	v_fmac_f32_e32 v227, v228, v225
	v_fma_f32 v224, -v224, v227, v226
	v_div_fmas_f32 v224, v224, v225, v227
	v_div_fixup_f32 v80, v224, v80, 1.0
	v_div_scale_f32 v224, s[16:17], v81, v81, 1.0
	v_rcp_f32_e32 v225, v224
	s_nop 0
	v_fma_f32 v226, -v224, v225, 1.0
	v_fmac_f32_e32 v225, v226, v225
	v_div_scale_f32 v226, vcc, 1.0, v81, 1.0
	v_mul_f32_e32 v227, v226, v225
	v_fma_f32 v228, -v224, v227, v226
	v_fmac_f32_e32 v227, v228, v225
	v_fma_f32 v224, -v224, v227, v226
	v_div_fmas_f32 v224, v224, v225, v227
	v_div_fixup_f32 v81, v224, v81, 1.0
	v_div_scale_f32 v224, s[16:17], v82, v82, 1.0
	v_rcp_f32_e32 v225, v224
	s_nop 0
	v_fma_f32 v226, -v224, v225, 1.0
	v_fmac_f32_e32 v225, v226, v225
	v_div_scale_f32 v226, vcc, 1.0, v82, 1.0
	v_mul_f32_e32 v227, v226, v225
	v_fma_f32 v228, -v224, v227, v226
	v_fmac_f32_e32 v227, v228, v225
	v_fma_f32 v224, -v224, v227, v226
	v_div_fmas_f32 v224, v224, v225, v227
	v_div_fixup_f32 v82, v224, v82, 1.0
	v_div_scale_f32 v224, s[16:17], v83, v83, 1.0
	v_rcp_f32_e32 v225, v224
	s_nop 0
	v_fma_f32 v226, -v224, v225, 1.0
	v_fmac_f32_e32 v225, v226, v225
	v_div_scale_f32 v226, vcc, 1.0, v83, 1.0
	v_mul_f32_e32 v227, v226, v225
	v_fma_f32 v228, -v224, v227, v226
	v_fmac_f32_e32 v227, v228, v225
	v_fma_f32 v224, -v224, v227, v226
	v_div_fmas_f32 v224, v224, v225, v227
	v_div_fixup_f32 v83, v224, v83, 1.0
	v_lshlrev_b32_e32 v236, 16, v190
	v_and_b32_e32 v237, 0xffff0000, v190
	v_lshlrev_b32_e32 v238, 16, v191
	v_and_b32_e32 v239, 0xffff0000, v191
	v_pk_fma_f32 v[80:81], v[80:81], v[236:237], v[180:181]
	v_pk_fma_f32 v[82:83], v[82:83], v[238:239], v[182:183]
	v_cvt_pk_bf16_f32 v159, v82, v83
	v_cvt_pk_bf16_f32 v158, v80, v81
	global_store_dwordx4 v[150:151], v[80:83], off offset:576
	global_store_dwordx2 v[156:157], v[158:159], off offset:288
	s_nop 0
	v_mul_f32_e32 v81, v81, v81
	v_mul_f32_e32 v83, v83, v83
	v_fmac_f32_e32 v81, v80, v80
	v_fmac_f32_e32 v83, v82, v82
	v_add_f32_e32 v80, v81, v83
	v_add_f32_e32 v229, v229, v80
	v_mov_b32_e32 v230, v229
	s_nop 1
	v_permlane16_swap_b32_e32 v229, v230
	v_add_f32_e32 v229, v229, v230
	v_mov_b32_e32 v230, v229
	s_nop 1
	v_permlane32_swap_b32_e32 v229, v230
	s_and_saveexec_b64 s[16:17], s[10:11]
	v_lshl_add_u64 v[156:157], v[144:145], 2, s[22:23]
	v_add_f32_e32 v229, v229, v230
	global_atomic_add_f32 v[156:157], v229, off
	s_or_b64 exec, exec, s[16:17]
	v_add_u32_e32 v144, 0x80, v154
	v_mov_b32_e32 v145, v155
	v_lshlrev_b64 v[148:149], 11, v[144:145]
	v_lshl_add_u64 v[148:149], v[148:149], 0, v[146:147]
	v_lshl_add_u64 v[150:151], v[148:149], 2, s[28:29]
	v_lshl_add_u64 v[152:153], v[148:149], 1, s[42:43]
	global_load_dwordx2 v[184:185], v[152:153], off
	global_load_dwordx4 v[168:171], v[150:151], off
	global_load_dwordx2 v[186:187], v[152:153], off offset:32
	global_load_dwordx4 v[172:175], v[150:151], off offset:64
	global_load_dwordx2 v[188:189], v[152:153], off offset:256
	global_load_dwordx4 v[176:179], v[150:151], off offset:512
	global_load_dwordx2 v[190:191], v[152:153], off offset:288
	global_load_dwordx4 v[180:183], v[150:151], off offset:576
	s_waitcnt vmcnt(17)
	v_fmamk_f32 v219, v219, 0x3a000000, v165
	v_mul_f32_e32 v235, 0x4b800000, v219
	v_cmp_gt_f32_e32 vcc, s47, v219
	s_nop 1
	v_cndmask_b32_e32 v219, v219, v235, vcc
	v_rsq_f32_e32 v219, v219
	s_nop 0
	v_mul_f32_e32 v235, 0x45800000, v219
	v_cndmask_b32_e32 v234, v219, v235, vcc
	v_add_u32_e32 v144, 0x30, v154
	v_mov_b32_e32 v145, v155
	v_lshlrev_b64 v[148:149], 11, v[144:145]
	v_lshl_add_u64 v[148:149], v[148:149], 0, v[146:147]
	v_lshl_add_u64 v[150:151], v[148:149], 2, s[28:29]
	v_lshl_add_u64 v[156:157], v[148:149], 1, s[24:25]
	v_pk_mul_f32 v[76:77], v[76:77], v[234:235] op_sel_hi:[1,0]
	v_pk_mul_f32 v[78:79], v[78:79], v[234:235] op_sel_hi:[1,0]
	v_mul_f32_e32 v76, 0xbfb8aa3b, v76
	v_mul_f32_e32 v77, 0xbfb8aa3b, v77
	v_mul_f32_e32 v78, 0xbfb8aa3b, v78
	v_mul_f32_e32 v79, 0xbfb8aa3b, v79
	v_exp_f32_e32 v76, v76
	v_exp_f32_e32 v77, v77
	v_exp_f32_e32 v78, v78
	v_exp_f32_e32 v79, v79
	v_pk_add_f32 v[76:77], v[76:77], 1.0 op_sel_hi:[1,0]
	v_pk_add_f32 v[78:79], v[78:79], 1.0 op_sel_hi:[1,0]
	v_div_scale_f32 v224, s[16:17], v76, v76, 1.0
	v_rcp_f32_e32 v225, v224
	s_nop 0
	v_fma_f32 v226, -v224, v225, 1.0
	v_fmac_f32_e32 v225, v226, v225
	v_div_scale_f32 v226, vcc, 1.0, v76, 1.0
	v_mul_f32_e32 v227, v226, v225
	v_fma_f32 v228, -v224, v227, v226
	v_fmac_f32_e32 v227, v228, v225
	v_fma_f32 v224, -v224, v227, v226
	v_div_fmas_f32 v224, v224, v225, v227
	v_div_fixup_f32 v76, v224, v76, 1.0
	v_div_scale_f32 v224, s[16:17], v77, v77, 1.0
	v_rcp_f32_e32 v225, v224
	s_nop 0
	v_fma_f32 v226, -v224, v225, 1.0
	v_fmac_f32_e32 v225, v226, v225
	v_div_scale_f32 v226, vcc, 1.0, v77, 1.0
	v_mul_f32_e32 v227, v226, v225
	v_fma_f32 v228, -v224, v227, v226
	v_fmac_f32_e32 v227, v228, v225
	v_fma_f32 v224, -v224, v227, v226
	v_div_fmas_f32 v224, v224, v225, v227
	v_div_fixup_f32 v77, v224, v77, 1.0
	v_div_scale_f32 v224, s[16:17], v78, v78, 1.0
	v_rcp_f32_e32 v225, v224
	s_nop 0
	v_fma_f32 v226, -v224, v225, 1.0
	v_fmac_f32_e32 v225, v226, v225
	v_div_scale_f32 v226, vcc, 1.0, v78, 1.0
	v_mul_f32_e32 v227, v226, v225
	v_fma_f32 v228, -v224, v227, v226
	v_fmac_f32_e32 v227, v228, v225
	v_fma_f32 v224, -v224, v227, v226
	v_div_fmas_f32 v224, v224, v225, v227
	v_div_fixup_f32 v78, v224, v78, 1.0
	v_div_scale_f32 v224, s[16:17], v79, v79, 1.0
	v_rcp_f32_e32 v225, v224
	s_nop 0
	v_fma_f32 v226, -v224, v225, 1.0
	v_fmac_f32_e32 v225, v226, v225
	v_div_scale_f32 v226, vcc, 1.0, v79, 1.0
	v_mul_f32_e32 v227, v226, v225
	v_fma_f32 v228, -v224, v227, v226
	v_fmac_f32_e32 v227, v228, v225
	v_fma_f32 v224, -v224, v227, v226
	v_div_fmas_f32 v224, v224, v225, v227
	v_div_fixup_f32 v79, v224, v79, 1.0
	v_lshlrev_b32_e32 v236, 16, v208
	v_and_b32_e32 v237, 0xffff0000, v208
	v_lshlrev_b32_e32 v238, 16, v209
	v_and_b32_e32 v239, 0xffff0000, v209
	v_pk_fma_f32 v[76:77], v[76:77], v[236:237], v[192:193]
	v_pk_fma_f32 v[78:79], v[78:79], v[238:239], v[194:195]
	v_cvt_pk_bf16_f32 v159, v78, v79
	v_cvt_pk_bf16_f32 v158, v76, v77
	global_store_dwordx4 v[150:151], v[76:79], off
	global_store_dwordx2 v[156:157], v[158:159], off
	s_nop 0
	v_mul_f32_e32 v77, v77, v77
	v_mul_f32_e32 v79, v79, v79
	v_fmac_f32_e32 v77, v76, v76
	v_fmac_f32_e32 v79, v78, v78
	v_add_f32_e32 v229, v77, v79
	v_pk_mul_f32 v[72:73], v[72:73], v[234:235] op_sel_hi:[1,0]
	v_pk_mul_f32 v[74:75], v[74:75], v[234:235] op_sel_hi:[1,0]
	v_mul_f32_e32 v72, 0xbfb8aa3b, v72
	v_mul_f32_e32 v73, 0xbfb8aa3b, v73
	v_mul_f32_e32 v74, 0xbfb8aa3b, v74
	v_mul_f32_e32 v75, 0xbfb8aa3b, v75
	v_exp_f32_e32 v72, v72
	v_exp_f32_e32 v73, v73
	v_exp_f32_e32 v74, v74
	v_exp_f32_e32 v75, v75
	v_pk_add_f32 v[72:73], v[72:73], 1.0 op_sel_hi:[1,0]
	v_pk_add_f32 v[74:75], v[74:75], 1.0 op_sel_hi:[1,0]
	v_div_scale_f32 v224, s[16:17], v72, v72, 1.0
	v_rcp_f32_e32 v225, v224
	s_nop 0
	v_fma_f32 v226, -v224, v225, 1.0
	v_fmac_f32_e32 v225, v226, v225
	v_div_scale_f32 v226, vcc, 1.0, v72, 1.0
	v_mul_f32_e32 v227, v226, v225
	v_fma_f32 v228, -v224, v227, v226
	v_fmac_f32_e32 v227, v228, v225
	v_fma_f32 v224, -v224, v227, v226
	v_div_fmas_f32 v224, v224, v225, v227
	v_div_fixup_f32 v72, v224, v72, 1.0
	v_div_scale_f32 v224, s[16:17], v73, v73, 1.0
	v_rcp_f32_e32 v225, v224
	s_nop 0
	v_fma_f32 v226, -v224, v225, 1.0
	v_fmac_f32_e32 v225, v226, v225
	v_div_scale_f32 v226, vcc, 1.0, v73, 1.0
	v_mul_f32_e32 v227, v226, v225
	v_fma_f32 v228, -v224, v227, v226
	v_fmac_f32_e32 v227, v228, v225
	v_fma_f32 v224, -v224, v227, v226
	v_div_fmas_f32 v224, v224, v225, v227
	v_div_fixup_f32 v73, v224, v73, 1.0
	v_div_scale_f32 v224, s[16:17], v74, v74, 1.0
	v_rcp_f32_e32 v225, v224
	s_nop 0
	v_fma_f32 v226, -v224, v225, 1.0
	v_fmac_f32_e32 v225, v226, v225
	v_div_scale_f32 v226, vcc, 1.0, v74, 1.0
	v_mul_f32_e32 v227, v226, v225
	v_fma_f32 v228, -v224, v227, v226
	v_fmac_f32_e32 v227, v228, v225
	v_fma_f32 v224, -v224, v227, v226
	v_div_fmas_f32 v224, v224, v225, v227
	v_div_fixup_f32 v74, v224, v74, 1.0
	v_div_scale_f32 v224, s[16:17], v75, v75, 1.0
	v_rcp_f32_e32 v225, v224
	s_nop 0
	v_fma_f32 v226, -v224, v225, 1.0
	v_fmac_f32_e32 v225, v226, v225
	v_div_scale_f32 v226, vcc, 1.0, v75, 1.0
	v_mul_f32_e32 v227, v226, v225
	v_fma_f32 v228, -v224, v227, v226
	v_fmac_f32_e32 v227, v228, v225
	v_fma_f32 v224, -v224, v227, v226
	v_div_fmas_f32 v224, v224, v225, v227
	v_div_fixup_f32 v75, v224, v75, 1.0
	v_lshlrev_b32_e32 v236, 16, v210
	v_and_b32_e32 v237, 0xffff0000, v210
	v_lshlrev_b32_e32 v238, 16, v211
	v_and_b32_e32 v239, 0xffff0000, v211
	v_pk_fma_f32 v[72:73], v[72:73], v[236:237], v[196:197]
	v_pk_fma_f32 v[74:75], v[74:75], v[238:239], v[198:199]
	v_cvt_pk_bf16_f32 v159, v74, v75
	v_cvt_pk_bf16_f32 v158, v72, v73
	global_store_dwordx4 v[150:151], v[72:75], off offset:64
	global_store_dwordx2 v[156:157], v[158:159], off offset:32
	s_nop 0
	v_mul_f32_e32 v73, v73, v73
	v_mul_f32_e32 v75, v75, v75
	v_fmac_f32_e32 v73, v72, v72
	v_fmac_f32_e32 v75, v74, v74
	v_add_f32_e32 v72, v73, v75
	v_add_f32_e32 v229, v229, v72
	v_pk_mul_f32 v[68:69], v[68:69], v[234:235] op_sel_hi:[1,0]
	v_pk_mul_f32 v[70:71], v[70:71], v[234:235] op_sel_hi:[1,0]
	v_mul_f32_e32 v68, 0xbfb8aa3b, v68
	v_mul_f32_e32 v69, 0xbfb8aa3b, v69
	v_mul_f32_e32 v70, 0xbfb8aa3b, v70
	v_mul_f32_e32 v71, 0xbfb8aa3b, v71
	v_exp_f32_e32 v68, v68
	v_exp_f32_e32 v69, v69
	v_exp_f32_e32 v70, v70
	v_exp_f32_e32 v71, v71
	v_pk_add_f32 v[68:69], v[68:69], 1.0 op_sel_hi:[1,0]
	v_pk_add_f32 v[70:71], v[70:71], 1.0 op_sel_hi:[1,0]
	v_div_scale_f32 v224, s[16:17], v68, v68, 1.0
	v_rcp_f32_e32 v225, v224
	s_nop 0
	v_fma_f32 v226, -v224, v225, 1.0
	v_fmac_f32_e32 v225, v226, v225
	v_div_scale_f32 v226, vcc, 1.0, v68, 1.0
	v_mul_f32_e32 v227, v226, v225
	v_fma_f32 v228, -v224, v227, v226
	v_fmac_f32_e32 v227, v228, v225
	v_fma_f32 v224, -v224, v227, v226
	v_div_fmas_f32 v224, v224, v225, v227
	v_div_fixup_f32 v68, v224, v68, 1.0
	v_div_scale_f32 v224, s[16:17], v69, v69, 1.0
	v_rcp_f32_e32 v225, v224
	s_nop 0
	v_fma_f32 v226, -v224, v225, 1.0
	v_fmac_f32_e32 v225, v226, v225
	v_div_scale_f32 v226, vcc, 1.0, v69, 1.0
	v_mul_f32_e32 v227, v226, v225
	v_fma_f32 v228, -v224, v227, v226
	v_fmac_f32_e32 v227, v228, v225
	v_fma_f32 v224, -v224, v227, v226
	v_div_fmas_f32 v224, v224, v225, v227
	v_div_fixup_f32 v69, v224, v69, 1.0
	v_div_scale_f32 v224, s[16:17], v70, v70, 1.0
	v_rcp_f32_e32 v225, v224
	s_nop 0
	v_fma_f32 v226, -v224, v225, 1.0
	v_fmac_f32_e32 v225, v226, v225
	v_div_scale_f32 v226, vcc, 1.0, v70, 1.0
	v_mul_f32_e32 v227, v226, v225
	v_fma_f32 v228, -v224, v227, v226
	v_fmac_f32_e32 v227, v228, v225
	v_fma_f32 v224, -v224, v227, v226
	v_div_fmas_f32 v224, v224, v225, v227
	v_div_fixup_f32 v70, v224, v70, 1.0
	v_div_scale_f32 v224, s[16:17], v71, v71, 1.0
	v_rcp_f32_e32 v225, v224
	s_nop 0
	v_fma_f32 v226, -v224, v225, 1.0
	v_fmac_f32_e32 v225, v226, v225
	v_div_scale_f32 v226, vcc, 1.0, v71, 1.0
	v_mul_f32_e32 v227, v226, v225
	v_fma_f32 v228, -v224, v227, v226
	v_fmac_f32_e32 v227, v228, v225
	v_fma_f32 v224, -v224, v227, v226
	v_div_fmas_f32 v224, v224, v225, v227
	v_div_fixup_f32 v71, v224, v71, 1.0
	v_lshlrev_b32_e32 v236, 16, v212
	v_and_b32_e32 v237, 0xffff0000, v212
	v_lshlrev_b32_e32 v238, 16, v213
	v_and_b32_e32 v239, 0xffff0000, v213
	v_pk_fma_f32 v[68:69], v[68:69], v[236:237], v[200:201]
	v_pk_fma_f32 v[70:71], v[70:71], v[238:239], v[202:203]
	v_cvt_pk_bf16_f32 v159, v70, v71
	v_cvt_pk_bf16_f32 v158, v68, v69
	global_store_dwordx4 v[150:151], v[68:71], off offset:512
	global_store_dwordx2 v[156:157], v[158:159], off offset:256
	s_nop 0
	v_mul_f32_e32 v69, v69, v69
	v_mul_f32_e32 v71, v71, v71
	v_fmac_f32_e32 v69, v68, v68
	v_fmac_f32_e32 v71, v70, v70
	v_add_f32_e32 v68, v69, v71
	v_add_f32_e32 v229, v229, v68
	v_pk_mul_f32 v[64:65], v[64:65], v[234:235] op_sel_hi:[1,0]
	v_pk_mul_f32 v[66:67], v[66:67], v[234:235] op_sel_hi:[1,0]
	v_mul_f32_e32 v64, 0xbfb8aa3b, v64
	v_mul_f32_e32 v65, 0xbfb8aa3b, v65
	v_mul_f32_e32 v66, 0xbfb8aa3b, v66
	v_mul_f32_e32 v67, 0xbfb8aa3b, v67
	v_exp_f32_e32 v64, v64
	v_exp_f32_e32 v65, v65
	v_exp_f32_e32 v66, v66
	v_exp_f32_e32 v67, v67
	v_pk_add_f32 v[64:65], v[64:65], 1.0 op_sel_hi:[1,0]
	v_pk_add_f32 v[66:67], v[66:67], 1.0 op_sel_hi:[1,0]
	v_div_scale_f32 v224, s[16:17], v64, v64, 1.0
	v_rcp_f32_e32 v225, v224
	s_nop 0
	v_fma_f32 v226, -v224, v225, 1.0
	v_fmac_f32_e32 v225, v226, v225
	v_div_scale_f32 v226, vcc, 1.0, v64, 1.0
	v_mul_f32_e32 v227, v226, v225
	v_fma_f32 v228, -v224, v227, v226
	v_fmac_f32_e32 v227, v228, v225
	v_fma_f32 v224, -v224, v227, v226
	v_div_fmas_f32 v224, v224, v225, v227
	v_div_fixup_f32 v64, v224, v64, 1.0
	v_div_scale_f32 v224, s[16:17], v65, v65, 1.0
	v_rcp_f32_e32 v225, v224
	s_nop 0
	v_fma_f32 v226, -v224, v225, 1.0
	v_fmac_f32_e32 v225, v226, v225
	v_div_scale_f32 v226, vcc, 1.0, v65, 1.0
	v_mul_f32_e32 v227, v226, v225
	v_fma_f32 v228, -v224, v227, v226
	v_fmac_f32_e32 v227, v228, v225
	v_fma_f32 v224, -v224, v227, v226
	v_div_fmas_f32 v224, v224, v225, v227
	v_div_fixup_f32 v65, v224, v65, 1.0
	v_div_scale_f32 v224, s[16:17], v66, v66, 1.0
	v_rcp_f32_e32 v225, v224
	s_nop 0
	v_fma_f32 v226, -v224, v225, 1.0
	v_fmac_f32_e32 v225, v226, v225
	v_div_scale_f32 v226, vcc, 1.0, v66, 1.0
	v_mul_f32_e32 v227, v226, v225
	v_fma_f32 v228, -v224, v227, v226
	v_fmac_f32_e32 v227, v228, v225
	v_fma_f32 v224, -v224, v227, v226
	v_div_fmas_f32 v224, v224, v225, v227
	v_div_fixup_f32 v66, v224, v66, 1.0
	v_div_scale_f32 v224, s[16:17], v67, v67, 1.0
	v_rcp_f32_e32 v225, v224
	s_nop 0
	v_fma_f32 v226, -v224, v225, 1.0
	v_fmac_f32_e32 v225, v226, v225
	v_div_scale_f32 v226, vcc, 1.0, v67, 1.0
	v_mul_f32_e32 v227, v226, v225
	v_fma_f32 v228, -v224, v227, v226
	v_fmac_f32_e32 v227, v228, v225
	v_fma_f32 v224, -v224, v227, v226
	v_div_fmas_f32 v224, v224, v225, v227
	v_div_fixup_f32 v67, v224, v67, 1.0
	v_lshlrev_b32_e32 v236, 16, v214
	v_and_b32_e32 v237, 0xffff0000, v214
	v_lshlrev_b32_e32 v238, 16, v215
	v_and_b32_e32 v239, 0xffff0000, v215
	v_pk_fma_f32 v[64:65], v[64:65], v[236:237], v[204:205]
	v_pk_fma_f32 v[66:67], v[66:67], v[238:239], v[206:207]
	v_cvt_pk_bf16_f32 v159, v66, v67
	v_cvt_pk_bf16_f32 v158, v64, v65
	global_store_dwordx4 v[150:151], v[64:67], off offset:576
	global_store_dwordx2 v[156:157], v[158:159], off offset:288
	s_nop 0
	v_mul_f32_e32 v65, v65, v65
	v_mul_f32_e32 v67, v67, v67
	v_fmac_f32_e32 v65, v64, v64
	v_fmac_f32_e32 v67, v66, v66
	v_add_f32_e32 v64, v65, v67
	v_add_f32_e32 v229, v229, v64
	v_mov_b32_e32 v230, v229
	s_nop 1
	v_permlane16_swap_b32_e32 v229, v230
	v_add_f32_e32 v229, v229, v230
	v_mov_b32_e32 v230, v229
	s_nop 1
	v_permlane32_swap_b32_e32 v229, v230
	s_and_saveexec_b64 s[16:17], s[10:11]
	v_lshl_add_u64 v[156:157], v[144:145], 2, s[22:23]
	v_add_f32_e32 v229, v229, v230
	global_atomic_add_f32 v[156:157], v229, off
	s_or_b64 exec, exec, s[16:17]
	v_add_u32_e32 v144, 0x90, v154
	v_mov_b32_e32 v145, v155
	v_lshlrev_b64 v[148:149], 11, v[144:145]
	v_lshl_add_u64 v[148:149], v[148:149], 0, v[146:147]
	v_lshl_add_u64 v[150:151], v[148:149], 2, s[28:29]
	v_lshl_add_u64 v[152:153], v[148:149], 1, s[42:43]
	global_load_dwordx2 v[208:209], v[152:153], off
	global_load_dwordx4 v[192:195], v[150:151], off
	global_load_dwordx2 v[210:211], v[152:153], off offset:32
	global_load_dwordx4 v[196:199], v[150:151], off offset:64
	global_load_dwordx2 v[212:213], v[152:153], off offset:256
	global_load_dwordx4 v[200:203], v[150:151], off offset:512
	global_load_dwordx2 v[214:215], v[152:153], off offset:288
	global_load_dwordx4 v[204:207], v[150:151], off offset:576
	s_waitcnt vmcnt(17)
	v_fmamk_f32 v220, v220, 0x3a000000, v165
	v_mul_f32_e32 v235, 0x4b800000, v220
	v_cmp_gt_f32_e32 vcc, s47, v220
	s_nop 1
	v_cndmask_b32_e32 v220, v220, v235, vcc
	v_rsq_f32_e32 v220, v220
	s_nop 0
	v_mul_f32_e32 v235, 0x45800000, v220
	v_cndmask_b32_e32 v234, v220, v235, vcc
	v_add_u32_e32 v144, 0x80, v154
	v_mov_b32_e32 v145, v155
	v_lshlrev_b64 v[148:149], 11, v[144:145]
	v_lshl_add_u64 v[148:149], v[148:149], 0, v[146:147]
	v_lshl_add_u64 v[150:151], v[148:149], 2, s[28:29]
	v_lshl_add_u64 v[156:157], v[148:149], 1, s[24:25]
	v_pk_mul_f32 v[60:61], v[60:61], v[234:235] op_sel_hi:[1,0]
	v_pk_mul_f32 v[62:63], v[62:63], v[234:235] op_sel_hi:[1,0]
	v_mul_f32_e32 v60, 0xbfb8aa3b, v60
	v_mul_f32_e32 v61, 0xbfb8aa3b, v61
	v_mul_f32_e32 v62, 0xbfb8aa3b, v62
	v_mul_f32_e32 v63, 0xbfb8aa3b, v63
	v_exp_f32_e32 v60, v60
	v_exp_f32_e32 v61, v61
	v_exp_f32_e32 v62, v62
	v_exp_f32_e32 v63, v63
	v_pk_add_f32 v[60:61], v[60:61], 1.0 op_sel_hi:[1,0]
	v_pk_add_f32 v[62:63], v[62:63], 1.0 op_sel_hi:[1,0]
	v_div_scale_f32 v224, s[16:17], v60, v60, 1.0
	v_rcp_f32_e32 v225, v224
	s_nop 0
	v_fma_f32 v226, -v224, v225, 1.0
	v_fmac_f32_e32 v225, v226, v225
	v_div_scale_f32 v226, vcc, 1.0, v60, 1.0
	v_mul_f32_e32 v227, v226, v225
	v_fma_f32 v228, -v224, v227, v226
	v_fmac_f32_e32 v227, v228, v225
	v_fma_f32 v224, -v224, v227, v226
	v_div_fmas_f32 v224, v224, v225, v227
	v_div_fixup_f32 v60, v224, v60, 1.0
	v_div_scale_f32 v224, s[16:17], v61, v61, 1.0
	v_rcp_f32_e32 v225, v224
	s_nop 0
	v_fma_f32 v226, -v224, v225, 1.0
	v_fmac_f32_e32 v225, v226, v225
	v_div_scale_f32 v226, vcc, 1.0, v61, 1.0
	v_mul_f32_e32 v227, v226, v225
	v_fma_f32 v228, -v224, v227, v226
	v_fmac_f32_e32 v227, v228, v225
	v_fma_f32 v224, -v224, v227, v226
	v_div_fmas_f32 v224, v224, v225, v227
	v_div_fixup_f32 v61, v224, v61, 1.0
	v_div_scale_f32 v224, s[16:17], v62, v62, 1.0
	v_rcp_f32_e32 v225, v224
	s_nop 0
	v_fma_f32 v226, -v224, v225, 1.0
	v_fmac_f32_e32 v225, v226, v225
	v_div_scale_f32 v226, vcc, 1.0, v62, 1.0
	v_mul_f32_e32 v227, v226, v225
	v_fma_f32 v228, -v224, v227, v226
	v_fmac_f32_e32 v227, v228, v225
	v_fma_f32 v224, -v224, v227, v226
	v_div_fmas_f32 v224, v224, v225, v227
	v_div_fixup_f32 v62, v224, v62, 1.0
	v_div_scale_f32 v224, s[16:17], v63, v63, 1.0
	v_rcp_f32_e32 v225, v224
	s_nop 0
	v_fma_f32 v226, -v224, v225, 1.0
	v_fmac_f32_e32 v225, v226, v225
	v_div_scale_f32 v226, vcc, 1.0, v63, 1.0
	v_mul_f32_e32 v227, v226, v225
	v_fma_f32 v228, -v224, v227, v226
	v_fmac_f32_e32 v227, v228, v225
	v_fma_f32 v224, -v224, v227, v226
	v_div_fmas_f32 v224, v224, v225, v227
	v_div_fixup_f32 v63, v224, v63, 1.0
	v_lshlrev_b32_e32 v236, 16, v184
	v_and_b32_e32 v237, 0xffff0000, v184
	v_lshlrev_b32_e32 v238, 16, v185
	v_and_b32_e32 v239, 0xffff0000, v185
	v_pk_fma_f32 v[60:61], v[60:61], v[236:237], v[168:169]
	v_pk_fma_f32 v[62:63], v[62:63], v[238:239], v[170:171]
	v_cvt_pk_bf16_f32 v159, v62, v63
	v_cvt_pk_bf16_f32 v158, v60, v61
	global_store_dwordx4 v[150:151], v[60:63], off
	global_store_dwordx2 v[156:157], v[158:159], off
	s_nop 0
	v_mul_f32_e32 v61, v61, v61
	v_mul_f32_e32 v63, v63, v63
	v_fmac_f32_e32 v61, v60, v60
	v_fmac_f32_e32 v63, v62, v62
	v_add_f32_e32 v229, v61, v63
	v_pk_mul_f32 v[56:57], v[56:57], v[234:235] op_sel_hi:[1,0]
	v_pk_mul_f32 v[58:59], v[58:59], v[234:235] op_sel_hi:[1,0]
	v_mul_f32_e32 v56, 0xbfb8aa3b, v56
	v_mul_f32_e32 v57, 0xbfb8aa3b, v57
	v_mul_f32_e32 v58, 0xbfb8aa3b, v58
	v_mul_f32_e32 v59, 0xbfb8aa3b, v59
	v_exp_f32_e32 v56, v56
	v_exp_f32_e32 v57, v57
	v_exp_f32_e32 v58, v58
	v_exp_f32_e32 v59, v59
	v_pk_add_f32 v[56:57], v[56:57], 1.0 op_sel_hi:[1,0]
	v_pk_add_f32 v[58:59], v[58:59], 1.0 op_sel_hi:[1,0]
	v_div_scale_f32 v224, s[16:17], v56, v56, 1.0
	v_rcp_f32_e32 v225, v224
	s_nop 0
	v_fma_f32 v226, -v224, v225, 1.0
	v_fmac_f32_e32 v225, v226, v225
	v_div_scale_f32 v226, vcc, 1.0, v56, 1.0
	v_mul_f32_e32 v227, v226, v225
	v_fma_f32 v228, -v224, v227, v226
	v_fmac_f32_e32 v227, v228, v225
	v_fma_f32 v224, -v224, v227, v226
	v_div_fmas_f32 v224, v224, v225, v227
	v_div_fixup_f32 v56, v224, v56, 1.0
	v_div_scale_f32 v224, s[16:17], v57, v57, 1.0
	v_rcp_f32_e32 v225, v224
	s_nop 0
	v_fma_f32 v226, -v224, v225, 1.0
	v_fmac_f32_e32 v225, v226, v225
	v_div_scale_f32 v226, vcc, 1.0, v57, 1.0
	v_mul_f32_e32 v227, v226, v225
	v_fma_f32 v228, -v224, v227, v226
	v_fmac_f32_e32 v227, v228, v225
	v_fma_f32 v224, -v224, v227, v226
	v_div_fmas_f32 v224, v224, v225, v227
	v_div_fixup_f32 v57, v224, v57, 1.0
	v_div_scale_f32 v224, s[16:17], v58, v58, 1.0
	v_rcp_f32_e32 v225, v224
	s_nop 0
	v_fma_f32 v226, -v224, v225, 1.0
	v_fmac_f32_e32 v225, v226, v225
	v_div_scale_f32 v226, vcc, 1.0, v58, 1.0
	v_mul_f32_e32 v227, v226, v225
	v_fma_f32 v228, -v224, v227, v226
	v_fmac_f32_e32 v227, v228, v225
	v_fma_f32 v224, -v224, v227, v226
	v_div_fmas_f32 v224, v224, v225, v227
	v_div_fixup_f32 v58, v224, v58, 1.0
	v_div_scale_f32 v224, s[16:17], v59, v59, 1.0
	v_rcp_f32_e32 v225, v224
	s_nop 0
	v_fma_f32 v226, -v224, v225, 1.0
	v_fmac_f32_e32 v225, v226, v225
	v_div_scale_f32 v226, vcc, 1.0, v59, 1.0
	v_mul_f32_e32 v227, v226, v225
	v_fma_f32 v228, -v224, v227, v226
	v_fmac_f32_e32 v227, v228, v225
	v_fma_f32 v224, -v224, v227, v226
	v_div_fmas_f32 v224, v224, v225, v227
	v_div_fixup_f32 v59, v224, v59, 1.0
	v_lshlrev_b32_e32 v236, 16, v186
	v_and_b32_e32 v237, 0xffff0000, v186
	v_lshlrev_b32_e32 v238, 16, v187
	v_and_b32_e32 v239, 0xffff0000, v187
	v_pk_fma_f32 v[56:57], v[56:57], v[236:237], v[172:173]
	v_pk_fma_f32 v[58:59], v[58:59], v[238:239], v[174:175]
	v_cvt_pk_bf16_f32 v159, v58, v59
	v_cvt_pk_bf16_f32 v158, v56, v57
	global_store_dwordx4 v[150:151], v[56:59], off offset:64
	global_store_dwordx2 v[156:157], v[158:159], off offset:32
	s_nop 0
	v_mul_f32_e32 v57, v57, v57
	v_mul_f32_e32 v59, v59, v59
	v_fmac_f32_e32 v57, v56, v56
	v_fmac_f32_e32 v59, v58, v58
	v_add_f32_e32 v56, v57, v59
	v_add_f32_e32 v229, v229, v56
	v_pk_mul_f32 v[52:53], v[52:53], v[234:235] op_sel_hi:[1,0]
	v_pk_mul_f32 v[54:55], v[54:55], v[234:235] op_sel_hi:[1,0]
	v_mul_f32_e32 v52, 0xbfb8aa3b, v52
	v_mul_f32_e32 v53, 0xbfb8aa3b, v53
	v_mul_f32_e32 v54, 0xbfb8aa3b, v54
	v_mul_f32_e32 v55, 0xbfb8aa3b, v55
	v_exp_f32_e32 v52, v52
	v_exp_f32_e32 v53, v53
	v_exp_f32_e32 v54, v54
	v_exp_f32_e32 v55, v55
	v_pk_add_f32 v[52:53], v[52:53], 1.0 op_sel_hi:[1,0]
	v_pk_add_f32 v[54:55], v[54:55], 1.0 op_sel_hi:[1,0]
	v_div_scale_f32 v224, s[16:17], v52, v52, 1.0
	v_rcp_f32_e32 v225, v224
	s_nop 0
	v_fma_f32 v226, -v224, v225, 1.0
	v_fmac_f32_e32 v225, v226, v225
	v_div_scale_f32 v226, vcc, 1.0, v52, 1.0
	v_mul_f32_e32 v227, v226, v225
	v_fma_f32 v228, -v224, v227, v226
	v_fmac_f32_e32 v227, v228, v225
	v_fma_f32 v224, -v224, v227, v226
	v_div_fmas_f32 v224, v224, v225, v227
	v_div_fixup_f32 v52, v224, v52, 1.0
	v_div_scale_f32 v224, s[16:17], v53, v53, 1.0
	v_rcp_f32_e32 v225, v224
	s_nop 0
	v_fma_f32 v226, -v224, v225, 1.0
	v_fmac_f32_e32 v225, v226, v225
	v_div_scale_f32 v226, vcc, 1.0, v53, 1.0
	v_mul_f32_e32 v227, v226, v225
	v_fma_f32 v228, -v224, v227, v226
	v_fmac_f32_e32 v227, v228, v225
	v_fma_f32 v224, -v224, v227, v226
	v_div_fmas_f32 v224, v224, v225, v227
	v_div_fixup_f32 v53, v224, v53, 1.0
	v_div_scale_f32 v224, s[16:17], v54, v54, 1.0
	v_rcp_f32_e32 v225, v224
	s_nop 0
	v_fma_f32 v226, -v224, v225, 1.0
	v_fmac_f32_e32 v225, v226, v225
	v_div_scale_f32 v226, vcc, 1.0, v54, 1.0
	v_mul_f32_e32 v227, v226, v225
	v_fma_f32 v228, -v224, v227, v226
	v_fmac_f32_e32 v227, v228, v225
	v_fma_f32 v224, -v224, v227, v226
	v_div_fmas_f32 v224, v224, v225, v227
	v_div_fixup_f32 v54, v224, v54, 1.0
	v_div_scale_f32 v224, s[16:17], v55, v55, 1.0
	v_rcp_f32_e32 v225, v224
	s_nop 0
	v_fma_f32 v226, -v224, v225, 1.0
	v_fmac_f32_e32 v225, v226, v225
	v_div_scale_f32 v226, vcc, 1.0, v55, 1.0
	v_mul_f32_e32 v227, v226, v225
	v_fma_f32 v228, -v224, v227, v226
	v_fmac_f32_e32 v227, v228, v225
	v_fma_f32 v224, -v224, v227, v226
	v_div_fmas_f32 v224, v224, v225, v227
	v_div_fixup_f32 v55, v224, v55, 1.0
	v_lshlrev_b32_e32 v236, 16, v188
	v_and_b32_e32 v237, 0xffff0000, v188
	v_lshlrev_b32_e32 v238, 16, v189
	v_and_b32_e32 v239, 0xffff0000, v189
	v_pk_fma_f32 v[52:53], v[52:53], v[236:237], v[176:177]
	v_pk_fma_f32 v[54:55], v[54:55], v[238:239], v[178:179]
	v_cvt_pk_bf16_f32 v159, v54, v55
	v_cvt_pk_bf16_f32 v158, v52, v53
	global_store_dwordx4 v[150:151], v[52:55], off offset:512
	global_store_dwordx2 v[156:157], v[158:159], off offset:256
	s_nop 0
	v_mul_f32_e32 v53, v53, v53
	v_mul_f32_e32 v55, v55, v55
	v_fmac_f32_e32 v53, v52, v52
	v_fmac_f32_e32 v55, v54, v54
	v_add_f32_e32 v52, v53, v55
	v_add_f32_e32 v229, v229, v52
	v_pk_mul_f32 v[48:49], v[48:49], v[234:235] op_sel_hi:[1,0]
	v_pk_mul_f32 v[50:51], v[50:51], v[234:235] op_sel_hi:[1,0]
	v_mul_f32_e32 v48, 0xbfb8aa3b, v48
	v_mul_f32_e32 v49, 0xbfb8aa3b, v49
	v_mul_f32_e32 v50, 0xbfb8aa3b, v50
	v_mul_f32_e32 v51, 0xbfb8aa3b, v51
	v_exp_f32_e32 v48, v48
	v_exp_f32_e32 v49, v49
	v_exp_f32_e32 v50, v50
	v_exp_f32_e32 v51, v51
	v_pk_add_f32 v[48:49], v[48:49], 1.0 op_sel_hi:[1,0]
	v_pk_add_f32 v[50:51], v[50:51], 1.0 op_sel_hi:[1,0]
	v_div_scale_f32 v224, s[16:17], v48, v48, 1.0
	v_rcp_f32_e32 v225, v224
	s_nop 0
	v_fma_f32 v226, -v224, v225, 1.0
	v_fmac_f32_e32 v225, v226, v225
	v_div_scale_f32 v226, vcc, 1.0, v48, 1.0
	v_mul_f32_e32 v227, v226, v225
	v_fma_f32 v228, -v224, v227, v226
	v_fmac_f32_e32 v227, v228, v225
	v_fma_f32 v224, -v224, v227, v226
	v_div_fmas_f32 v224, v224, v225, v227
	v_div_fixup_f32 v48, v224, v48, 1.0
	v_div_scale_f32 v224, s[16:17], v49, v49, 1.0
	v_rcp_f32_e32 v225, v224
	s_nop 0
	v_fma_f32 v226, -v224, v225, 1.0
	v_fmac_f32_e32 v225, v226, v225
	v_div_scale_f32 v226, vcc, 1.0, v49, 1.0
	v_mul_f32_e32 v227, v226, v225
	v_fma_f32 v228, -v224, v227, v226
	v_fmac_f32_e32 v227, v228, v225
	v_fma_f32 v224, -v224, v227, v226
	v_div_fmas_f32 v224, v224, v225, v227
	v_div_fixup_f32 v49, v224, v49, 1.0
	v_div_scale_f32 v224, s[16:17], v50, v50, 1.0
	v_rcp_f32_e32 v225, v224
	s_nop 0
	v_fma_f32 v226, -v224, v225, 1.0
	v_fmac_f32_e32 v225, v226, v225
	v_div_scale_f32 v226, vcc, 1.0, v50, 1.0
	v_mul_f32_e32 v227, v226, v225
	v_fma_f32 v228, -v224, v227, v226
	v_fmac_f32_e32 v227, v228, v225
	v_fma_f32 v224, -v224, v227, v226
	v_div_fmas_f32 v224, v224, v225, v227
	v_div_fixup_f32 v50, v224, v50, 1.0
	v_div_scale_f32 v224, s[16:17], v51, v51, 1.0
	v_rcp_f32_e32 v225, v224
	s_nop 0
	v_fma_f32 v226, -v224, v225, 1.0
	v_fmac_f32_e32 v225, v226, v225
	v_div_scale_f32 v226, vcc, 1.0, v51, 1.0
	v_mul_f32_e32 v227, v226, v225
	v_fma_f32 v228, -v224, v227, v226
	v_fmac_f32_e32 v227, v228, v225
	v_fma_f32 v224, -v224, v227, v226
	v_div_fmas_f32 v224, v224, v225, v227
	v_div_fixup_f32 v51, v224, v51, 1.0
	v_lshlrev_b32_e32 v236, 16, v190
	v_and_b32_e32 v237, 0xffff0000, v190
	v_lshlrev_b32_e32 v238, 16, v191
	v_and_b32_e32 v239, 0xffff0000, v191
	v_pk_fma_f32 v[48:49], v[48:49], v[236:237], v[180:181]
	v_pk_fma_f32 v[50:51], v[50:51], v[238:239], v[182:183]
	v_cvt_pk_bf16_f32 v159, v50, v51
	v_cvt_pk_bf16_f32 v158, v48, v49
	global_store_dwordx4 v[150:151], v[48:51], off offset:576
	global_store_dwordx2 v[156:157], v[158:159], off offset:288
	s_nop 0
	v_mul_f32_e32 v49, v49, v49
	v_mul_f32_e32 v51, v51, v51
	v_fmac_f32_e32 v49, v48, v48
	v_fmac_f32_e32 v51, v50, v50
	v_add_f32_e32 v48, v49, v51
	v_add_f32_e32 v229, v229, v48
	v_mov_b32_e32 v230, v229
	s_nop 1
	v_permlane16_swap_b32_e32 v229, v230
	v_add_f32_e32 v229, v229, v230
	v_mov_b32_e32 v230, v229
	s_nop 1
	v_permlane32_swap_b32_e32 v229, v230
	s_and_saveexec_b64 s[16:17], s[10:11]
	v_lshl_add_u64 v[156:157], v[144:145], 2, s[22:23]
	v_add_f32_e32 v229, v229, v230
	global_atomic_add_f32 v[156:157], v229, off
	s_or_b64 exec, exec, s[16:17]
	v_add_u32_e32 v144, 0xa0, v154
	v_mov_b32_e32 v145, v155
	v_lshlrev_b64 v[148:149], 11, v[144:145]
	v_lshl_add_u64 v[148:149], v[148:149], 0, v[146:147]
	v_lshl_add_u64 v[150:151], v[148:149], 2, s[28:29]
	v_lshl_add_u64 v[152:153], v[148:149], 1, s[42:43]
	global_load_dwordx2 v[184:185], v[152:153], off
	global_load_dwordx4 v[168:171], v[150:151], off
	global_load_dwordx2 v[186:187], v[152:153], off offset:32
	global_load_dwordx4 v[172:175], v[150:151], off offset:64
	global_load_dwordx2 v[188:189], v[152:153], off offset:256
	global_load_dwordx4 v[176:179], v[150:151], off offset:512
	global_load_dwordx2 v[190:191], v[152:153], off offset:288
	global_load_dwordx4 v[180:183], v[150:151], off offset:576
	s_waitcnt vmcnt(17)
	v_fmamk_f32 v221, v221, 0x3a000000, v165
	v_mul_f32_e32 v235, 0x4b800000, v221
	v_cmp_gt_f32_e32 vcc, s47, v221
	s_nop 1
	v_cndmask_b32_e32 v221, v221, v235, vcc
	v_rsq_f32_e32 v221, v221
	s_nop 0
	v_mul_f32_e32 v235, 0x45800000, v221
	v_cndmask_b32_e32 v234, v221, v235, vcc
	v_add_u32_e32 v144, 0x90, v154
	v_mov_b32_e32 v145, v155
	v_lshlrev_b64 v[148:149], 11, v[144:145]
	v_lshl_add_u64 v[148:149], v[148:149], 0, v[146:147]
	v_lshl_add_u64 v[150:151], v[148:149], 2, s[28:29]
	v_lshl_add_u64 v[156:157], v[148:149], 1, s[24:25]
	v_pk_mul_f32 v[44:45], v[44:45], v[234:235] op_sel_hi:[1,0]
	v_pk_mul_f32 v[46:47], v[46:47], v[234:235] op_sel_hi:[1,0]
	v_mul_f32_e32 v44, 0xbfb8aa3b, v44
	v_mul_f32_e32 v45, 0xbfb8aa3b, v45
	v_mul_f32_e32 v46, 0xbfb8aa3b, v46
	v_mul_f32_e32 v47, 0xbfb8aa3b, v47
	v_exp_f32_e32 v44, v44
	v_exp_f32_e32 v45, v45
	v_exp_f32_e32 v46, v46
	v_exp_f32_e32 v47, v47
	v_pk_add_f32 v[44:45], v[44:45], 1.0 op_sel_hi:[1,0]
	v_pk_add_f32 v[46:47], v[46:47], 1.0 op_sel_hi:[1,0]
	v_div_scale_f32 v224, s[16:17], v44, v44, 1.0
	v_rcp_f32_e32 v225, v224
	s_nop 0
	v_fma_f32 v226, -v224, v225, 1.0
	v_fmac_f32_e32 v225, v226, v225
	v_div_scale_f32 v226, vcc, 1.0, v44, 1.0
	v_mul_f32_e32 v227, v226, v225
	v_fma_f32 v228, -v224, v227, v226
	v_fmac_f32_e32 v227, v228, v225
	v_fma_f32 v224, -v224, v227, v226
	v_div_fmas_f32 v224, v224, v225, v227
	v_div_fixup_f32 v44, v224, v44, 1.0
	v_div_scale_f32 v224, s[16:17], v45, v45, 1.0
	v_rcp_f32_e32 v225, v224
	s_nop 0
	v_fma_f32 v226, -v224, v225, 1.0
	v_fmac_f32_e32 v225, v226, v225
	v_div_scale_f32 v226, vcc, 1.0, v45, 1.0
	v_mul_f32_e32 v227, v226, v225
	v_fma_f32 v228, -v224, v227, v226
	v_fmac_f32_e32 v227, v228, v225
	v_fma_f32 v224, -v224, v227, v226
	v_div_fmas_f32 v224, v224, v225, v227
	v_div_fixup_f32 v45, v224, v45, 1.0
	v_div_scale_f32 v224, s[16:17], v46, v46, 1.0
	v_rcp_f32_e32 v225, v224
	s_nop 0
	v_fma_f32 v226, -v224, v225, 1.0
	v_fmac_f32_e32 v225, v226, v225
	v_div_scale_f32 v226, vcc, 1.0, v46, 1.0
	v_mul_f32_e32 v227, v226, v225
	v_fma_f32 v228, -v224, v227, v226
	v_fmac_f32_e32 v227, v228, v225
	v_fma_f32 v224, -v224, v227, v226
	v_div_fmas_f32 v224, v224, v225, v227
	v_div_fixup_f32 v46, v224, v46, 1.0
	v_div_scale_f32 v224, s[16:17], v47, v47, 1.0
	v_rcp_f32_e32 v225, v224
	s_nop 0
	v_fma_f32 v226, -v224, v225, 1.0
	v_fmac_f32_e32 v225, v226, v225
	v_div_scale_f32 v226, vcc, 1.0, v47, 1.0
	v_mul_f32_e32 v227, v226, v225
	v_fma_f32 v228, -v224, v227, v226
	v_fmac_f32_e32 v227, v228, v225
	v_fma_f32 v224, -v224, v227, v226
	v_div_fmas_f32 v224, v224, v225, v227
	v_div_fixup_f32 v47, v224, v47, 1.0
	v_lshlrev_b32_e32 v236, 16, v208
	v_and_b32_e32 v237, 0xffff0000, v208
	v_lshlrev_b32_e32 v238, 16, v209
	v_and_b32_e32 v239, 0xffff0000, v209
	v_pk_fma_f32 v[44:45], v[44:45], v[236:237], v[192:193]
	v_pk_fma_f32 v[46:47], v[46:47], v[238:239], v[194:195]
	v_cvt_pk_bf16_f32 v159, v46, v47
	v_cvt_pk_bf16_f32 v158, v44, v45
	global_store_dwordx4 v[150:151], v[44:47], off
	global_store_dwordx2 v[156:157], v[158:159], off
	s_nop 0
	v_mul_f32_e32 v45, v45, v45
	v_mul_f32_e32 v47, v47, v47
	v_fmac_f32_e32 v45, v44, v44
	v_fmac_f32_e32 v47, v46, v46
	v_add_f32_e32 v229, v45, v47
	v_pk_mul_f32 v[40:41], v[40:41], v[234:235] op_sel_hi:[1,0]
	v_pk_mul_f32 v[42:43], v[42:43], v[234:235] op_sel_hi:[1,0]
	v_mul_f32_e32 v40, 0xbfb8aa3b, v40
	v_mul_f32_e32 v41, 0xbfb8aa3b, v41
	v_mul_f32_e32 v42, 0xbfb8aa3b, v42
	v_mul_f32_e32 v43, 0xbfb8aa3b, v43
	v_exp_f32_e32 v40, v40
	v_exp_f32_e32 v41, v41
	v_exp_f32_e32 v42, v42
	v_exp_f32_e32 v43, v43
	v_pk_add_f32 v[40:41], v[40:41], 1.0 op_sel_hi:[1,0]
	v_pk_add_f32 v[42:43], v[42:43], 1.0 op_sel_hi:[1,0]
	v_div_scale_f32 v224, s[16:17], v40, v40, 1.0
	v_rcp_f32_e32 v225, v224
	s_nop 0
	v_fma_f32 v226, -v224, v225, 1.0
	v_fmac_f32_e32 v225, v226, v225
	v_div_scale_f32 v226, vcc, 1.0, v40, 1.0
	v_mul_f32_e32 v227, v226, v225
	v_fma_f32 v228, -v224, v227, v226
	v_fmac_f32_e32 v227, v228, v225
	v_fma_f32 v224, -v224, v227, v226
	v_div_fmas_f32 v224, v224, v225, v227
	v_div_fixup_f32 v40, v224, v40, 1.0
	v_div_scale_f32 v224, s[16:17], v41, v41, 1.0
	v_rcp_f32_e32 v225, v224
	s_nop 0
	v_fma_f32 v226, -v224, v225, 1.0
	v_fmac_f32_e32 v225, v226, v225
	v_div_scale_f32 v226, vcc, 1.0, v41, 1.0
	v_mul_f32_e32 v227, v226, v225
	v_fma_f32 v228, -v224, v227, v226
	v_fmac_f32_e32 v227, v228, v225
	v_fma_f32 v224, -v224, v227, v226
	v_div_fmas_f32 v224, v224, v225, v227
	v_div_fixup_f32 v41, v224, v41, 1.0
	v_div_scale_f32 v224, s[16:17], v42, v42, 1.0
	v_rcp_f32_e32 v225, v224
	s_nop 0
	v_fma_f32 v226, -v224, v225, 1.0
	v_fmac_f32_e32 v225, v226, v225
	v_div_scale_f32 v226, vcc, 1.0, v42, 1.0
	v_mul_f32_e32 v227, v226, v225
	v_fma_f32 v228, -v224, v227, v226
	v_fmac_f32_e32 v227, v228, v225
	v_fma_f32 v224, -v224, v227, v226
	v_div_fmas_f32 v224, v224, v225, v227
	v_div_fixup_f32 v42, v224, v42, 1.0
	v_div_scale_f32 v224, s[16:17], v43, v43, 1.0
	v_rcp_f32_e32 v225, v224
	s_nop 0
	v_fma_f32 v226, -v224, v225, 1.0
	v_fmac_f32_e32 v225, v226, v225
	v_div_scale_f32 v226, vcc, 1.0, v43, 1.0
	v_mul_f32_e32 v227, v226, v225
	v_fma_f32 v228, -v224, v227, v226
	v_fmac_f32_e32 v227, v228, v225
	v_fma_f32 v224, -v224, v227, v226
	v_div_fmas_f32 v224, v224, v225, v227
	v_div_fixup_f32 v43, v224, v43, 1.0
	v_lshlrev_b32_e32 v236, 16, v210
	v_and_b32_e32 v237, 0xffff0000, v210
	v_lshlrev_b32_e32 v238, 16, v211
	v_and_b32_e32 v239, 0xffff0000, v211
	v_pk_fma_f32 v[40:41], v[40:41], v[236:237], v[196:197]
	v_pk_fma_f32 v[42:43], v[42:43], v[238:239], v[198:199]
	v_cvt_pk_bf16_f32 v159, v42, v43
	v_cvt_pk_bf16_f32 v158, v40, v41
	global_store_dwordx4 v[150:151], v[40:43], off offset:64
	global_store_dwordx2 v[156:157], v[158:159], off offset:32
	s_nop 0
	v_mul_f32_e32 v41, v41, v41
	v_mul_f32_e32 v43, v43, v43
	v_fmac_f32_e32 v41, v40, v40
	v_fmac_f32_e32 v43, v42, v42
	v_add_f32_e32 v40, v41, v43
	v_add_f32_e32 v229, v229, v40
	v_pk_mul_f32 v[36:37], v[36:37], v[234:235] op_sel_hi:[1,0]
	v_pk_mul_f32 v[38:39], v[38:39], v[234:235] op_sel_hi:[1,0]
	v_mul_f32_e32 v36, 0xbfb8aa3b, v36
	v_mul_f32_e32 v37, 0xbfb8aa3b, v37
	v_mul_f32_e32 v38, 0xbfb8aa3b, v38
	v_mul_f32_e32 v39, 0xbfb8aa3b, v39
	v_exp_f32_e32 v36, v36
	v_exp_f32_e32 v37, v37
	v_exp_f32_e32 v38, v38
	v_exp_f32_e32 v39, v39
	v_pk_add_f32 v[36:37], v[36:37], 1.0 op_sel_hi:[1,0]
	v_pk_add_f32 v[38:39], v[38:39], 1.0 op_sel_hi:[1,0]
	v_div_scale_f32 v224, s[16:17], v36, v36, 1.0
	v_rcp_f32_e32 v225, v224
	s_nop 0
	v_fma_f32 v226, -v224, v225, 1.0
	v_fmac_f32_e32 v225, v226, v225
	v_div_scale_f32 v226, vcc, 1.0, v36, 1.0
	v_mul_f32_e32 v227, v226, v225
	v_fma_f32 v228, -v224, v227, v226
	v_fmac_f32_e32 v227, v228, v225
	v_fma_f32 v224, -v224, v227, v226
	v_div_fmas_f32 v224, v224, v225, v227
	v_div_fixup_f32 v36, v224, v36, 1.0
	v_div_scale_f32 v224, s[16:17], v37, v37, 1.0
	v_rcp_f32_e32 v225, v224
	s_nop 0
	v_fma_f32 v226, -v224, v225, 1.0
	v_fmac_f32_e32 v225, v226, v225
	v_div_scale_f32 v226, vcc, 1.0, v37, 1.0
	v_mul_f32_e32 v227, v226, v225
	v_fma_f32 v228, -v224, v227, v226
	v_fmac_f32_e32 v227, v228, v225
	v_fma_f32 v224, -v224, v227, v226
	v_div_fmas_f32 v224, v224, v225, v227
	v_div_fixup_f32 v37, v224, v37, 1.0
	v_div_scale_f32 v224, s[16:17], v38, v38, 1.0
	v_rcp_f32_e32 v225, v224
	s_nop 0
	v_fma_f32 v226, -v224, v225, 1.0
	v_fmac_f32_e32 v225, v226, v225
	v_div_scale_f32 v226, vcc, 1.0, v38, 1.0
	v_mul_f32_e32 v227, v226, v225
	v_fma_f32 v228, -v224, v227, v226
	v_fmac_f32_e32 v227, v228, v225
	v_fma_f32 v224, -v224, v227, v226
	v_div_fmas_f32 v224, v224, v225, v227
	v_div_fixup_f32 v38, v224, v38, 1.0
	v_div_scale_f32 v224, s[16:17], v39, v39, 1.0
	v_rcp_f32_e32 v225, v224
	s_nop 0
	v_fma_f32 v226, -v224, v225, 1.0
	v_fmac_f32_e32 v225, v226, v225
	v_div_scale_f32 v226, vcc, 1.0, v39, 1.0
	v_mul_f32_e32 v227, v226, v225
	v_fma_f32 v228, -v224, v227, v226
	v_fmac_f32_e32 v227, v228, v225
	v_fma_f32 v224, -v224, v227, v226
	v_div_fmas_f32 v224, v224, v225, v227
	v_div_fixup_f32 v39, v224, v39, 1.0
	v_lshlrev_b32_e32 v236, 16, v212
	v_and_b32_e32 v237, 0xffff0000, v212
	v_lshlrev_b32_e32 v238, 16, v213
	v_and_b32_e32 v239, 0xffff0000, v213
	v_pk_fma_f32 v[36:37], v[36:37], v[236:237], v[200:201]
	v_pk_fma_f32 v[38:39], v[38:39], v[238:239], v[202:203]
	v_cvt_pk_bf16_f32 v159, v38, v39
	v_cvt_pk_bf16_f32 v158, v36, v37
	global_store_dwordx4 v[150:151], v[36:39], off offset:512
	global_store_dwordx2 v[156:157], v[158:159], off offset:256
	s_nop 0
	v_mul_f32_e32 v37, v37, v37
	v_mul_f32_e32 v39, v39, v39
	v_fmac_f32_e32 v37, v36, v36
	v_fmac_f32_e32 v39, v38, v38
	v_add_f32_e32 v36, v37, v39
	v_add_f32_e32 v229, v229, v36
	v_pk_mul_f32 v[32:33], v[32:33], v[234:235] op_sel_hi:[1,0]
	v_pk_mul_f32 v[34:35], v[34:35], v[234:235] op_sel_hi:[1,0]
	v_mul_f32_e32 v32, 0xbfb8aa3b, v32
	v_mul_f32_e32 v33, 0xbfb8aa3b, v33
	v_mul_f32_e32 v34, 0xbfb8aa3b, v34
	v_mul_f32_e32 v35, 0xbfb8aa3b, v35
	v_exp_f32_e32 v32, v32
	v_exp_f32_e32 v33, v33
	v_exp_f32_e32 v34, v34
	v_exp_f32_e32 v35, v35
	v_pk_add_f32 v[32:33], v[32:33], 1.0 op_sel_hi:[1,0]
	v_pk_add_f32 v[34:35], v[34:35], 1.0 op_sel_hi:[1,0]
	v_div_scale_f32 v224, s[16:17], v32, v32, 1.0
	v_rcp_f32_e32 v225, v224
	s_nop 0
	v_fma_f32 v226, -v224, v225, 1.0
	v_fmac_f32_e32 v225, v226, v225
	v_div_scale_f32 v226, vcc, 1.0, v32, 1.0
	v_mul_f32_e32 v227, v226, v225
	v_fma_f32 v228, -v224, v227, v226
	v_fmac_f32_e32 v227, v228, v225
	v_fma_f32 v224, -v224, v227, v226
	v_div_fmas_f32 v224, v224, v225, v227
	v_div_fixup_f32 v32, v224, v32, 1.0
	v_div_scale_f32 v224, s[16:17], v33, v33, 1.0
	v_rcp_f32_e32 v225, v224
	s_nop 0
	v_fma_f32 v226, -v224, v225, 1.0
	v_fmac_f32_e32 v225, v226, v225
	v_div_scale_f32 v226, vcc, 1.0, v33, 1.0
	v_mul_f32_e32 v227, v226, v225
	v_fma_f32 v228, -v224, v227, v226
	v_fmac_f32_e32 v227, v228, v225
	v_fma_f32 v224, -v224, v227, v226
	v_div_fmas_f32 v224, v224, v225, v227
	v_div_fixup_f32 v33, v224, v33, 1.0
	v_div_scale_f32 v224, s[16:17], v34, v34, 1.0
	v_rcp_f32_e32 v225, v224
	s_nop 0
	v_fma_f32 v226, -v224, v225, 1.0
	v_fmac_f32_e32 v225, v226, v225
	v_div_scale_f32 v226, vcc, 1.0, v34, 1.0
	v_mul_f32_e32 v227, v226, v225
	v_fma_f32 v228, -v224, v227, v226
	v_fmac_f32_e32 v227, v228, v225
	v_fma_f32 v224, -v224, v227, v226
	v_div_fmas_f32 v224, v224, v225, v227
	v_div_fixup_f32 v34, v224, v34, 1.0
	v_div_scale_f32 v224, s[16:17], v35, v35, 1.0
	v_rcp_f32_e32 v225, v224
	s_nop 0
	v_fma_f32 v226, -v224, v225, 1.0
	v_fmac_f32_e32 v225, v226, v225
	v_div_scale_f32 v226, vcc, 1.0, v35, 1.0
	v_mul_f32_e32 v227, v226, v225
	v_fma_f32 v228, -v224, v227, v226
	v_fmac_f32_e32 v227, v228, v225
	v_fma_f32 v224, -v224, v227, v226
	v_div_fmas_f32 v224, v224, v225, v227
	v_div_fixup_f32 v35, v224, v35, 1.0
	v_lshlrev_b32_e32 v236, 16, v214
	v_and_b32_e32 v237, 0xffff0000, v214
	v_lshlrev_b32_e32 v238, 16, v215
	v_and_b32_e32 v239, 0xffff0000, v215
	v_pk_fma_f32 v[32:33], v[32:33], v[236:237], v[204:205]
	v_pk_fma_f32 v[34:35], v[34:35], v[238:239], v[206:207]
	v_cvt_pk_bf16_f32 v159, v34, v35
	v_cvt_pk_bf16_f32 v158, v32, v33
	global_store_dwordx4 v[150:151], v[32:35], off offset:576
	global_store_dwordx2 v[156:157], v[158:159], off offset:288
	s_nop 0
	v_mul_f32_e32 v33, v33, v33
	v_mul_f32_e32 v35, v35, v35
	v_fmac_f32_e32 v33, v32, v32
	v_fmac_f32_e32 v35, v34, v34
	v_add_f32_e32 v32, v33, v35
	v_add_f32_e32 v229, v229, v32
	v_mov_b32_e32 v230, v229
	s_nop 1
	v_permlane16_swap_b32_e32 v229, v230
	v_add_f32_e32 v229, v229, v230
	v_mov_b32_e32 v230, v229
	s_nop 1
	v_permlane32_swap_b32_e32 v229, v230
	s_and_saveexec_b64 s[16:17], s[10:11]
	v_lshl_add_u64 v[156:157], v[144:145], 2, s[22:23]
	v_add_f32_e32 v229, v229, v230
	global_atomic_add_f32 v[156:157], v229, off
	s_or_b64 exec, exec, s[16:17]
	v_add_u32_e32 v144, 0xb0, v154
	v_mov_b32_e32 v145, v155
	v_lshlrev_b64 v[148:149], 11, v[144:145]
	v_lshl_add_u64 v[148:149], v[148:149], 0, v[146:147]
	v_lshl_add_u64 v[150:151], v[148:149], 2, s[28:29]
	v_lshl_add_u64 v[152:153], v[148:149], 1, s[42:43]
	global_load_dwordx2 v[208:209], v[152:153], off
	global_load_dwordx4 v[192:195], v[150:151], off
	global_load_dwordx2 v[210:211], v[152:153], off offset:32
	global_load_dwordx4 v[196:199], v[150:151], off offset:64
	global_load_dwordx2 v[212:213], v[152:153], off offset:256
	global_load_dwordx4 v[200:203], v[150:151], off offset:512
	global_load_dwordx2 v[214:215], v[152:153], off offset:288
	global_load_dwordx4 v[204:207], v[150:151], off offset:576
	s_waitcnt vmcnt(17)
	v_fmamk_f32 v222, v222, 0x3a000000, v165
	v_mul_f32_e32 v235, 0x4b800000, v222
	v_cmp_gt_f32_e32 vcc, s47, v222
	s_nop 1
	v_cndmask_b32_e32 v222, v222, v235, vcc
	v_rsq_f32_e32 v222, v222
	s_nop 0
	v_mul_f32_e32 v235, 0x45800000, v222
	v_cndmask_b32_e32 v234, v222, v235, vcc
	v_add_u32_e32 v144, 0xa0, v154
	v_mov_b32_e32 v145, v155
	v_lshlrev_b64 v[148:149], 11, v[144:145]
	v_lshl_add_u64 v[148:149], v[148:149], 0, v[146:147]
	v_lshl_add_u64 v[150:151], v[148:149], 2, s[28:29]
	v_lshl_add_u64 v[156:157], v[148:149], 1, s[24:25]
	v_pk_mul_f32 v[28:29], v[28:29], v[234:235] op_sel_hi:[1,0]
	v_pk_mul_f32 v[30:31], v[30:31], v[234:235] op_sel_hi:[1,0]
	v_mul_f32_e32 v28, 0xbfb8aa3b, v28
	v_mul_f32_e32 v29, 0xbfb8aa3b, v29
	v_mul_f32_e32 v30, 0xbfb8aa3b, v30
	v_mul_f32_e32 v31, 0xbfb8aa3b, v31
	v_exp_f32_e32 v28, v28
	v_exp_f32_e32 v29, v29
	v_exp_f32_e32 v30, v30
	v_exp_f32_e32 v31, v31
	v_pk_add_f32 v[28:29], v[28:29], 1.0 op_sel_hi:[1,0]
	v_pk_add_f32 v[30:31], v[30:31], 1.0 op_sel_hi:[1,0]
	v_div_scale_f32 v224, s[16:17], v28, v28, 1.0
	v_rcp_f32_e32 v225, v224
	s_nop 0
	v_fma_f32 v226, -v224, v225, 1.0
	v_fmac_f32_e32 v225, v226, v225
	v_div_scale_f32 v226, vcc, 1.0, v28, 1.0
	v_mul_f32_e32 v227, v226, v225
	v_fma_f32 v228, -v224, v227, v226
	v_fmac_f32_e32 v227, v228, v225
	v_fma_f32 v224, -v224, v227, v226
	v_div_fmas_f32 v224, v224, v225, v227
	v_div_fixup_f32 v28, v224, v28, 1.0
	v_div_scale_f32 v224, s[16:17], v29, v29, 1.0
	v_rcp_f32_e32 v225, v224
	s_nop 0
	v_fma_f32 v226, -v224, v225, 1.0
	v_fmac_f32_e32 v225, v226, v225
	v_div_scale_f32 v226, vcc, 1.0, v29, 1.0
	v_mul_f32_e32 v227, v226, v225
	v_fma_f32 v228, -v224, v227, v226
	v_fmac_f32_e32 v227, v228, v225
	v_fma_f32 v224, -v224, v227, v226
	v_div_fmas_f32 v224, v224, v225, v227
	v_div_fixup_f32 v29, v224, v29, 1.0
	v_div_scale_f32 v224, s[16:17], v30, v30, 1.0
	v_rcp_f32_e32 v225, v224
	s_nop 0
	v_fma_f32 v226, -v224, v225, 1.0
	v_fmac_f32_e32 v225, v226, v225
	v_div_scale_f32 v226, vcc, 1.0, v30, 1.0
	v_mul_f32_e32 v227, v226, v225
	v_fma_f32 v228, -v224, v227, v226
	v_fmac_f32_e32 v227, v228, v225
	v_fma_f32 v224, -v224, v227, v226
	v_div_fmas_f32 v224, v224, v225, v227
	v_div_fixup_f32 v30, v224, v30, 1.0
	v_div_scale_f32 v224, s[16:17], v31, v31, 1.0
	v_rcp_f32_e32 v225, v224
	s_nop 0
	v_fma_f32 v226, -v224, v225, 1.0
	v_fmac_f32_e32 v225, v226, v225
	v_div_scale_f32 v226, vcc, 1.0, v31, 1.0
	v_mul_f32_e32 v227, v226, v225
	v_fma_f32 v228, -v224, v227, v226
	v_fmac_f32_e32 v227, v228, v225
	v_fma_f32 v224, -v224, v227, v226
	v_div_fmas_f32 v224, v224, v225, v227
	v_div_fixup_f32 v31, v224, v31, 1.0
	v_lshlrev_b32_e32 v236, 16, v184
	v_and_b32_e32 v237, 0xffff0000, v184
	v_lshlrev_b32_e32 v238, 16, v185
	v_and_b32_e32 v239, 0xffff0000, v185
	v_pk_fma_f32 v[28:29], v[28:29], v[236:237], v[168:169]
	v_pk_fma_f32 v[30:31], v[30:31], v[238:239], v[170:171]
	v_cvt_pk_bf16_f32 v159, v30, v31
	v_cvt_pk_bf16_f32 v158, v28, v29
	global_store_dwordx4 v[150:151], v[28:31], off
	global_store_dwordx2 v[156:157], v[158:159], off
	s_nop 0
	v_mul_f32_e32 v29, v29, v29
	v_mul_f32_e32 v31, v31, v31
	v_fmac_f32_e32 v29, v28, v28
	v_fmac_f32_e32 v31, v30, v30
	v_add_f32_e32 v229, v29, v31
	v_pk_mul_f32 v[24:25], v[24:25], v[234:235] op_sel_hi:[1,0]
	v_pk_mul_f32 v[26:27], v[26:27], v[234:235] op_sel_hi:[1,0]
	v_mul_f32_e32 v24, 0xbfb8aa3b, v24
	v_mul_f32_e32 v25, 0xbfb8aa3b, v25
	v_mul_f32_e32 v26, 0xbfb8aa3b, v26
	v_mul_f32_e32 v27, 0xbfb8aa3b, v27
	v_exp_f32_e32 v24, v24
	v_exp_f32_e32 v25, v25
	v_exp_f32_e32 v26, v26
	v_exp_f32_e32 v27, v27
	v_pk_add_f32 v[24:25], v[24:25], 1.0 op_sel_hi:[1,0]
	v_pk_add_f32 v[26:27], v[26:27], 1.0 op_sel_hi:[1,0]
	v_div_scale_f32 v224, s[16:17], v24, v24, 1.0
	v_rcp_f32_e32 v225, v224
	s_nop 0
	v_fma_f32 v226, -v224, v225, 1.0
	v_fmac_f32_e32 v225, v226, v225
	v_div_scale_f32 v226, vcc, 1.0, v24, 1.0
	v_mul_f32_e32 v227, v226, v225
	v_fma_f32 v228, -v224, v227, v226
	v_fmac_f32_e32 v227, v228, v225
	v_fma_f32 v224, -v224, v227, v226
	v_div_fmas_f32 v224, v224, v225, v227
	v_div_fixup_f32 v24, v224, v24, 1.0
	v_div_scale_f32 v224, s[16:17], v25, v25, 1.0
	v_rcp_f32_e32 v225, v224
	s_nop 0
	v_fma_f32 v226, -v224, v225, 1.0
	v_fmac_f32_e32 v225, v226, v225
	v_div_scale_f32 v226, vcc, 1.0, v25, 1.0
	v_mul_f32_e32 v227, v226, v225
	v_fma_f32 v228, -v224, v227, v226
	v_fmac_f32_e32 v227, v228, v225
	v_fma_f32 v224, -v224, v227, v226
	v_div_fmas_f32 v224, v224, v225, v227
	v_div_fixup_f32 v25, v224, v25, 1.0
	v_div_scale_f32 v224, s[16:17], v26, v26, 1.0
	v_rcp_f32_e32 v225, v224
	s_nop 0
	v_fma_f32 v226, -v224, v225, 1.0
	v_fmac_f32_e32 v225, v226, v225
	v_div_scale_f32 v226, vcc, 1.0, v26, 1.0
	v_mul_f32_e32 v227, v226, v225
	v_fma_f32 v228, -v224, v227, v226
	v_fmac_f32_e32 v227, v228, v225
	v_fma_f32 v224, -v224, v227, v226
	v_div_fmas_f32 v224, v224, v225, v227
	v_div_fixup_f32 v26, v224, v26, 1.0
	v_div_scale_f32 v224, s[16:17], v27, v27, 1.0
	v_rcp_f32_e32 v225, v224
	s_nop 0
	v_fma_f32 v226, -v224, v225, 1.0
	v_fmac_f32_e32 v225, v226, v225
	v_div_scale_f32 v226, vcc, 1.0, v27, 1.0
	v_mul_f32_e32 v227, v226, v225
	v_fma_f32 v228, -v224, v227, v226
	v_fmac_f32_e32 v227, v228, v225
	v_fma_f32 v224, -v224, v227, v226
	v_div_fmas_f32 v224, v224, v225, v227
	v_div_fixup_f32 v27, v224, v27, 1.0
	v_lshlrev_b32_e32 v236, 16, v186
	v_and_b32_e32 v237, 0xffff0000, v186
	v_lshlrev_b32_e32 v238, 16, v187
	v_and_b32_e32 v239, 0xffff0000, v187
	v_pk_fma_f32 v[24:25], v[24:25], v[236:237], v[172:173]
	v_pk_fma_f32 v[26:27], v[26:27], v[238:239], v[174:175]
	v_cvt_pk_bf16_f32 v159, v26, v27
	v_cvt_pk_bf16_f32 v158, v24, v25
	global_store_dwordx4 v[150:151], v[24:27], off offset:64
	global_store_dwordx2 v[156:157], v[158:159], off offset:32
	s_nop 0
	v_mul_f32_e32 v25, v25, v25
	v_mul_f32_e32 v27, v27, v27
	v_fmac_f32_e32 v25, v24, v24
	v_fmac_f32_e32 v27, v26, v26
	v_add_f32_e32 v24, v25, v27
	v_add_f32_e32 v229, v229, v24
	v_pk_mul_f32 v[20:21], v[20:21], v[234:235] op_sel_hi:[1,0]
	v_pk_mul_f32 v[22:23], v[22:23], v[234:235] op_sel_hi:[1,0]
	v_mul_f32_e32 v20, 0xbfb8aa3b, v20
	v_mul_f32_e32 v21, 0xbfb8aa3b, v21
	v_mul_f32_e32 v22, 0xbfb8aa3b, v22
	v_mul_f32_e32 v23, 0xbfb8aa3b, v23
	v_exp_f32_e32 v20, v20
	v_exp_f32_e32 v21, v21
	v_exp_f32_e32 v22, v22
	v_exp_f32_e32 v23, v23
	v_pk_add_f32 v[20:21], v[20:21], 1.0 op_sel_hi:[1,0]
	v_pk_add_f32 v[22:23], v[22:23], 1.0 op_sel_hi:[1,0]
	v_div_scale_f32 v224, s[16:17], v20, v20, 1.0
	v_rcp_f32_e32 v225, v224
	s_nop 0
	v_fma_f32 v226, -v224, v225, 1.0
	v_fmac_f32_e32 v225, v226, v225
	v_div_scale_f32 v226, vcc, 1.0, v20, 1.0
	v_mul_f32_e32 v227, v226, v225
	v_fma_f32 v228, -v224, v227, v226
	v_fmac_f32_e32 v227, v228, v225
	v_fma_f32 v224, -v224, v227, v226
	v_div_fmas_f32 v224, v224, v225, v227
	v_div_fixup_f32 v20, v224, v20, 1.0
	v_div_scale_f32 v224, s[16:17], v21, v21, 1.0
	v_rcp_f32_e32 v225, v224
	s_nop 0
	v_fma_f32 v226, -v224, v225, 1.0
	v_fmac_f32_e32 v225, v226, v225
	v_div_scale_f32 v226, vcc, 1.0, v21, 1.0
	v_mul_f32_e32 v227, v226, v225
	v_fma_f32 v228, -v224, v227, v226
	v_fmac_f32_e32 v227, v228, v225
	v_fma_f32 v224, -v224, v227, v226
	v_div_fmas_f32 v224, v224, v225, v227
	v_div_fixup_f32 v21, v224, v21, 1.0
	v_div_scale_f32 v224, s[16:17], v22, v22, 1.0
	v_rcp_f32_e32 v225, v224
	s_nop 0
	v_fma_f32 v226, -v224, v225, 1.0
	v_fmac_f32_e32 v225, v226, v225
	v_div_scale_f32 v226, vcc, 1.0, v22, 1.0
	v_mul_f32_e32 v227, v226, v225
	v_fma_f32 v228, -v224, v227, v226
	v_fmac_f32_e32 v227, v228, v225
	v_fma_f32 v224, -v224, v227, v226
	v_div_fmas_f32 v224, v224, v225, v227
	v_div_fixup_f32 v22, v224, v22, 1.0
	v_div_scale_f32 v224, s[16:17], v23, v23, 1.0
	v_rcp_f32_e32 v225, v224
	s_nop 0
	v_fma_f32 v226, -v224, v225, 1.0
	v_fmac_f32_e32 v225, v226, v225
	v_div_scale_f32 v226, vcc, 1.0, v23, 1.0
	v_mul_f32_e32 v227, v226, v225
	v_fma_f32 v228, -v224, v227, v226
	v_fmac_f32_e32 v227, v228, v225
	v_fma_f32 v224, -v224, v227, v226
	v_div_fmas_f32 v224, v224, v225, v227
	v_div_fixup_f32 v23, v224, v23, 1.0
	v_lshlrev_b32_e32 v236, 16, v188
	v_and_b32_e32 v237, 0xffff0000, v188
	v_lshlrev_b32_e32 v238, 16, v189
	v_and_b32_e32 v239, 0xffff0000, v189
	v_pk_fma_f32 v[20:21], v[20:21], v[236:237], v[176:177]
	v_pk_fma_f32 v[22:23], v[22:23], v[238:239], v[178:179]
	v_cvt_pk_bf16_f32 v159, v22, v23
	v_cvt_pk_bf16_f32 v158, v20, v21
	global_store_dwordx4 v[150:151], v[20:23], off offset:512
	global_store_dwordx2 v[156:157], v[158:159], off offset:256
	s_nop 0
	v_mul_f32_e32 v21, v21, v21
	v_mul_f32_e32 v23, v23, v23
	v_fmac_f32_e32 v21, v20, v20
	v_fmac_f32_e32 v23, v22, v22
	v_add_f32_e32 v20, v21, v23
	v_add_f32_e32 v229, v229, v20
	v_pk_mul_f32 v[16:17], v[16:17], v[234:235] op_sel_hi:[1,0]
	v_pk_mul_f32 v[18:19], v[18:19], v[234:235] op_sel_hi:[1,0]
	v_mul_f32_e32 v16, 0xbfb8aa3b, v16
	v_mul_f32_e32 v17, 0xbfb8aa3b, v17
	v_mul_f32_e32 v18, 0xbfb8aa3b, v18
	v_mul_f32_e32 v19, 0xbfb8aa3b, v19
	v_exp_f32_e32 v16, v16
	v_exp_f32_e32 v17, v17
	v_exp_f32_e32 v18, v18
	v_exp_f32_e32 v19, v19
	v_pk_add_f32 v[16:17], v[16:17], 1.0 op_sel_hi:[1,0]
	v_pk_add_f32 v[18:19], v[18:19], 1.0 op_sel_hi:[1,0]
	v_div_scale_f32 v224, s[16:17], v16, v16, 1.0
	v_rcp_f32_e32 v225, v224
	s_nop 0
	v_fma_f32 v226, -v224, v225, 1.0
	v_fmac_f32_e32 v225, v226, v225
	v_div_scale_f32 v226, vcc, 1.0, v16, 1.0
	v_mul_f32_e32 v227, v226, v225
	v_fma_f32 v228, -v224, v227, v226
	v_fmac_f32_e32 v227, v228, v225
	v_fma_f32 v224, -v224, v227, v226
	v_div_fmas_f32 v224, v224, v225, v227
	v_div_fixup_f32 v16, v224, v16, 1.0
	v_div_scale_f32 v224, s[16:17], v17, v17, 1.0
	v_rcp_f32_e32 v225, v224
	s_nop 0
	v_fma_f32 v226, -v224, v225, 1.0
	v_fmac_f32_e32 v225, v226, v225
	v_div_scale_f32 v226, vcc, 1.0, v17, 1.0
	v_mul_f32_e32 v227, v226, v225
	v_fma_f32 v228, -v224, v227, v226
	v_fmac_f32_e32 v227, v228, v225
	v_fma_f32 v224, -v224, v227, v226
	v_div_fmas_f32 v224, v224, v225, v227
	v_div_fixup_f32 v17, v224, v17, 1.0
	v_div_scale_f32 v224, s[16:17], v18, v18, 1.0
	v_rcp_f32_e32 v225, v224
	s_nop 0
	v_fma_f32 v226, -v224, v225, 1.0
	v_fmac_f32_e32 v225, v226, v225
	v_div_scale_f32 v226, vcc, 1.0, v18, 1.0
	v_mul_f32_e32 v227, v226, v225
	v_fma_f32 v228, -v224, v227, v226
	v_fmac_f32_e32 v227, v228, v225
	v_fma_f32 v224, -v224, v227, v226
	v_div_fmas_f32 v224, v224, v225, v227
	v_div_fixup_f32 v18, v224, v18, 1.0
	v_div_scale_f32 v224, s[16:17], v19, v19, 1.0
	v_rcp_f32_e32 v225, v224
	s_nop 0
	v_fma_f32 v226, -v224, v225, 1.0
	v_fmac_f32_e32 v225, v226, v225
	v_div_scale_f32 v226, vcc, 1.0, v19, 1.0
	v_mul_f32_e32 v227, v226, v225
	v_fma_f32 v228, -v224, v227, v226
	v_fmac_f32_e32 v227, v228, v225
	v_fma_f32 v224, -v224, v227, v226
	v_div_fmas_f32 v224, v224, v225, v227
	v_div_fixup_f32 v19, v224, v19, 1.0
	v_lshlrev_b32_e32 v236, 16, v190
	v_and_b32_e32 v237, 0xffff0000, v190
	v_lshlrev_b32_e32 v238, 16, v191
	v_and_b32_e32 v239, 0xffff0000, v191
	v_pk_fma_f32 v[16:17], v[16:17], v[236:237], v[180:181]
	v_pk_fma_f32 v[18:19], v[18:19], v[238:239], v[182:183]
	v_cvt_pk_bf16_f32 v159, v18, v19
	v_cvt_pk_bf16_f32 v158, v16, v17
	global_store_dwordx4 v[150:151], v[16:19], off offset:576
	global_store_dwordx2 v[156:157], v[158:159], off offset:288
	s_nop 0
	v_mul_f32_e32 v17, v17, v17
	v_mul_f32_e32 v19, v19, v19
	v_fmac_f32_e32 v17, v16, v16
	v_fmac_f32_e32 v19, v18, v18
	v_add_f32_e32 v16, v17, v19
	v_add_f32_e32 v229, v229, v16
	v_mov_b32_e32 v230, v229
	s_nop 1
	v_permlane16_swap_b32_e32 v229, v230
	v_add_f32_e32 v229, v229, v230
	v_mov_b32_e32 v230, v229
	s_nop 1
	v_permlane32_swap_b32_e32 v229, v230
	s_and_saveexec_b64 s[16:17], s[10:11]
	v_lshl_add_u64 v[156:157], v[144:145], 2, s[22:23]
	v_add_f32_e32 v229, v229, v230
	global_atomic_add_f32 v[156:157], v229, off
	s_or_b64 exec, exec, s[16:17]
	s_waitcnt vmcnt(9)
	v_fmamk_f32 v223, v223, 0x3a000000, v165
	v_mul_f32_e32 v235, 0x4b800000, v223
	v_cmp_gt_f32_e32 vcc, s47, v223
	s_nop 1
	v_cndmask_b32_e32 v223, v223, v235, vcc
	v_rsq_f32_e32 v223, v223
	s_nop 0
	v_mul_f32_e32 v235, 0x45800000, v223
	v_cndmask_b32_e32 v234, v223, v235, vcc
	v_add_u32_e32 v144, 0xb0, v154
	v_mov_b32_e32 v145, v155
	v_lshlrev_b64 v[148:149], 11, v[144:145]
	v_lshl_add_u64 v[148:149], v[148:149], 0, v[146:147]
	v_lshl_add_u64 v[150:151], v[148:149], 2, s[28:29]
	v_lshl_add_u64 v[156:157], v[148:149], 1, s[24:25]
	v_pk_mul_f32 v[12:13], v[12:13], v[234:235] op_sel_hi:[1,0]
	v_pk_mul_f32 v[14:15], v[14:15], v[234:235] op_sel_hi:[1,0]
	v_mul_f32_e32 v12, 0xbfb8aa3b, v12
	v_mul_f32_e32 v13, 0xbfb8aa3b, v13
	v_mul_f32_e32 v14, 0xbfb8aa3b, v14
	v_mul_f32_e32 v15, 0xbfb8aa3b, v15
	v_exp_f32_e32 v12, v12
	v_exp_f32_e32 v13, v13
	v_exp_f32_e32 v14, v14
	v_exp_f32_e32 v15, v15
	v_pk_add_f32 v[12:13], v[12:13], 1.0 op_sel_hi:[1,0]
	v_pk_add_f32 v[14:15], v[14:15], 1.0 op_sel_hi:[1,0]
	v_div_scale_f32 v224, s[16:17], v12, v12, 1.0
	v_rcp_f32_e32 v225, v224
	s_nop 0
	v_fma_f32 v226, -v224, v225, 1.0
	v_fmac_f32_e32 v225, v226, v225
	v_div_scale_f32 v226, vcc, 1.0, v12, 1.0
	v_mul_f32_e32 v227, v226, v225
	v_fma_f32 v228, -v224, v227, v226
	v_fmac_f32_e32 v227, v228, v225
	v_fma_f32 v224, -v224, v227, v226
	v_div_fmas_f32 v224, v224, v225, v227
	v_div_fixup_f32 v12, v224, v12, 1.0
	v_div_scale_f32 v224, s[16:17], v13, v13, 1.0
	v_rcp_f32_e32 v225, v224
	s_nop 0
	v_fma_f32 v226, -v224, v225, 1.0
	v_fmac_f32_e32 v225, v226, v225
	v_div_scale_f32 v226, vcc, 1.0, v13, 1.0
	v_mul_f32_e32 v227, v226, v225
	v_fma_f32 v228, -v224, v227, v226
	v_fmac_f32_e32 v227, v228, v225
	v_fma_f32 v224, -v224, v227, v226
	v_div_fmas_f32 v224, v224, v225, v227
	v_div_fixup_f32 v13, v224, v13, 1.0
	v_div_scale_f32 v224, s[16:17], v14, v14, 1.0
	v_rcp_f32_e32 v225, v224
	s_nop 0
	v_fma_f32 v226, -v224, v225, 1.0
	v_fmac_f32_e32 v225, v226, v225
	v_div_scale_f32 v226, vcc, 1.0, v14, 1.0
	v_mul_f32_e32 v227, v226, v225
	v_fma_f32 v228, -v224, v227, v226
	v_fmac_f32_e32 v227, v228, v225
	v_fma_f32 v224, -v224, v227, v226
	v_div_fmas_f32 v224, v224, v225, v227
	v_div_fixup_f32 v14, v224, v14, 1.0
	v_div_scale_f32 v224, s[16:17], v15, v15, 1.0
	v_rcp_f32_e32 v225, v224
	s_nop 0
	v_fma_f32 v226, -v224, v225, 1.0
	v_fmac_f32_e32 v225, v226, v225
	v_div_scale_f32 v226, vcc, 1.0, v15, 1.0
	v_mul_f32_e32 v227, v226, v225
	v_fma_f32 v228, -v224, v227, v226
	v_fmac_f32_e32 v227, v228, v225
	v_fma_f32 v224, -v224, v227, v226
	v_div_fmas_f32 v224, v224, v225, v227
	v_div_fixup_f32 v15, v224, v15, 1.0
	v_lshlrev_b32_e32 v236, 16, v208
	v_and_b32_e32 v237, 0xffff0000, v208
	v_lshlrev_b32_e32 v238, 16, v209
	v_and_b32_e32 v239, 0xffff0000, v209
	v_pk_fma_f32 v[12:13], v[12:13], v[236:237], v[192:193]
	v_pk_fma_f32 v[14:15], v[14:15], v[238:239], v[194:195]
	v_cvt_pk_bf16_f32 v159, v14, v15
	v_cvt_pk_bf16_f32 v158, v12, v13
	global_store_dwordx4 v[150:151], v[12:15], off
	global_store_dwordx2 v[156:157], v[158:159], off
	s_nop 0
	v_mul_f32_e32 v13, v13, v13
	v_mul_f32_e32 v15, v15, v15
	v_fmac_f32_e32 v13, v12, v12
	v_fmac_f32_e32 v15, v14, v14
	v_add_f32_e32 v229, v13, v15
	v_pk_mul_f32 v[8:9], v[8:9], v[234:235] op_sel_hi:[1,0]
	v_pk_mul_f32 v[10:11], v[10:11], v[234:235] op_sel_hi:[1,0]
	v_mul_f32_e32 v8, 0xbfb8aa3b, v8
	v_mul_f32_e32 v9, 0xbfb8aa3b, v9
	v_mul_f32_e32 v10, 0xbfb8aa3b, v10
	v_mul_f32_e32 v11, 0xbfb8aa3b, v11
	v_exp_f32_e32 v8, v8
	v_exp_f32_e32 v9, v9
	v_exp_f32_e32 v10, v10
	v_exp_f32_e32 v11, v11
	v_pk_add_f32 v[8:9], v[8:9], 1.0 op_sel_hi:[1,0]
	v_pk_add_f32 v[10:11], v[10:11], 1.0 op_sel_hi:[1,0]
	v_div_scale_f32 v224, s[16:17], v8, v8, 1.0
	v_rcp_f32_e32 v225, v224
	s_nop 0
	v_fma_f32 v226, -v224, v225, 1.0
	v_fmac_f32_e32 v225, v226, v225
	v_div_scale_f32 v226, vcc, 1.0, v8, 1.0
	v_mul_f32_e32 v227, v226, v225
	v_fma_f32 v228, -v224, v227, v226
	v_fmac_f32_e32 v227, v228, v225
	v_fma_f32 v224, -v224, v227, v226
	v_div_fmas_f32 v224, v224, v225, v227
	v_div_fixup_f32 v8, v224, v8, 1.0
	v_div_scale_f32 v224, s[16:17], v9, v9, 1.0
	v_rcp_f32_e32 v225, v224
	s_nop 0
	v_fma_f32 v226, -v224, v225, 1.0
	v_fmac_f32_e32 v225, v226, v225
	v_div_scale_f32 v226, vcc, 1.0, v9, 1.0
	v_mul_f32_e32 v227, v226, v225
	v_fma_f32 v228, -v224, v227, v226
	v_fmac_f32_e32 v227, v228, v225
	v_fma_f32 v224, -v224, v227, v226
	v_div_fmas_f32 v224, v224, v225, v227
	v_div_fixup_f32 v9, v224, v9, 1.0
	v_div_scale_f32 v224, s[16:17], v10, v10, 1.0
	v_rcp_f32_e32 v225, v224
	s_nop 0
	v_fma_f32 v226, -v224, v225, 1.0
	v_fmac_f32_e32 v225, v226, v225
	v_div_scale_f32 v226, vcc, 1.0, v10, 1.0
	v_mul_f32_e32 v227, v226, v225
	v_fma_f32 v228, -v224, v227, v226
	v_fmac_f32_e32 v227, v228, v225
	v_fma_f32 v224, -v224, v227, v226
	v_div_fmas_f32 v224, v224, v225, v227
	v_div_fixup_f32 v10, v224, v10, 1.0
	v_div_scale_f32 v224, s[16:17], v11, v11, 1.0
	v_rcp_f32_e32 v225, v224
	s_nop 0
	v_fma_f32 v226, -v224, v225, 1.0
	v_fmac_f32_e32 v225, v226, v225
	v_div_scale_f32 v226, vcc, 1.0, v11, 1.0
	v_mul_f32_e32 v227, v226, v225
	v_fma_f32 v228, -v224, v227, v226
	v_fmac_f32_e32 v227, v228, v225
	v_fma_f32 v224, -v224, v227, v226
	v_div_fmas_f32 v224, v224, v225, v227
	v_div_fixup_f32 v11, v224, v11, 1.0
	v_lshlrev_b32_e32 v236, 16, v210
	v_and_b32_e32 v237, 0xffff0000, v210
	v_lshlrev_b32_e32 v238, 16, v211
	v_and_b32_e32 v239, 0xffff0000, v211
	v_pk_fma_f32 v[8:9], v[8:9], v[236:237], v[196:197]
	v_pk_fma_f32 v[10:11], v[10:11], v[238:239], v[198:199]
	v_cvt_pk_bf16_f32 v159, v10, v11
	v_cvt_pk_bf16_f32 v158, v8, v9
	global_store_dwordx4 v[150:151], v[8:11], off offset:64
	global_store_dwordx2 v[156:157], v[158:159], off offset:32
	s_nop 0
	v_mul_f32_e32 v9, v9, v9
	v_mul_f32_e32 v11, v11, v11
	v_fmac_f32_e32 v9, v8, v8
	v_fmac_f32_e32 v11, v10, v10
	v_add_f32_e32 v8, v9, v11
	v_add_f32_e32 v229, v229, v8
	v_pk_mul_f32 v[4:5], v[4:5], v[234:235] op_sel_hi:[1,0]
	v_pk_mul_f32 v[6:7], v[6:7], v[234:235] op_sel_hi:[1,0]
	v_mul_f32_e32 v4, 0xbfb8aa3b, v4
	v_mul_f32_e32 v5, 0xbfb8aa3b, v5
	v_mul_f32_e32 v6, 0xbfb8aa3b, v6
	v_mul_f32_e32 v7, 0xbfb8aa3b, v7
	v_exp_f32_e32 v4, v4
	v_exp_f32_e32 v5, v5
	v_exp_f32_e32 v6, v6
	v_exp_f32_e32 v7, v7
	v_pk_add_f32 v[4:5], v[4:5], 1.0 op_sel_hi:[1,0]
	v_pk_add_f32 v[6:7], v[6:7], 1.0 op_sel_hi:[1,0]
	v_div_scale_f32 v224, s[16:17], v4, v4, 1.0
	v_rcp_f32_e32 v225, v224
	s_nop 0
	v_fma_f32 v226, -v224, v225, 1.0
	v_fmac_f32_e32 v225, v226, v225
	v_div_scale_f32 v226, vcc, 1.0, v4, 1.0
	v_mul_f32_e32 v227, v226, v225
	v_fma_f32 v228, -v224, v227, v226
	v_fmac_f32_e32 v227, v228, v225
	v_fma_f32 v224, -v224, v227, v226
	v_div_fmas_f32 v224, v224, v225, v227
	v_div_fixup_f32 v4, v224, v4, 1.0
	v_div_scale_f32 v224, s[16:17], v5, v5, 1.0
	v_rcp_f32_e32 v225, v224
	s_nop 0
	v_fma_f32 v226, -v224, v225, 1.0
	v_fmac_f32_e32 v225, v226, v225
	v_div_scale_f32 v226, vcc, 1.0, v5, 1.0
	v_mul_f32_e32 v227, v226, v225
	v_fma_f32 v228, -v224, v227, v226
	v_fmac_f32_e32 v227, v228, v225
	v_fma_f32 v224, -v224, v227, v226
	v_div_fmas_f32 v224, v224, v225, v227
	v_div_fixup_f32 v5, v224, v5, 1.0
	v_div_scale_f32 v224, s[16:17], v6, v6, 1.0
	v_rcp_f32_e32 v225, v224
	s_nop 0
	v_fma_f32 v226, -v224, v225, 1.0
	v_fmac_f32_e32 v225, v226, v225
	v_div_scale_f32 v226, vcc, 1.0, v6, 1.0
	v_mul_f32_e32 v227, v226, v225
	v_fma_f32 v228, -v224, v227, v226
	v_fmac_f32_e32 v227, v228, v225
	v_fma_f32 v224, -v224, v227, v226
	v_div_fmas_f32 v224, v224, v225, v227
	v_div_fixup_f32 v6, v224, v6, 1.0
	v_div_scale_f32 v224, s[16:17], v7, v7, 1.0
	v_rcp_f32_e32 v225, v224
	s_nop 0
	v_fma_f32 v226, -v224, v225, 1.0
	v_fmac_f32_e32 v225, v226, v225
	v_div_scale_f32 v226, vcc, 1.0, v7, 1.0
	v_mul_f32_e32 v227, v226, v225
	v_fma_f32 v228, -v224, v227, v226
	v_fmac_f32_e32 v227, v228, v225
	v_fma_f32 v224, -v224, v227, v226
	v_div_fmas_f32 v224, v224, v225, v227
	v_div_fixup_f32 v7, v224, v7, 1.0
	v_lshlrev_b32_e32 v236, 16, v212
	v_and_b32_e32 v237, 0xffff0000, v212
	v_lshlrev_b32_e32 v238, 16, v213
	v_and_b32_e32 v239, 0xffff0000, v213
	v_pk_fma_f32 v[4:5], v[4:5], v[236:237], v[200:201]
	v_pk_fma_f32 v[6:7], v[6:7], v[238:239], v[202:203]
	v_cvt_pk_bf16_f32 v159, v6, v7
	v_cvt_pk_bf16_f32 v158, v4, v5
	global_store_dwordx4 v[150:151], v[4:7], off offset:512
	global_store_dwordx2 v[156:157], v[158:159], off offset:256
	s_nop 0
	v_mul_f32_e32 v5, v5, v5
	v_mul_f32_e32 v7, v7, v7
	v_fmac_f32_e32 v5, v4, v4
	v_fmac_f32_e32 v7, v6, v6
	v_add_f32_e32 v4, v5, v7
	v_add_f32_e32 v229, v229, v4
	v_pk_mul_f32 v[0:1], v[0:1], v[234:235] op_sel_hi:[1,0]
	v_pk_mul_f32 v[2:3], v[2:3], v[234:235] op_sel_hi:[1,0]
	v_mul_f32_e32 v0, 0xbfb8aa3b, v0
	v_mul_f32_e32 v1, 0xbfb8aa3b, v1
	v_mul_f32_e32 v2, 0xbfb8aa3b, v2
	v_mul_f32_e32 v3, 0xbfb8aa3b, v3
	v_exp_f32_e32 v0, v0
	v_exp_f32_e32 v1, v1
	v_exp_f32_e32 v2, v2
	v_exp_f32_e32 v3, v3
	v_pk_add_f32 v[0:1], v[0:1], 1.0 op_sel_hi:[1,0]
	v_pk_add_f32 v[2:3], v[2:3], 1.0 op_sel_hi:[1,0]
	v_div_scale_f32 v224, s[16:17], v0, v0, 1.0
	v_rcp_f32_e32 v225, v224
	s_nop 0
	v_fma_f32 v226, -v224, v225, 1.0
	v_fmac_f32_e32 v225, v226, v225
	v_div_scale_f32 v226, vcc, 1.0, v0, 1.0
	v_mul_f32_e32 v227, v226, v225
	v_fma_f32 v228, -v224, v227, v226
	v_fmac_f32_e32 v227, v228, v225
	v_fma_f32 v224, -v224, v227, v226
	v_div_fmas_f32 v224, v224, v225, v227
	v_div_fixup_f32 v0, v224, v0, 1.0
	v_div_scale_f32 v224, s[16:17], v1, v1, 1.0
	v_rcp_f32_e32 v225, v224
	s_nop 0
	v_fma_f32 v226, -v224, v225, 1.0
	v_fmac_f32_e32 v225, v226, v225
	v_div_scale_f32 v226, vcc, 1.0, v1, 1.0
	v_mul_f32_e32 v227, v226, v225
	v_fma_f32 v228, -v224, v227, v226
	v_fmac_f32_e32 v227, v228, v225
	v_fma_f32 v224, -v224, v227, v226
	v_div_fmas_f32 v224, v224, v225, v227
	v_div_fixup_f32 v1, v224, v1, 1.0
	v_div_scale_f32 v224, s[16:17], v2, v2, 1.0
	v_rcp_f32_e32 v225, v224
	s_nop 0
	v_fma_f32 v226, -v224, v225, 1.0
	v_fmac_f32_e32 v225, v226, v225
	v_div_scale_f32 v226, vcc, 1.0, v2, 1.0
	v_mul_f32_e32 v227, v226, v225
	v_fma_f32 v228, -v224, v227, v226
	v_fmac_f32_e32 v227, v228, v225
	v_fma_f32 v224, -v224, v227, v226
	v_div_fmas_f32 v224, v224, v225, v227
	v_div_fixup_f32 v2, v224, v2, 1.0
	v_div_scale_f32 v224, s[16:17], v3, v3, 1.0
	v_rcp_f32_e32 v225, v224
	s_nop 0
	v_fma_f32 v226, -v224, v225, 1.0
	v_fmac_f32_e32 v225, v226, v225
	v_div_scale_f32 v226, vcc, 1.0, v3, 1.0
	v_mul_f32_e32 v227, v226, v225
	v_fma_f32 v228, -v224, v227, v226
	v_fmac_f32_e32 v227, v228, v225
	v_fma_f32 v224, -v224, v227, v226
	v_div_fmas_f32 v224, v224, v225, v227
	v_div_fixup_f32 v3, v224, v3, 1.0
	v_lshlrev_b32_e32 v236, 16, v214
	v_and_b32_e32 v237, 0xffff0000, v214
	v_lshlrev_b32_e32 v238, 16, v215
	v_and_b32_e32 v239, 0xffff0000, v215
	v_pk_fma_f32 v[0:1], v[0:1], v[236:237], v[204:205]
	v_pk_fma_f32 v[2:3], v[2:3], v[238:239], v[206:207]
	v_cvt_pk_bf16_f32 v159, v2, v3
	v_cvt_pk_bf16_f32 v158, v0, v1
	global_store_dwordx4 v[150:151], v[0:3], off offset:576
	global_store_dwordx2 v[156:157], v[158:159], off offset:288
	s_nop 0
	v_mul_f32_e32 v1, v1, v1
	v_mul_f32_e32 v3, v3, v3
	v_fmac_f32_e32 v1, v0, v0
	v_fmac_f32_e32 v3, v2, v2
	v_add_f32_e32 v0, v1, v3
	v_add_f32_e32 v229, v229, v0
	v_mov_b32_e32 v230, v229
	s_nop 1
	v_permlane16_swap_b32_e32 v229, v230
	v_add_f32_e32 v229, v229, v230
	v_mov_b32_e32 v230, v229
	s_nop 1
	v_permlane32_swap_b32_e32 v229, v230
	s_and_saveexec_b64 s[16:17], s[10:11]
	v_lshl_add_u64 v[156:157], v[144:145], 2, s[22:23]
	v_add_f32_e32 v229, v229, v230
	global_atomic_add_f32 v[156:157], v229, off
	s_or_b64 exec, exec, s[16:17]
	s_branch .LBB0_739

.LBB0_1893:
	ds_read_b128 v[144:147], v161
	ds_read_b128 v[148:151], v161 offset:1024
	ds_read_b128 v[152:155], v161 offset:2048
	ds_read_b128 v[156:159], v161 offset:3072
	s_add_u32 s56, s14, 0xfff80080
	s_addc_u32 s57, s15, -1
	s_cmp_eq_u32 s64, 28
	s_cselect_b32 s59, s11, s57
	s_cselect_b32 s58, s13, s56
	s_cselect_b32 s57, s23, s63
	s_cselect_b32 s56, s51, s62
	v_lshl_add_u64 v[198:199], s[14:15], 0, v[134:135]
	s_add_i32 m0, s26, 0xc000
	ds_read_b128 v[166:169], v162
	ds_read_b128 v[170:173], v162 offset:1024
	ds_read_b128 v[174:177], v162 offset:2048
	ds_read_b128 v[178:181], v162 offset:3072
	ds_read_b128 v[182:185], v162 offset:4096
	ds_read_b128 v[186:189], v162 offset:5120
	ds_read_b128 v[190:193], v162 offset:6144
	ds_read_b128 v[194:197], v162 offset:7168
	global_load_lds_dwordx4 v[198:199], off
	v_lshl_add_u64 v[198:199], s[14:15], 0, v[138:139]
	s_add_i32 m0, s26, 0xe000
	s_nop 0
	global_load_lds_dwordx4 v[198:199], off
	s_waitcnt lgkmcnt(8)
	s_barrier
	s_waitcnt lgkmcnt(0)
	s_setprio 1
	s_waitcnt lgkmcnt(0)
	v_mfma_f32_16x16x32_bf16 v[124:127], v[144:147], v[166:169], v[124:127]
	v_mfma_f32_16x16x32_bf16 v[120:123], v[152:155], v[166:169], v[120:123]
	v_mfma_f32_16x16x32_bf16 v[108:111], v[144:147], v[174:177], v[108:111]
	v_mfma_f32_16x16x32_bf16 v[104:107], v[152:155], v[174:177], v[104:107]
	v_mfma_f32_16x16x32_bf16 v[92:95], v[144:147], v[182:185], v[92:95]
	v_mfma_f32_16x16x32_bf16 v[88:91], v[152:155], v[182:185], v[88:91]
	v_mfma_f32_16x16x32_bf16 v[76:79], v[144:147], v[190:193], v[76:79]
	v_mfma_f32_16x16x32_bf16 v[72:75], v[152:155], v[190:193], v[72:75]
	v_mfma_f32_16x16x32_bf16 v[124:127], v[148:151], v[170:173], v[124:127]
	v_mfma_f32_16x16x32_bf16 v[120:123], v[156:159], v[170:173], v[120:123]
	v_mfma_f32_16x16x32_bf16 v[108:111], v[148:151], v[178:181], v[108:111]
	v_mfma_f32_16x16x32_bf16 v[104:107], v[156:159], v[178:181], v[104:107]
	v_mfma_f32_16x16x32_bf16 v[92:95], v[148:151], v[186:189], v[92:95]
	v_mfma_f32_16x16x32_bf16 v[88:91], v[156:159], v[186:189], v[88:91]
	v_mfma_f32_16x16x32_bf16 v[76:79], v[148:151], v[194:197], v[76:79]
	v_mfma_f32_16x16x32_bf16 v[72:75], v[156:159], v[194:197], v[72:75]
	s_setprio 0
	s_barrier
	s_add_i32 s65, s49, s5
	v_lshl_add_u64 v[214:215], s[56:57], 0, v[128:129]
	s_mov_b32 m0, s65
	ds_read_b128 v[198:201], v163
	ds_read_b128 v[202:205], v163 offset:1024
	ds_read_b128 v[206:209], v163 offset:2048
	ds_read_b128 v[210:213], v163 offset:3072
	global_load_lds_dwordx4 v[214:215], off
	v_lshl_add_u64 v[216:217], s[56:57], 0, v[130:131]
	s_add_i32 m0, s65, 0x2000
	s_nop 0
	global_load_lds_dwordx4 v[216:217], off
	s_barrier
	s_waitcnt lgkmcnt(0)
	s_setprio 1
	s_waitcnt lgkmcnt(0)
	v_mfma_f32_16x16x32_bf16 v[116:119], v[198:201], v[166:169], v[116:119]
	v_mfma_f32_16x16x32_bf16 v[112:115], v[206:209], v[166:169], v[112:115]
	v_mfma_f32_16x16x32_bf16 v[100:103], v[198:201], v[174:177], v[100:103]
	v_mfma_f32_16x16x32_bf16 v[96:99], v[206:209], v[174:177], v[96:99]
	v_mfma_f32_16x16x32_bf16 v[84:87], v[198:201], v[182:185], v[84:87]
	v_mfma_f32_16x16x32_bf16 v[80:83], v[206:209], v[182:185], v[80:83]
	v_mfma_f32_16x16x32_bf16 v[68:71], v[198:201], v[190:193], v[68:71]
	v_mfma_f32_16x16x32_bf16 v[64:67], v[206:209], v[190:193], v[64:67]
	v_mfma_f32_16x16x32_bf16 v[116:119], v[202:205], v[170:173], v[116:119]
	v_mfma_f32_16x16x32_bf16 v[112:115], v[210:213], v[170:173], v[112:115]
	v_mfma_f32_16x16x32_bf16 v[100:103], v[202:205], v[178:181], v[100:103]
	v_mfma_f32_16x16x32_bf16 v[96:99], v[210:213], v[178:181], v[96:99]
	v_mfma_f32_16x16x32_bf16 v[84:87], v[202:205], v[186:189], v[84:87]
	v_mfma_f32_16x16x32_bf16 v[80:83], v[210:213], v[186:189], v[80:83]
	v_mfma_f32_16x16x32_bf16 v[68:71], v[202:205], v[194:197], v[68:71]
	v_mfma_f32_16x16x32_bf16 v[64:67], v[210:213], v[194:197], v[64:67]
	s_setprio 0
	s_mov_b32 m0, s26
	v_lshl_add_u64 v[218:219], s[58:59], 0, v[128:129]
	s_barrier
	ds_read_b128 v[166:169], v162 offset:16384
	ds_read_b128 v[170:173], v162 offset:17408
	ds_read_b128 v[174:177], v162 offset:18432
	ds_read_b128 v[178:181], v162 offset:19456
	ds_read_b128 v[182:185], v162 offset:20480
	ds_read_b128 v[186:189], v162 offset:21504
	ds_read_b128 v[190:193], v162 offset:22528
	ds_read_b128 v[194:197], v162 offset:23552
	global_load_lds_dwordx4 v[218:219], off
	v_lshl_add_u64 v[220:221], s[58:59], 0, v[130:131]
	s_mov_b32 m0, s27
	s_nop 0
	global_load_lds_dwordx4 v[220:221], off
	s_barrier
	s_waitcnt lgkmcnt(0)
	s_setprio 1
	s_waitcnt lgkmcnt(0)
	v_mfma_f32_16x16x32_bf16 v[60:63], v[144:147], v[166:169], v[60:63]
	v_mfma_f32_16x16x32_bf16 v[56:59], v[152:155], v[166:169], v[56:59]
	v_mfma_f32_16x16x32_bf16 v[44:47], v[144:147], v[174:177], v[44:47]
	v_mfma_f32_16x16x32_bf16 v[40:43], v[152:155], v[174:177], v[40:43]
	v_mfma_f32_16x16x32_bf16 v[28:31], v[144:147], v[182:185], v[28:31]
	v_mfma_f32_16x16x32_bf16 v[24:27], v[152:155], v[182:185], v[24:27]
	v_mfma_f32_16x16x32_bf16 v[12:15], v[144:147], v[190:193], v[12:15]
	v_mfma_f32_16x16x32_bf16 v[8:11], v[152:155], v[190:193], v[8:11]
	v_mfma_f32_16x16x32_bf16 v[60:63], v[148:151], v[170:173], v[60:63]
	v_mfma_f32_16x16x32_bf16 v[56:59], v[156:159], v[170:173], v[56:59]
	v_mfma_f32_16x16x32_bf16 v[44:47], v[148:151], v[178:181], v[44:47]
	v_mfma_f32_16x16x32_bf16 v[40:43], v[156:159], v[178:181], v[40:43]
	v_mfma_f32_16x16x32_bf16 v[28:31], v[148:151], v[186:189], v[28:31]
	v_mfma_f32_16x16x32_bf16 v[24:27], v[156:159], v[186:189], v[24:27]
	v_mfma_f32_16x16x32_bf16 v[12:15], v[148:151], v[194:197], v[12:15]
	v_mfma_f32_16x16x32_bf16 v[8:11], v[156:159], v[194:197], v[8:11]
	s_setprio 0
	s_barrier
	s_add_u32 s66, s56, 0x80000
	s_addc_u32 s67, s57, 0
	s_add_i32 s65, s60, s5
	v_lshl_add_u64 v[144:145], s[66:67], 0, v[128:129]
	s_mov_b32 m0, s65
	s_nop 0
	global_load_lds_dwordx4 v[144:145], off
	v_lshl_add_u64 v[144:145], s[66:67], 0, v[130:131]
	s_add_i32 m0, s65, 0x2000
	s_nop 0
	global_load_lds_dwordx4 v[144:145], off
	s_waitcnt vmcnt(6)
	s_barrier
	s_setprio 1
	v_mfma_f32_16x16x32_bf16 v[52:55], v[198:201], v[166:169], v[52:55]
	v_mfma_f32_16x16x32_bf16 v[48:51], v[206:209], v[166:169], v[48:51]
	v_mfma_f32_16x16x32_bf16 v[36:39], v[198:201], v[174:177], v[36:39]
	v_mfma_f32_16x16x32_bf16 v[32:35], v[206:209], v[174:177], v[32:35]
	v_mfma_f32_16x16x32_bf16 v[20:23], v[198:201], v[182:185], v[20:23]
	v_mfma_f32_16x16x32_bf16 v[16:19], v[206:209], v[182:185], v[16:19]
	v_mfma_f32_16x16x32_bf16 v[4:7], v[198:201], v[190:193], v[4:7]
	v_mfma_f32_16x16x32_bf16 v[0:3], v[206:209], v[190:193], v[0:3]
	v_mfma_f32_16x16x32_bf16 v[52:55], v[202:205], v[170:173], v[52:55]
	v_mfma_f32_16x16x32_bf16 v[48:51], v[210:213], v[170:173], v[48:51]
	v_mfma_f32_16x16x32_bf16 v[36:39], v[202:205], v[178:181], v[36:39]
	v_mfma_f32_16x16x32_bf16 v[32:35], v[210:213], v[178:181], v[32:35]
	v_mfma_f32_16x16x32_bf16 v[20:23], v[202:205], v[186:189], v[20:23]
	v_mfma_f32_16x16x32_bf16 v[16:19], v[210:213], v[186:189], v[16:19]
	v_mfma_f32_16x16x32_bf16 v[4:7], v[202:205], v[194:197], v[4:7]
	v_mfma_f32_16x16x32_bf16 v[0:3], v[210:213], v[194:197], v[0:3]
	s_setprio 0
	s_add_i32 s65, 16, 0x18000
	v_add_u32_e32 v156, s65, v137
	s_barrier
	ds_read_b128 v[144:147], v156
	ds_read_b128 v[148:151], v156 offset:1024
	ds_read_b128 v[152:155], v156 offset:2048
	ds_read_b128 v[156:159], v156 offset:3072
	s_add_u32 s58, s58, 0x80000
	s_addc_u32 s59, s59, 0
	s_mov_b32 m0, s39
	v_lshl_add_u64 v[198:199], s[58:59], 0, v[128:129]
	ds_read_b128 v[166:169], v162 offset:32768
	ds_read_b128 v[170:173], v162 offset:33792
	ds_read_b128 v[174:177], v162 offset:34816
	ds_read_b128 v[178:181], v162 offset:35840
	ds_read_b128 v[182:185], v162 offset:36864
	ds_read_b128 v[186:189], v162 offset:37888
	ds_read_b128 v[190:193], v162 offset:38912
	ds_read_b128 v[194:197], v162 offset:39936
	global_load_lds_dwordx4 v[198:199], off
	v_lshl_add_u64 v[198:199], s[58:59], 0, v[130:131]
	s_mov_b32 m0, s44
	s_nop 0
	global_load_lds_dwordx4 v[198:199], off
	s_waitcnt lgkmcnt(8)
	s_barrier
	s_waitcnt lgkmcnt(0)
	s_setprio 1
	s_waitcnt lgkmcnt(0)
	v_mfma_f32_16x16x32_bf16 v[124:127], v[144:147], v[166:169], v[124:127]
	v_mfma_f32_16x16x32_bf16 v[120:123], v[152:155], v[166:169], v[120:123]
	v_mfma_f32_16x16x32_bf16 v[108:111], v[144:147], v[174:177], v[108:111]
	v_mfma_f32_16x16x32_bf16 v[104:107], v[152:155], v[174:177], v[104:107]
	v_mfma_f32_16x16x32_bf16 v[92:95], v[144:147], v[182:185], v[92:95]
	v_mfma_f32_16x16x32_bf16 v[88:91], v[152:155], v[182:185], v[88:91]
	v_mfma_f32_16x16x32_bf16 v[76:79], v[144:147], v[190:193], v[76:79]
	v_mfma_f32_16x16x32_bf16 v[72:75], v[152:155], v[190:193], v[72:75]
	v_mfma_f32_16x16x32_bf16 v[124:127], v[148:151], v[170:173], v[124:127]
	v_mfma_f32_16x16x32_bf16 v[120:123], v[156:159], v[170:173], v[120:123]
	v_mfma_f32_16x16x32_bf16 v[108:111], v[148:151], v[178:181], v[108:111]
	v_mfma_f32_16x16x32_bf16 v[104:107], v[156:159], v[178:181], v[104:107]
	v_mfma_f32_16x16x32_bf16 v[92:95], v[148:151], v[186:189], v[92:95]
	v_mfma_f32_16x16x32_bf16 v[88:91], v[156:159], v[186:189], v[88:91]
	v_mfma_f32_16x16x32_bf16 v[76:79], v[148:151], v[194:197], v[76:79]
	v_mfma_f32_16x16x32_bf16 v[72:75], v[156:159], v[194:197], v[72:75]
	s_setprio 0
	s_barrier
	s_add_i32 s58, 16, 0x1c000
	s_add_i32 s59, s65, s5
	v_add_u32_e32 v160, s58, v137
	v_lshl_add_u64 v[214:215], v[214:215], 0, s[20:21]
	s_mov_b32 m0, s59
	ds_read_b128 v[198:201], v160
	ds_read_b128 v[202:205], v160 offset:1024
	ds_read_b128 v[206:209], v160 offset:2048
	ds_read_b128 v[210:213], v160 offset:3072
	global_load_lds_dwordx4 v[214:215], off
	v_lshl_add_u64 v[214:215], v[216:217], 0, s[20:21]
	s_add_i32 m0, s59, 0x2000
	s_nop 0
	global_load_lds_dwordx4 v[214:215], off
	s_barrier
	s_waitcnt lgkmcnt(0)
	s_setprio 1
	s_waitcnt lgkmcnt(0)
	v_mfma_f32_16x16x32_bf16 v[116:119], v[198:201], v[166:169], v[116:119]
	v_mfma_f32_16x16x32_bf16 v[112:115], v[206:209], v[166:169], v[112:115]
	v_mfma_f32_16x16x32_bf16 v[100:103], v[198:201], v[174:177], v[100:103]
	v_mfma_f32_16x16x32_bf16 v[96:99], v[206:209], v[174:177], v[96:99]
	v_mfma_f32_16x16x32_bf16 v[84:87], v[198:201], v[182:185], v[84:87]
	v_mfma_f32_16x16x32_bf16 v[80:83], v[206:209], v[182:185], v[80:83]
	v_mfma_f32_16x16x32_bf16 v[68:71], v[198:201], v[190:193], v[68:71]
	v_mfma_f32_16x16x32_bf16 v[64:67], v[206:209], v[190:193], v[64:67]
	v_mfma_f32_16x16x32_bf16 v[116:119], v[202:205], v[170:173], v[116:119]
	v_mfma_f32_16x16x32_bf16 v[112:115], v[210:213], v[170:173], v[112:115]
	v_mfma_f32_16x16x32_bf16 v[100:103], v[202:205], v[178:181], v[100:103]
	v_mfma_f32_16x16x32_bf16 v[96:99], v[210:213], v[178:181], v[96:99]
	v_mfma_f32_16x16x32_bf16 v[84:87], v[202:205], v[186:189], v[84:87]
	v_mfma_f32_16x16x32_bf16 v[80:83], v[210:213], v[186:189], v[80:83]
	v_mfma_f32_16x16x32_bf16 v[68:71], v[202:205], v[194:197], v[68:71]
	v_mfma_f32_16x16x32_bf16 v[64:67], v[210:213], v[194:197], v[64:67]
	s_setprio 0
	s_mov_b32 m0, s45
	v_lshl_add_u64 v[214:215], v[218:219], 0, s[20:21]
	s_barrier
	ds_read_b128 v[166:169], v162 offset:49152
	ds_read_b128 v[170:173], v162 offset:50176
	ds_read_b128 v[174:177], v162 offset:51200
	ds_read_b128 v[178:181], v162 offset:52224
	ds_read_b128 v[182:185], v162 offset:53248
	ds_read_b128 v[186:189], v162 offset:54272
	ds_read_b128 v[190:193], v162 offset:55296
	ds_read_b128 v[194:197], v162 offset:56320
	global_load_lds_dwordx4 v[214:215], off
	v_lshl_add_u64 v[214:215], v[220:221], 0, s[20:21]
	s_mov_b32 m0, s46
	s_nop 0
	global_load_lds_dwordx4 v[214:215], off
	s_barrier
	s_waitcnt lgkmcnt(0)
	s_setprio 1
	s_waitcnt lgkmcnt(0)
	v_mfma_f32_16x16x32_bf16 v[60:63], v[144:147], v[166:169], v[60:63]
	v_mfma_f32_16x16x32_bf16 v[56:59], v[152:155], v[166:169], v[56:59]
	v_mfma_f32_16x16x32_bf16 v[44:47], v[144:147], v[174:177], v[44:47]
	v_mfma_f32_16x16x32_bf16 v[40:43], v[152:155], v[174:177], v[40:43]
	v_mfma_f32_16x16x32_bf16 v[28:31], v[144:147], v[182:185], v[28:31]
	v_mfma_f32_16x16x32_bf16 v[24:27], v[152:155], v[182:185], v[24:27]
	v_mfma_f32_16x16x32_bf16 v[12:15], v[144:147], v[190:193], v[12:15]
	v_mfma_f32_16x16x32_bf16 v[8:11], v[152:155], v[190:193], v[8:11]
	v_mfma_f32_16x16x32_bf16 v[60:63], v[148:151], v[170:173], v[60:63]
	v_mfma_f32_16x16x32_bf16 v[56:59], v[156:159], v[170:173], v[56:59]
	v_mfma_f32_16x16x32_bf16 v[44:47], v[148:151], v[178:181], v[44:47]
	v_mfma_f32_16x16x32_bf16 v[40:43], v[156:159], v[178:181], v[40:43]
	v_mfma_f32_16x16x32_bf16 v[28:31], v[148:151], v[186:189], v[28:31]
	v_mfma_f32_16x16x32_bf16 v[24:27], v[156:159], v[186:189], v[24:27]
	v_mfma_f32_16x16x32_bf16 v[12:15], v[148:151], v[194:197], v[12:15]
	v_mfma_f32_16x16x32_bf16 v[8:11], v[156:159], v[194:197], v[8:11]
	s_setprio 0
	s_barrier
	s_add_u32 s56, s56, 0x80080
	s_addc_u32 s57, s57, 0
	s_add_i32 s58, s58, s5
	v_lshl_add_u64 v[144:145], s[56:57], 0, v[128:129]
	s_mov_b32 m0, s58
	s_nop 0
	global_load_lds_dwordx4 v[144:145], off
	v_lshl_add_u64 v[144:145], s[56:57], 0, v[130:131]
	s_add_i32 m0, s58, 0x2000
	s_nop 0
	global_load_lds_dwordx4 v[144:145], off
	s_waitcnt vmcnt(6)
	s_barrier
	s_setprio 1
	v_mfma_f32_16x16x32_bf16 v[52:55], v[198:201], v[166:169], v[52:55]
	v_mfma_f32_16x16x32_bf16 v[48:51], v[206:209], v[166:169], v[48:51]
	v_mfma_f32_16x16x32_bf16 v[36:39], v[198:201], v[174:177], v[36:39]
	v_mfma_f32_16x16x32_bf16 v[32:35], v[206:209], v[174:177], v[32:35]
	v_mfma_f32_16x16x32_bf16 v[20:23], v[198:201], v[182:185], v[20:23]
	v_mfma_f32_16x16x32_bf16 v[16:19], v[206:209], v[182:185], v[16:19]
	v_mfma_f32_16x16x32_bf16 v[4:7], v[198:201], v[190:193], v[4:7]
	v_mfma_f32_16x16x32_bf16 v[0:3], v[206:209], v[190:193], v[0:3]
	v_mfma_f32_16x16x32_bf16 v[52:55], v[202:205], v[170:173], v[52:55]
	v_mfma_f32_16x16x32_bf16 v[48:51], v[210:213], v[170:173], v[48:51]
	v_mfma_f32_16x16x32_bf16 v[36:39], v[202:205], v[178:181], v[36:39]
	v_mfma_f32_16x16x32_bf16 v[32:35], v[210:213], v[178:181], v[32:35]
	v_mfma_f32_16x16x32_bf16 v[20:23], v[202:205], v[186:189], v[20:23]
	v_mfma_f32_16x16x32_bf16 v[16:19], v[210:213], v[186:189], v[16:19]
	v_mfma_f32_16x16x32_bf16 v[4:7], v[202:205], v[194:197], v[4:7]
	v_mfma_f32_16x16x32_bf16 v[0:3], v[210:213], v[194:197], v[0:3]
	s_setprio 0
	s_add_i32 s64, s64, 2
	s_add_u32 s14, s14, 0x100
	s_addc_u32 s15, s15, 0
	s_add_u32 s62, s62, 0x100
	s_addc_u32 s63, s63, 0
	s_cmp_gt_u32 s64, 29
	s_barrier
	s_cbranch_scc0 .LBB0_1893
	v_lshl_add_u32 v154, s12, 8, v133
	v_ashrrev_i32_e32 v155, 31, v154
	s_lshl_b32 s10, s10, 8
	s_ashr_i32 s11, s10, 31
	v_mov_b32_e32 v147, s11
	v_or_b32_e32 v146, s10, v132
	v_mov_b32_e32 v144, v154
	v_mov_b32_e32 v145, v155
	v_lshl_add_u64 v[148:149], v[144:145], 2, s[16:17]
	global_load_dword v216, v[148:149], off
	v_add_u32_e32 v144, 0x10, v154
	v_mov_b32_e32 v145, v155
	v_lshl_add_u64 v[148:149], v[144:145], 2, s[16:17]
	global_load_dword v217, v[148:149], off
	v_add_u32_e32 v144, 0x20, v154
	v_mov_b32_e32 v145, v155
	v_lshl_add_u64 v[148:149], v[144:145], 2, s[16:17]
	global_load_dword v218, v[148:149], off
	v_add_u32_e32 v144, 0x30, v154
	v_mov_b32_e32 v145, v155
	v_lshl_add_u64 v[148:149], v[144:145], 2, s[16:17]
	global_load_dword v219, v[148:149], off
	v_add_u32_e32 v144, 0x80, v154
	v_mov_b32_e32 v145, v155
	v_lshl_add_u64 v[148:149], v[144:145], 2, s[16:17]
	global_load_dword v220, v[148:149], off
	v_add_u32_e32 v144, 0x90, v154
	v_mov_b32_e32 v145, v155
	v_lshl_add_u64 v[148:149], v[144:145], 2, s[16:17]
	global_load_dword v221, v[148:149], off
	v_add_u32_e32 v144, 0xa0, v154
	v_mov_b32_e32 v145, v155
	v_lshl_add_u64 v[148:149], v[144:145], 2, s[16:17]
	global_load_dword v222, v[148:149], off
	v_add_u32_e32 v144, 0xb0, v154
	v_mov_b32_e32 v145, v155
	v_lshl_add_u64 v[148:149], v[144:145], 2, s[16:17]
	global_load_dword v223, v[148:149], off
	v_mov_b32_e32 v144, v154
	v_mov_b32_e32 v145, v155
	v_lshlrev_b64 v[148:149], 11, v[144:145]
	v_lshl_add_u64 v[148:149], v[148:149], 0, v[146:147]
	v_lshl_add_u64 v[150:151], v[148:149], 2, s[28:29]
	v_lshl_add_u64 v[152:153], v[148:149], 1, s[42:43]
	global_load_dwordx2 v[184:185], v[152:153], off
	global_load_dwordx4 v[168:171], v[150:151], off
	global_load_dwordx2 v[186:187], v[152:153], off offset:32
	global_load_dwordx4 v[172:175], v[150:151], off offset:64
	global_load_dwordx2 v[188:189], v[152:153], off offset:256
	global_load_dwordx4 v[176:179], v[150:151], off offset:512
	global_load_dwordx2 v[190:191], v[152:153], off offset:288
	global_load_dwordx4 v[180:183], v[150:151], off offset:576
	v_add_u32_e32 v144, 0x10, v154
	v_mov_b32_e32 v145, v155
	v_lshlrev_b64 v[148:149], 11, v[144:145]
	v_lshl_add_u64 v[148:149], v[148:149], 0, v[146:147]
	v_lshl_add_u64 v[150:151], v[148:149], 2, s[28:29]
	v_lshl_add_u64 v[152:153], v[148:149], 1, s[42:43]
	global_load_dwordx2 v[208:209], v[152:153], off
	global_load_dwordx4 v[192:195], v[150:151], off
	global_load_dwordx2 v[210:211], v[152:153], off offset:32
	global_load_dwordx4 v[196:199], v[150:151], off offset:64
	global_load_dwordx2 v[212:213], v[152:153], off offset:256
	global_load_dwordx4 v[200:203], v[150:151], off offset:512
	global_load_dwordx2 v[214:215], v[152:153], off offset:288
	global_load_dwordx4 v[204:207], v[150:151], off offset:576
	s_waitcnt vmcnt(8)
	v_fmamk_f32 v216, v216, 0x3a000000, v164
	v_mul_f32_e32 v235, 0x4b800000, v216
	v_cmp_gt_f32_e32 vcc, s61, v216
	s_nop 1
	v_cndmask_b32_e32 v216, v216, v235, vcc
	v_rsq_f32_e32 v216, v216
	s_nop 0
	v_mul_f32_e32 v235, 0x45800000, v216
	v_cndmask_b32_e32 v234, v216, v235, vcc
	v_mov_b32_e32 v144, v154
	v_mov_b32_e32 v145, v155
	v_lshlrev_b64 v[148:149], 11, v[144:145]
	v_lshl_add_u64 v[148:149], v[148:149], 0, v[146:147]
	v_lshl_add_u64 v[150:151], v[148:149], 2, s[28:29]
	v_lshl_add_u64 v[156:157], v[148:149], 1, s[24:25]
	v_pk_mul_f32 v[124:125], v[124:125], v[234:235] op_sel_hi:[1,0]
	v_pk_mul_f32 v[126:127], v[126:127], v[234:235] op_sel_hi:[1,0]
	v_mul_f32_e32 v124, 0xbfb8aa3b, v124
	v_mul_f32_e32 v125, 0xbfb8aa3b, v125
	v_mul_f32_e32 v126, 0xbfb8aa3b, v126
	v_mul_f32_e32 v127, 0xbfb8aa3b, v127
	v_exp_f32_e32 v124, v124
	v_exp_f32_e32 v125, v125
	v_exp_f32_e32 v126, v126
	v_exp_f32_e32 v127, v127
	v_pk_add_f32 v[124:125], v[124:125], 1.0 op_sel_hi:[1,0]
	v_pk_add_f32 v[126:127], v[126:127], 1.0 op_sel_hi:[1,0]
	v_div_scale_f32 v224, s[10:11], v124, v124, 1.0
	v_rcp_f32_e32 v225, v224
	s_nop 0
	v_fma_f32 v226, -v224, v225, 1.0
	v_fmac_f32_e32 v225, v226, v225
	v_div_scale_f32 v226, vcc, 1.0, v124, 1.0
	v_mul_f32_e32 v227, v226, v225
	v_fma_f32 v228, -v224, v227, v226
	v_fmac_f32_e32 v227, v228, v225
	v_fma_f32 v224, -v224, v227, v226
	v_div_fmas_f32 v224, v224, v225, v227
	v_div_fixup_f32 v124, v224, v124, 1.0
	v_div_scale_f32 v224, s[10:11], v125, v125, 1.0
	v_rcp_f32_e32 v225, v224
	s_nop 0
	v_fma_f32 v226, -v224, v225, 1.0
	v_fmac_f32_e32 v225, v226, v225
	v_div_scale_f32 v226, vcc, 1.0, v125, 1.0
	v_mul_f32_e32 v227, v226, v225
	v_fma_f32 v228, -v224, v227, v226
	v_fmac_f32_e32 v227, v228, v225
	v_fma_f32 v224, -v224, v227, v226
	v_div_fmas_f32 v224, v224, v225, v227
	v_div_fixup_f32 v125, v224, v125, 1.0
	v_div_scale_f32 v224, s[10:11], v126, v126, 1.0
	v_rcp_f32_e32 v225, v224
	s_nop 0
	v_fma_f32 v226, -v224, v225, 1.0
	v_fmac_f32_e32 v225, v226, v225
	v_div_scale_f32 v226, vcc, 1.0, v126, 1.0
	v_mul_f32_e32 v227, v226, v225
	v_fma_f32 v228, -v224, v227, v226
	v_fmac_f32_e32 v227, v228, v225
	v_fma_f32 v224, -v224, v227, v226
	v_div_fmas_f32 v224, v224, v225, v227
	v_div_fixup_f32 v126, v224, v126, 1.0
	v_div_scale_f32 v224, s[10:11], v127, v127, 1.0
	v_rcp_f32_e32 v225, v224
	s_nop 0
	v_fma_f32 v226, -v224, v225, 1.0
	v_fmac_f32_e32 v225, v226, v225
	v_div_scale_f32 v226, vcc, 1.0, v127, 1.0
	v_mul_f32_e32 v227, v226, v225
	v_fma_f32 v228, -v224, v227, v226
	v_fmac_f32_e32 v227, v228, v225
	v_fma_f32 v224, -v224, v227, v226
	v_div_fmas_f32 v224, v224, v225, v227
	v_div_fixup_f32 v127, v224, v127, 1.0
	v_lshlrev_b32_e32 v236, 16, v184
	v_and_b32_e32 v237, 0xffff0000, v184
	v_lshlrev_b32_e32 v238, 16, v185
	v_and_b32_e32 v239, 0xffff0000, v185
	v_pk_fma_f32 v[124:125], v[124:125], v[236:237], v[168:169]
	v_pk_fma_f32 v[126:127], v[126:127], v[238:239], v[170:171]
	v_cvt_pk_bf16_f32 v159, v126, v127
	v_cvt_pk_bf16_f32 v158, v124, v125
	global_store_dwordx4 v[150:151], v[124:127], off
	global_store_dwordx2 v[156:157], v[158:159], off
	s_nop 0
	v_mul_f32_e32 v125, v125, v125
	v_mul_f32_e32 v127, v127, v127
	v_fmac_f32_e32 v125, v124, v124
	v_fmac_f32_e32 v127, v126, v126
	v_add_f32_e32 v229, v125, v127
	v_pk_mul_f32 v[120:121], v[120:121], v[234:235] op_sel_hi:[1,0]
	v_pk_mul_f32 v[122:123], v[122:123], v[234:235] op_sel_hi:[1,0]
	v_mul_f32_e32 v120, 0xbfb8aa3b, v120
	v_mul_f32_e32 v121, 0xbfb8aa3b, v121
	v_mul_f32_e32 v122, 0xbfb8aa3b, v122
	v_mul_f32_e32 v123, 0xbfb8aa3b, v123
	v_exp_f32_e32 v120, v120
	v_exp_f32_e32 v121, v121
	v_exp_f32_e32 v122, v122
	v_exp_f32_e32 v123, v123
	v_pk_add_f32 v[120:121], v[120:121], 1.0 op_sel_hi:[1,0]
	v_pk_add_f32 v[122:123], v[122:123], 1.0 op_sel_hi:[1,0]
	v_div_scale_f32 v224, s[10:11], v120, v120, 1.0
	v_rcp_f32_e32 v225, v224
	s_nop 0
	v_fma_f32 v226, -v224, v225, 1.0
	v_fmac_f32_e32 v225, v226, v225
	v_div_scale_f32 v226, vcc, 1.0, v120, 1.0
	v_mul_f32_e32 v227, v226, v225
	v_fma_f32 v228, -v224, v227, v226
	v_fmac_f32_e32 v227, v228, v225
	v_fma_f32 v224, -v224, v227, v226
	v_div_fmas_f32 v224, v224, v225, v227
	v_div_fixup_f32 v120, v224, v120, 1.0
	v_div_scale_f32 v224, s[10:11], v121, v121, 1.0
	v_rcp_f32_e32 v225, v224
	s_nop 0
	v_fma_f32 v226, -v224, v225, 1.0
	v_fmac_f32_e32 v225, v226, v225
	v_div_scale_f32 v226, vcc, 1.0, v121, 1.0
	v_mul_f32_e32 v227, v226, v225
	v_fma_f32 v228, -v224, v227, v226
	v_fmac_f32_e32 v227, v228, v225
	v_fma_f32 v224, -v224, v227, v226
	v_div_fmas_f32 v224, v224, v225, v227
	v_div_fixup_f32 v121, v224, v121, 1.0
	v_div_scale_f32 v224, s[10:11], v122, v122, 1.0
	v_rcp_f32_e32 v225, v224
	s_nop 0
	v_fma_f32 v226, -v224, v225, 1.0
	v_fmac_f32_e32 v225, v226, v225
	v_div_scale_f32 v226, vcc, 1.0, v122, 1.0
	v_mul_f32_e32 v227, v226, v225
	v_fma_f32 v228, -v224, v227, v226
	v_fmac_f32_e32 v227, v228, v225
	v_fma_f32 v224, -v224, v227, v226
	v_div_fmas_f32 v224, v224, v225, v227
	v_div_fixup_f32 v122, v224, v122, 1.0
	v_div_scale_f32 v224, s[10:11], v123, v123, 1.0
	v_rcp_f32_e32 v225, v224
	s_nop 0
	v_fma_f32 v226, -v224, v225, 1.0
	v_fmac_f32_e32 v225, v226, v225
	v_div_scale_f32 v226, vcc, 1.0, v123, 1.0
	v_mul_f32_e32 v227, v226, v225
	v_fma_f32 v228, -v224, v227, v226
	v_fmac_f32_e32 v227, v228, v225
	v_fma_f32 v224, -v224, v227, v226
	v_div_fmas_f32 v224, v224, v225, v227
	v_div_fixup_f32 v123, v224, v123, 1.0
	v_lshlrev_b32_e32 v236, 16, v186
	v_and_b32_e32 v237, 0xffff0000, v186
	v_lshlrev_b32_e32 v238, 16, v187
	v_and_b32_e32 v239, 0xffff0000, v187
	v_pk_fma_f32 v[120:121], v[120:121], v[236:237], v[172:173]
	v_pk_fma_f32 v[122:123], v[122:123], v[238:239], v[174:175]
	v_cvt_pk_bf16_f32 v159, v122, v123
	v_cvt_pk_bf16_f32 v158, v120, v121
	global_store_dwordx4 v[150:151], v[120:123], off offset:64
	global_store_dwordx2 v[156:157], v[158:159], off offset:32
	s_nop 0
	v_mul_f32_e32 v121, v121, v121
	v_mul_f32_e32 v123, v123, v123
	v_fmac_f32_e32 v121, v120, v120
	v_fmac_f32_e32 v123, v122, v122
	v_add_f32_e32 v120, v121, v123
	v_add_f32_e32 v229, v229, v120
	v_pk_mul_f32 v[116:117], v[116:117], v[234:235] op_sel_hi:[1,0]
	v_pk_mul_f32 v[118:119], v[118:119], v[234:235] op_sel_hi:[1,0]
	v_mul_f32_e32 v116, 0xbfb8aa3b, v116
	v_mul_f32_e32 v117, 0xbfb8aa3b, v117
	v_mul_f32_e32 v118, 0xbfb8aa3b, v118
	v_mul_f32_e32 v119, 0xbfb8aa3b, v119
	v_exp_f32_e32 v116, v116
	v_exp_f32_e32 v117, v117
	v_exp_f32_e32 v118, v118
	v_exp_f32_e32 v119, v119
	v_pk_add_f32 v[116:117], v[116:117], 1.0 op_sel_hi:[1,0]
	v_pk_add_f32 v[118:119], v[118:119], 1.0 op_sel_hi:[1,0]
	v_div_scale_f32 v224, s[10:11], v116, v116, 1.0
	v_rcp_f32_e32 v225, v224
	s_nop 0
	v_fma_f32 v226, -v224, v225, 1.0
	v_fmac_f32_e32 v225, v226, v225
	v_div_scale_f32 v226, vcc, 1.0, v116, 1.0
	v_mul_f32_e32 v227, v226, v225
	v_fma_f32 v228, -v224, v227, v226
	v_fmac_f32_e32 v227, v228, v225
	v_fma_f32 v224, -v224, v227, v226
	v_div_fmas_f32 v224, v224, v225, v227
	v_div_fixup_f32 v116, v224, v116, 1.0
	v_div_scale_f32 v224, s[10:11], v117, v117, 1.0
	v_rcp_f32_e32 v225, v224
	s_nop 0
	v_fma_f32 v226, -v224, v225, 1.0
	v_fmac_f32_e32 v225, v226, v225
	v_div_scale_f32 v226, vcc, 1.0, v117, 1.0
	v_mul_f32_e32 v227, v226, v225
	v_fma_f32 v228, -v224, v227, v226
	v_fmac_f32_e32 v227, v228, v225
	v_fma_f32 v224, -v224, v227, v226
	v_div_fmas_f32 v224, v224, v225, v227
	v_div_fixup_f32 v117, v224, v117, 1.0
	v_div_scale_f32 v224, s[10:11], v118, v118, 1.0
	v_rcp_f32_e32 v225, v224
	s_nop 0
	v_fma_f32 v226, -v224, v225, 1.0
	v_fmac_f32_e32 v225, v226, v225
	v_div_scale_f32 v226, vcc, 1.0, v118, 1.0
	v_mul_f32_e32 v227, v226, v225
	v_fma_f32 v228, -v224, v227, v226
	v_fmac_f32_e32 v227, v228, v225
	v_fma_f32 v224, -v224, v227, v226
	v_div_fmas_f32 v224, v224, v225, v227
	v_div_fixup_f32 v118, v224, v118, 1.0
	v_div_scale_f32 v224, s[10:11], v119, v119, 1.0
	v_rcp_f32_e32 v225, v224
	s_nop 0
	v_fma_f32 v226, -v224, v225, 1.0
	v_fmac_f32_e32 v225, v226, v225
	v_div_scale_f32 v226, vcc, 1.0, v119, 1.0
	v_mul_f32_e32 v227, v226, v225
	v_fma_f32 v228, -v224, v227, v226
	v_fmac_f32_e32 v227, v228, v225
	v_fma_f32 v224, -v224, v227, v226
	v_div_fmas_f32 v224, v224, v225, v227
	v_div_fixup_f32 v119, v224, v119, 1.0
	v_lshlrev_b32_e32 v236, 16, v188
	v_and_b32_e32 v237, 0xffff0000, v188
	v_lshlrev_b32_e32 v238, 16, v189
	v_and_b32_e32 v239, 0xffff0000, v189
	v_pk_fma_f32 v[116:117], v[116:117], v[236:237], v[176:177]
	v_pk_fma_f32 v[118:119], v[118:119], v[238:239], v[178:179]
	v_cvt_pk_bf16_f32 v159, v118, v119
	v_cvt_pk_bf16_f32 v158, v116, v117
	global_store_dwordx4 v[150:151], v[116:119], off offset:512
	global_store_dwordx2 v[156:157], v[158:159], off offset:256
	s_nop 0
	v_mul_f32_e32 v117, v117, v117
	v_mul_f32_e32 v119, v119, v119
	v_fmac_f32_e32 v117, v116, v116
	v_fmac_f32_e32 v119, v118, v118
	v_add_f32_e32 v116, v117, v119
	v_add_f32_e32 v229, v229, v116
	v_pk_mul_f32 v[112:113], v[112:113], v[234:235] op_sel_hi:[1,0]
	v_pk_mul_f32 v[114:115], v[114:115], v[234:235] op_sel_hi:[1,0]
	v_mul_f32_e32 v112, 0xbfb8aa3b, v112
	v_mul_f32_e32 v113, 0xbfb8aa3b, v113
	v_mul_f32_e32 v114, 0xbfb8aa3b, v114
	v_mul_f32_e32 v115, 0xbfb8aa3b, v115
	v_exp_f32_e32 v112, v112
	v_exp_f32_e32 v113, v113
	v_exp_f32_e32 v114, v114
	v_exp_f32_e32 v115, v115
	v_pk_add_f32 v[112:113], v[112:113], 1.0 op_sel_hi:[1,0]
	v_pk_add_f32 v[114:115], v[114:115], 1.0 op_sel_hi:[1,0]
	v_div_scale_f32 v224, s[10:11], v112, v112, 1.0
	v_rcp_f32_e32 v225, v224
	s_nop 0
	v_fma_f32 v226, -v224, v225, 1.0
	v_fmac_f32_e32 v225, v226, v225
	v_div_scale_f32 v226, vcc, 1.0, v112, 1.0
	v_mul_f32_e32 v227, v226, v225
	v_fma_f32 v228, -v224, v227, v226
	v_fmac_f32_e32 v227, v228, v225
	v_fma_f32 v224, -v224, v227, v226
	v_div_fmas_f32 v224, v224, v225, v227
	v_div_fixup_f32 v112, v224, v112, 1.0
	v_div_scale_f32 v224, s[10:11], v113, v113, 1.0
	v_rcp_f32_e32 v225, v224
	s_nop 0
	v_fma_f32 v226, -v224, v225, 1.0
	v_fmac_f32_e32 v225, v226, v225
	v_div_scale_f32 v226, vcc, 1.0, v113, 1.0
	v_mul_f32_e32 v227, v226, v225
	v_fma_f32 v228, -v224, v227, v226
	v_fmac_f32_e32 v227, v228, v225
	v_fma_f32 v224, -v224, v227, v226
	v_div_fmas_f32 v224, v224, v225, v227
	v_div_fixup_f32 v113, v224, v113, 1.0
	v_div_scale_f32 v224, s[10:11], v114, v114, 1.0
	v_rcp_f32_e32 v225, v224
	s_nop 0
	v_fma_f32 v226, -v224, v225, 1.0
	v_fmac_f32_e32 v225, v226, v225
	v_div_scale_f32 v226, vcc, 1.0, v114, 1.0
	v_mul_f32_e32 v227, v226, v225
	v_fma_f32 v228, -v224, v227, v226
	v_fmac_f32_e32 v227, v228, v225
	v_fma_f32 v224, -v224, v227, v226
	v_div_fmas_f32 v224, v224, v225, v227
	v_div_fixup_f32 v114, v224, v114, 1.0
	v_div_scale_f32 v224, s[10:11], v115, v115, 1.0
	v_rcp_f32_e32 v225, v224
	s_nop 0
	v_fma_f32 v226, -v224, v225, 1.0
	v_fmac_f32_e32 v225, v226, v225
	v_div_scale_f32 v226, vcc, 1.0, v115, 1.0
	v_mul_f32_e32 v227, v226, v225
	v_fma_f32 v228, -v224, v227, v226
	v_fmac_f32_e32 v227, v228, v225
	v_fma_f32 v224, -v224, v227, v226
	v_div_fmas_f32 v224, v224, v225, v227
	v_div_fixup_f32 v115, v224, v115, 1.0
	v_lshlrev_b32_e32 v236, 16, v190
	v_and_b32_e32 v237, 0xffff0000, v190
	v_lshlrev_b32_e32 v238, 16, v191
	v_and_b32_e32 v239, 0xffff0000, v191
	v_pk_fma_f32 v[112:113], v[112:113], v[236:237], v[180:181]
	v_pk_fma_f32 v[114:115], v[114:115], v[238:239], v[182:183]
	v_cvt_pk_bf16_f32 v159, v114, v115
	v_cvt_pk_bf16_f32 v158, v112, v113
	global_store_dwordx4 v[150:151], v[112:115], off offset:576
	global_store_dwordx2 v[156:157], v[158:159], off offset:288
	s_nop 0
	v_mul_f32_e32 v113, v113, v113
	v_mul_f32_e32 v115, v115, v115
	v_fmac_f32_e32 v113, v112, v112
	v_fmac_f32_e32 v115, v114, v114
	v_add_f32_e32 v112, v113, v115
	v_add_f32_e32 v229, v229, v112
	v_mov_b32_e32 v230, v229
	s_nop 1
	v_permlane16_swap_b32_e32 v229, v230
	v_add_f32_e32 v229, v229, v230
	v_mov_b32_e32 v230, v229
	s_nop 1
	v_permlane32_swap_b32_e32 v229, v230
	s_and_saveexec_b64 s[10:11], s[6:7]
	v_lshl_add_u64 v[156:157], v[144:145], 2, s[18:19]
	v_add_f32_e32 v229, v229, v230
	global_atomic_add_f32 v[156:157], v229, off
	s_or_b64 exec, exec, s[10:11]
	v_add_u32_e32 v144, 0x20, v154
	v_mov_b32_e32 v145, v155
	v_lshlrev_b64 v[148:149], 11, v[144:145]
	v_lshl_add_u64 v[148:149], v[148:149], 0, v[146:147]
	v_lshl_add_u64 v[150:151], v[148:149], 2, s[28:29]
	v_lshl_add_u64 v[152:153], v[148:149], 1, s[42:43]
	global_load_dwordx2 v[184:185], v[152:153], off
	global_load_dwordx4 v[168:171], v[150:151], off
	global_load_dwordx2 v[186:187], v[152:153], off offset:32
	global_load_dwordx4 v[172:175], v[150:151], off offset:64
	global_load_dwordx2 v[188:189], v[152:153], off offset:256
	global_load_dwordx4 v[176:179], v[150:151], off offset:512
	global_load_dwordx2 v[190:191], v[152:153], off offset:288
	global_load_dwordx4 v[180:183], v[150:151], off offset:576
	s_waitcnt vmcnt(17)
	v_fmamk_f32 v217, v217, 0x3a000000, v164
	v_mul_f32_e32 v235, 0x4b800000, v217
	v_cmp_gt_f32_e32 vcc, s61, v217
	s_nop 1
	v_cndmask_b32_e32 v217, v217, v235, vcc
	v_rsq_f32_e32 v217, v217
	s_nop 0
	v_mul_f32_e32 v235, 0x45800000, v217
	v_cndmask_b32_e32 v234, v217, v235, vcc
	v_add_u32_e32 v144, 0x10, v154
	v_mov_b32_e32 v145, v155
	v_lshlrev_b64 v[148:149], 11, v[144:145]
	v_lshl_add_u64 v[148:149], v[148:149], 0, v[146:147]
	v_lshl_add_u64 v[150:151], v[148:149], 2, s[28:29]
	v_lshl_add_u64 v[156:157], v[148:149], 1, s[24:25]
	v_pk_mul_f32 v[108:109], v[108:109], v[234:235] op_sel_hi:[1,0]
	v_pk_mul_f32 v[110:111], v[110:111], v[234:235] op_sel_hi:[1,0]
	v_mul_f32_e32 v108, 0xbfb8aa3b, v108
	v_mul_f32_e32 v109, 0xbfb8aa3b, v109
	v_mul_f32_e32 v110, 0xbfb8aa3b, v110
	v_mul_f32_e32 v111, 0xbfb8aa3b, v111
	v_exp_f32_e32 v108, v108
	v_exp_f32_e32 v109, v109
	v_exp_f32_e32 v110, v110
	v_exp_f32_e32 v111, v111
	v_pk_add_f32 v[108:109], v[108:109], 1.0 op_sel_hi:[1,0]
	v_pk_add_f32 v[110:111], v[110:111], 1.0 op_sel_hi:[1,0]
	v_div_scale_f32 v224, s[10:11], v108, v108, 1.0
	v_rcp_f32_e32 v225, v224
	s_nop 0
	v_fma_f32 v226, -v224, v225, 1.0
	v_fmac_f32_e32 v225, v226, v225
	v_div_scale_f32 v226, vcc, 1.0, v108, 1.0
	v_mul_f32_e32 v227, v226, v225
	v_fma_f32 v228, -v224, v227, v226
	v_fmac_f32_e32 v227, v228, v225
	v_fma_f32 v224, -v224, v227, v226
	v_div_fmas_f32 v224, v224, v225, v227
	v_div_fixup_f32 v108, v224, v108, 1.0
	v_div_scale_f32 v224, s[10:11], v109, v109, 1.0
	v_rcp_f32_e32 v225, v224
	s_nop 0
	v_fma_f32 v226, -v224, v225, 1.0
	v_fmac_f32_e32 v225, v226, v225
	v_div_scale_f32 v226, vcc, 1.0, v109, 1.0
	v_mul_f32_e32 v227, v226, v225
	v_fma_f32 v228, -v224, v227, v226
	v_fmac_f32_e32 v227, v228, v225
	v_fma_f32 v224, -v224, v227, v226
	v_div_fmas_f32 v224, v224, v225, v227
	v_div_fixup_f32 v109, v224, v109, 1.0
	v_div_scale_f32 v224, s[10:11], v110, v110, 1.0
	v_rcp_f32_e32 v225, v224
	s_nop 0
	v_fma_f32 v226, -v224, v225, 1.0
	v_fmac_f32_e32 v225, v226, v225
	v_div_scale_f32 v226, vcc, 1.0, v110, 1.0
	v_mul_f32_e32 v227, v226, v225
	v_fma_f32 v228, -v224, v227, v226
	v_fmac_f32_e32 v227, v228, v225
	v_fma_f32 v224, -v224, v227, v226
	v_div_fmas_f32 v224, v224, v225, v227
	v_div_fixup_f32 v110, v224, v110, 1.0
	v_div_scale_f32 v224, s[10:11], v111, v111, 1.0
	v_rcp_f32_e32 v225, v224
	s_nop 0
	v_fma_f32 v226, -v224, v225, 1.0
	v_fmac_f32_e32 v225, v226, v225
	v_div_scale_f32 v226, vcc, 1.0, v111, 1.0
	v_mul_f32_e32 v227, v226, v225
	v_fma_f32 v228, -v224, v227, v226
	v_fmac_f32_e32 v227, v228, v225
	v_fma_f32 v224, -v224, v227, v226
	v_div_fmas_f32 v224, v224, v225, v227
	v_div_fixup_f32 v111, v224, v111, 1.0
	v_lshlrev_b32_e32 v236, 16, v208
	v_and_b32_e32 v237, 0xffff0000, v208
	v_lshlrev_b32_e32 v238, 16, v209
	v_and_b32_e32 v239, 0xffff0000, v209
	v_pk_fma_f32 v[108:109], v[108:109], v[236:237], v[192:193]
	v_pk_fma_f32 v[110:111], v[110:111], v[238:239], v[194:195]
	v_cvt_pk_bf16_f32 v159, v110, v111
	v_cvt_pk_bf16_f32 v158, v108, v109
	global_store_dwordx4 v[150:151], v[108:111], off
	global_store_dwordx2 v[156:157], v[158:159], off
	s_nop 0
	v_mul_f32_e32 v109, v109, v109
	v_mul_f32_e32 v111, v111, v111
	v_fmac_f32_e32 v109, v108, v108
	v_fmac_f32_e32 v111, v110, v110
	v_add_f32_e32 v229, v109, v111
	v_pk_mul_f32 v[104:105], v[104:105], v[234:235] op_sel_hi:[1,0]
	v_pk_mul_f32 v[106:107], v[106:107], v[234:235] op_sel_hi:[1,0]
	v_mul_f32_e32 v104, 0xbfb8aa3b, v104
	v_mul_f32_e32 v105, 0xbfb8aa3b, v105
	v_mul_f32_e32 v106, 0xbfb8aa3b, v106
	v_mul_f32_e32 v107, 0xbfb8aa3b, v107
	v_exp_f32_e32 v104, v104
	v_exp_f32_e32 v105, v105
	v_exp_f32_e32 v106, v106
	v_exp_f32_e32 v107, v107
	v_pk_add_f32 v[104:105], v[104:105], 1.0 op_sel_hi:[1,0]
	v_pk_add_f32 v[106:107], v[106:107], 1.0 op_sel_hi:[1,0]
	v_div_scale_f32 v224, s[10:11], v104, v104, 1.0
	v_rcp_f32_e32 v225, v224
	s_nop 0
	v_fma_f32 v226, -v224, v225, 1.0
	v_fmac_f32_e32 v225, v226, v225
	v_div_scale_f32 v226, vcc, 1.0, v104, 1.0
	v_mul_f32_e32 v227, v226, v225
	v_fma_f32 v228, -v224, v227, v226
	v_fmac_f32_e32 v227, v228, v225
	v_fma_f32 v224, -v224, v227, v226
	v_div_fmas_f32 v224, v224, v225, v227
	v_div_fixup_f32 v104, v224, v104, 1.0
	v_div_scale_f32 v224, s[10:11], v105, v105, 1.0
	v_rcp_f32_e32 v225, v224
	s_nop 0
	v_fma_f32 v226, -v224, v225, 1.0
	v_fmac_f32_e32 v225, v226, v225
	v_div_scale_f32 v226, vcc, 1.0, v105, 1.0
	v_mul_f32_e32 v227, v226, v225
	v_fma_f32 v228, -v224, v227, v226
	v_fmac_f32_e32 v227, v228, v225
	v_fma_f32 v224, -v224, v227, v226
	v_div_fmas_f32 v224, v224, v225, v227
	v_div_fixup_f32 v105, v224, v105, 1.0
	v_div_scale_f32 v224, s[10:11], v106, v106, 1.0
	v_rcp_f32_e32 v225, v224
	s_nop 0
	v_fma_f32 v226, -v224, v225, 1.0
	v_fmac_f32_e32 v225, v226, v225
	v_div_scale_f32 v226, vcc, 1.0, v106, 1.0
	v_mul_f32_e32 v227, v226, v225
	v_fma_f32 v228, -v224, v227, v226
	v_fmac_f32_e32 v227, v228, v225
	v_fma_f32 v224, -v224, v227, v226
	v_div_fmas_f32 v224, v224, v225, v227
	v_div_fixup_f32 v106, v224, v106, 1.0
	v_div_scale_f32 v224, s[10:11], v107, v107, 1.0
	v_rcp_f32_e32 v225, v224
	s_nop 0
	v_fma_f32 v226, -v224, v225, 1.0
	v_fmac_f32_e32 v225, v226, v225
	v_div_scale_f32 v226, vcc, 1.0, v107, 1.0
	v_mul_f32_e32 v227, v226, v225
	v_fma_f32 v228, -v224, v227, v226
	v_fmac_f32_e32 v227, v228, v225
	v_fma_f32 v224, -v224, v227, v226
	v_div_fmas_f32 v224, v224, v225, v227
	v_div_fixup_f32 v107, v224, v107, 1.0
	v_lshlrev_b32_e32 v236, 16, v210
	v_and_b32_e32 v237, 0xffff0000, v210
	v_lshlrev_b32_e32 v238, 16, v211
	v_and_b32_e32 v239, 0xffff0000, v211
	v_pk_fma_f32 v[104:105], v[104:105], v[236:237], v[196:197]
	v_pk_fma_f32 v[106:107], v[106:107], v[238:239], v[198:199]
	v_cvt_pk_bf16_f32 v159, v106, v107
	v_cvt_pk_bf16_f32 v158, v104, v105
	global_store_dwordx4 v[150:151], v[104:107], off offset:64
	global_store_dwordx2 v[156:157], v[158:159], off offset:32
	s_nop 0
	v_mul_f32_e32 v105, v105, v105
	v_mul_f32_e32 v107, v107, v107
	v_fmac_f32_e32 v105, v104, v104
	v_fmac_f32_e32 v107, v106, v106
	v_add_f32_e32 v104, v105, v107
	v_add_f32_e32 v229, v229, v104
	v_pk_mul_f32 v[100:101], v[100:101], v[234:235] op_sel_hi:[1,0]
	v_pk_mul_f32 v[102:103], v[102:103], v[234:235] op_sel_hi:[1,0]
	v_mul_f32_e32 v100, 0xbfb8aa3b, v100
	v_mul_f32_e32 v101, 0xbfb8aa3b, v101
	v_mul_f32_e32 v102, 0xbfb8aa3b, v102
	v_mul_f32_e32 v103, 0xbfb8aa3b, v103
	v_exp_f32_e32 v100, v100
	v_exp_f32_e32 v101, v101
	v_exp_f32_e32 v102, v102
	v_exp_f32_e32 v103, v103
	v_pk_add_f32 v[100:101], v[100:101], 1.0 op_sel_hi:[1,0]
	v_pk_add_f32 v[102:103], v[102:103], 1.0 op_sel_hi:[1,0]
	v_div_scale_f32 v224, s[10:11], v100, v100, 1.0
	v_rcp_f32_e32 v225, v224
	s_nop 0
	v_fma_f32 v226, -v224, v225, 1.0
	v_fmac_f32_e32 v225, v226, v225
	v_div_scale_f32 v226, vcc, 1.0, v100, 1.0
	v_mul_f32_e32 v227, v226, v225
	v_fma_f32 v228, -v224, v227, v226
	v_fmac_f32_e32 v227, v228, v225
	v_fma_f32 v224, -v224, v227, v226
	v_div_fmas_f32 v224, v224, v225, v227
	v_div_fixup_f32 v100, v224, v100, 1.0
	v_div_scale_f32 v224, s[10:11], v101, v101, 1.0
	v_rcp_f32_e32 v225, v224
	s_nop 0
	v_fma_f32 v226, -v224, v225, 1.0
	v_fmac_f32_e32 v225, v226, v225
	v_div_scale_f32 v226, vcc, 1.0, v101, 1.0
	v_mul_f32_e32 v227, v226, v225
	v_fma_f32 v228, -v224, v227, v226
	v_fmac_f32_e32 v227, v228, v225
	v_fma_f32 v224, -v224, v227, v226
	v_div_fmas_f32 v224, v224, v225, v227
	v_div_fixup_f32 v101, v224, v101, 1.0
	v_div_scale_f32 v224, s[10:11], v102, v102, 1.0
	v_rcp_f32_e32 v225, v224
	s_nop 0
	v_fma_f32 v226, -v224, v225, 1.0
	v_fmac_f32_e32 v225, v226, v225
	v_div_scale_f32 v226, vcc, 1.0, v102, 1.0
	v_mul_f32_e32 v227, v226, v225
	v_fma_f32 v228, -v224, v227, v226
	v_fmac_f32_e32 v227, v228, v225
	v_fma_f32 v224, -v224, v227, v226
	v_div_fmas_f32 v224, v224, v225, v227
	v_div_fixup_f32 v102, v224, v102, 1.0
	v_div_scale_f32 v224, s[10:11], v103, v103, 1.0
	v_rcp_f32_e32 v225, v224
	s_nop 0
	v_fma_f32 v226, -v224, v225, 1.0
	v_fmac_f32_e32 v225, v226, v225
	v_div_scale_f32 v226, vcc, 1.0, v103, 1.0
	v_mul_f32_e32 v227, v226, v225
	v_fma_f32 v228, -v224, v227, v226
	v_fmac_f32_e32 v227, v228, v225
	v_fma_f32 v224, -v224, v227, v226
	v_div_fmas_f32 v224, v224, v225, v227
	v_div_fixup_f32 v103, v224, v103, 1.0
	v_lshlrev_b32_e32 v236, 16, v212
	v_and_b32_e32 v237, 0xffff0000, v212
	v_lshlrev_b32_e32 v238, 16, v213
	v_and_b32_e32 v239, 0xffff0000, v213
	v_pk_fma_f32 v[100:101], v[100:101], v[236:237], v[200:201]
	v_pk_fma_f32 v[102:103], v[102:103], v[238:239], v[202:203]
	v_cvt_pk_bf16_f32 v159, v102, v103
	v_cvt_pk_bf16_f32 v158, v100, v101
	global_store_dwordx4 v[150:151], v[100:103], off offset:512
	global_store_dwordx2 v[156:157], v[158:159], off offset:256
	s_nop 0
	v_mul_f32_e32 v101, v101, v101
	v_mul_f32_e32 v103, v103, v103
	v_fmac_f32_e32 v101, v100, v100
	v_fmac_f32_e32 v103, v102, v102
	v_add_f32_e32 v100, v101, v103
	v_add_f32_e32 v229, v229, v100
	v_pk_mul_f32 v[96:97], v[96:97], v[234:235] op_sel_hi:[1,0]
	v_pk_mul_f32 v[98:99], v[98:99], v[234:235] op_sel_hi:[1,0]
	v_mul_f32_e32 v96, 0xbfb8aa3b, v96
	v_mul_f32_e32 v97, 0xbfb8aa3b, v97
	v_mul_f32_e32 v98, 0xbfb8aa3b, v98
	v_mul_f32_e32 v99, 0xbfb8aa3b, v99
	v_exp_f32_e32 v96, v96
	v_exp_f32_e32 v97, v97
	v_exp_f32_e32 v98, v98
	v_exp_f32_e32 v99, v99
	v_pk_add_f32 v[96:97], v[96:97], 1.0 op_sel_hi:[1,0]
	v_pk_add_f32 v[98:99], v[98:99], 1.0 op_sel_hi:[1,0]
	v_div_scale_f32 v224, s[10:11], v96, v96, 1.0
	v_rcp_f32_e32 v225, v224
	s_nop 0
	v_fma_f32 v226, -v224, v225, 1.0
	v_fmac_f32_e32 v225, v226, v225
	v_div_scale_f32 v226, vcc, 1.0, v96, 1.0
	v_mul_f32_e32 v227, v226, v225
	v_fma_f32 v228, -v224, v227, v226
	v_fmac_f32_e32 v227, v228, v225
	v_fma_f32 v224, -v224, v227, v226
	v_div_fmas_f32 v224, v224, v225, v227
	v_div_fixup_f32 v96, v224, v96, 1.0
	v_div_scale_f32 v224, s[10:11], v97, v97, 1.0
	v_rcp_f32_e32 v225, v224
	s_nop 0
	v_fma_f32 v226, -v224, v225, 1.0
	v_fmac_f32_e32 v225, v226, v225
	v_div_scale_f32 v226, vcc, 1.0, v97, 1.0
	v_mul_f32_e32 v227, v226, v225
	v_fma_f32 v228, -v224, v227, v226
	v_fmac_f32_e32 v227, v228, v225
	v_fma_f32 v224, -v224, v227, v226
	v_div_fmas_f32 v224, v224, v225, v227
	v_div_fixup_f32 v97, v224, v97, 1.0
	v_div_scale_f32 v224, s[10:11], v98, v98, 1.0
	v_rcp_f32_e32 v225, v224
	s_nop 0
	v_fma_f32 v226, -v224, v225, 1.0
	v_fmac_f32_e32 v225, v226, v225
	v_div_scale_f32 v226, vcc, 1.0, v98, 1.0
	v_mul_f32_e32 v227, v226, v225
	v_fma_f32 v228, -v224, v227, v226
	v_fmac_f32_e32 v227, v228, v225
	v_fma_f32 v224, -v224, v227, v226
	v_div_fmas_f32 v224, v224, v225, v227
	v_div_fixup_f32 v98, v224, v98, 1.0
	v_div_scale_f32 v224, s[10:11], v99, v99, 1.0
	v_rcp_f32_e32 v225, v224
	s_nop 0
	v_fma_f32 v226, -v224, v225, 1.0
	v_fmac_f32_e32 v225, v226, v225
	v_div_scale_f32 v226, vcc, 1.0, v99, 1.0
	v_mul_f32_e32 v227, v226, v225
	v_fma_f32 v228, -v224, v227, v226
	v_fmac_f32_e32 v227, v228, v225
	v_fma_f32 v224, -v224, v227, v226
	v_div_fmas_f32 v224, v224, v225, v227
	v_div_fixup_f32 v99, v224, v99, 1.0
	v_lshlrev_b32_e32 v236, 16, v214
	v_and_b32_e32 v237, 0xffff0000, v214
	v_lshlrev_b32_e32 v238, 16, v215
	v_and_b32_e32 v239, 0xffff0000, v215
	v_pk_fma_f32 v[96:97], v[96:97], v[236:237], v[204:205]
	v_pk_fma_f32 v[98:99], v[98:99], v[238:239], v[206:207]
	v_cvt_pk_bf16_f32 v159, v98, v99
	v_cvt_pk_bf16_f32 v158, v96, v97
	global_store_dwordx4 v[150:151], v[96:99], off offset:576
	global_store_dwordx2 v[156:157], v[158:159], off offset:288
	s_nop 0
	v_mul_f32_e32 v97, v97, v97
	v_mul_f32_e32 v99, v99, v99
	v_fmac_f32_e32 v97, v96, v96
	v_fmac_f32_e32 v99, v98, v98
	v_add_f32_e32 v96, v97, v99
	v_add_f32_e32 v229, v229, v96
	v_mov_b32_e32 v230, v229
	s_nop 1
	v_permlane16_swap_b32_e32 v229, v230
	v_add_f32_e32 v229, v229, v230
	v_mov_b32_e32 v230, v229
	s_nop 1
	v_permlane32_swap_b32_e32 v229, v230
	s_and_saveexec_b64 s[10:11], s[6:7]
	v_lshl_add_u64 v[156:157], v[144:145], 2, s[18:19]
	v_add_f32_e32 v229, v229, v230
	global_atomic_add_f32 v[156:157], v229, off
	s_or_b64 exec, exec, s[10:11]
	v_add_u32_e32 v144, 0x30, v154
	v_mov_b32_e32 v145, v155
	v_lshlrev_b64 v[148:149], 11, v[144:145]
	v_lshl_add_u64 v[148:149], v[148:149], 0, v[146:147]
	v_lshl_add_u64 v[150:151], v[148:149], 2, s[28:29]
	v_lshl_add_u64 v[152:153], v[148:149], 1, s[42:43]
	global_load_dwordx2 v[208:209], v[152:153], off
	global_load_dwordx4 v[192:195], v[150:151], off
	global_load_dwordx2 v[210:211], v[152:153], off offset:32
	global_load_dwordx4 v[196:199], v[150:151], off offset:64
	global_load_dwordx2 v[212:213], v[152:153], off offset:256
	global_load_dwordx4 v[200:203], v[150:151], off offset:512
	global_load_dwordx2 v[214:215], v[152:153], off offset:288
	global_load_dwordx4 v[204:207], v[150:151], off offset:576
	s_waitcnt vmcnt(17)
	v_fmamk_f32 v218, v218, 0x3a000000, v164
	v_mul_f32_e32 v235, 0x4b800000, v218
	v_cmp_gt_f32_e32 vcc, s61, v218
	s_nop 1
	v_cndmask_b32_e32 v218, v218, v235, vcc
	v_rsq_f32_e32 v218, v218
	s_nop 0
	v_mul_f32_e32 v235, 0x45800000, v218
	v_cndmask_b32_e32 v234, v218, v235, vcc
	v_add_u32_e32 v144, 0x20, v154
	v_mov_b32_e32 v145, v155
	v_lshlrev_b64 v[148:149], 11, v[144:145]
	v_lshl_add_u64 v[148:149], v[148:149], 0, v[146:147]
	v_lshl_add_u64 v[150:151], v[148:149], 2, s[28:29]
	v_lshl_add_u64 v[156:157], v[148:149], 1, s[24:25]
	v_pk_mul_f32 v[92:93], v[92:93], v[234:235] op_sel_hi:[1,0]
	v_pk_mul_f32 v[94:95], v[94:95], v[234:235] op_sel_hi:[1,0]
	v_mul_f32_e32 v92, 0xbfb8aa3b, v92
	v_mul_f32_e32 v93, 0xbfb8aa3b, v93
	v_mul_f32_e32 v94, 0xbfb8aa3b, v94
	v_mul_f32_e32 v95, 0xbfb8aa3b, v95
	v_exp_f32_e32 v92, v92
	v_exp_f32_e32 v93, v93
	v_exp_f32_e32 v94, v94
	v_exp_f32_e32 v95, v95
	v_pk_add_f32 v[92:93], v[92:93], 1.0 op_sel_hi:[1,0]
	v_pk_add_f32 v[94:95], v[94:95], 1.0 op_sel_hi:[1,0]
	v_div_scale_f32 v224, s[10:11], v92, v92, 1.0
	v_rcp_f32_e32 v225, v224
	s_nop 0
	v_fma_f32 v226, -v224, v225, 1.0
	v_fmac_f32_e32 v225, v226, v225
	v_div_scale_f32 v226, vcc, 1.0, v92, 1.0
	v_mul_f32_e32 v227, v226, v225
	v_fma_f32 v228, -v224, v227, v226
	v_fmac_f32_e32 v227, v228, v225
	v_fma_f32 v224, -v224, v227, v226
	v_div_fmas_f32 v224, v224, v225, v227
	v_div_fixup_f32 v92, v224, v92, 1.0
	v_div_scale_f32 v224, s[10:11], v93, v93, 1.0
	v_rcp_f32_e32 v225, v224
	s_nop 0
	v_fma_f32 v226, -v224, v225, 1.0
	v_fmac_f32_e32 v225, v226, v225
	v_div_scale_f32 v226, vcc, 1.0, v93, 1.0
	v_mul_f32_e32 v227, v226, v225
	v_fma_f32 v228, -v224, v227, v226
	v_fmac_f32_e32 v227, v228, v225
	v_fma_f32 v224, -v224, v227, v226
	v_div_fmas_f32 v224, v224, v225, v227
	v_div_fixup_f32 v93, v224, v93, 1.0
	v_div_scale_f32 v224, s[10:11], v94, v94, 1.0
	v_rcp_f32_e32 v225, v224
	s_nop 0
	v_fma_f32 v226, -v224, v225, 1.0
	v_fmac_f32_e32 v225, v226, v225
	v_div_scale_f32 v226, vcc, 1.0, v94, 1.0
	v_mul_f32_e32 v227, v226, v225
	v_fma_f32 v228, -v224, v227, v226
	v_fmac_f32_e32 v227, v228, v225
	v_fma_f32 v224, -v224, v227, v226
	v_div_fmas_f32 v224, v224, v225, v227
	v_div_fixup_f32 v94, v224, v94, 1.0
	v_div_scale_f32 v224, s[10:11], v95, v95, 1.0
	v_rcp_f32_e32 v225, v224
	s_nop 0
	v_fma_f32 v226, -v224, v225, 1.0
	v_fmac_f32_e32 v225, v226, v225
	v_div_scale_f32 v226, vcc, 1.0, v95, 1.0
	v_mul_f32_e32 v227, v226, v225
	v_fma_f32 v228, -v224, v227, v226
	v_fmac_f32_e32 v227, v228, v225
	v_fma_f32 v224, -v224, v227, v226
	v_div_fmas_f32 v224, v224, v225, v227
	v_div_fixup_f32 v95, v224, v95, 1.0
	v_lshlrev_b32_e32 v236, 16, v184
	v_and_b32_e32 v237, 0xffff0000, v184
	v_lshlrev_b32_e32 v238, 16, v185
	v_and_b32_e32 v239, 0xffff0000, v185
	v_pk_fma_f32 v[92:93], v[92:93], v[236:237], v[168:169]
	v_pk_fma_f32 v[94:95], v[94:95], v[238:239], v[170:171]
	v_cvt_pk_bf16_f32 v159, v94, v95
	v_cvt_pk_bf16_f32 v158, v92, v93
	global_store_dwordx4 v[150:151], v[92:95], off
	global_store_dwordx2 v[156:157], v[158:159], off
	s_nop 0
	v_mul_f32_e32 v93, v93, v93
	v_mul_f32_e32 v95, v95, v95
	v_fmac_f32_e32 v93, v92, v92
	v_fmac_f32_e32 v95, v94, v94
	v_add_f32_e32 v229, v93, v95
	v_pk_mul_f32 v[88:89], v[88:89], v[234:235] op_sel_hi:[1,0]
	v_pk_mul_f32 v[90:91], v[90:91], v[234:235] op_sel_hi:[1,0]
	v_mul_f32_e32 v88, 0xbfb8aa3b, v88
	v_mul_f32_e32 v89, 0xbfb8aa3b, v89
	v_mul_f32_e32 v90, 0xbfb8aa3b, v90
	v_mul_f32_e32 v91, 0xbfb8aa3b, v91
	v_exp_f32_e32 v88, v88
	v_exp_f32_e32 v89, v89
	v_exp_f32_e32 v90, v90
	v_exp_f32_e32 v91, v91
	v_pk_add_f32 v[88:89], v[88:89], 1.0 op_sel_hi:[1,0]
	v_pk_add_f32 v[90:91], v[90:91], 1.0 op_sel_hi:[1,0]
	v_div_scale_f32 v224, s[10:11], v88, v88, 1.0
	v_rcp_f32_e32 v225, v224
	s_nop 0
	v_fma_f32 v226, -v224, v225, 1.0
	v_fmac_f32_e32 v225, v226, v225
	v_div_scale_f32 v226, vcc, 1.0, v88, 1.0
	v_mul_f32_e32 v227, v226, v225
	v_fma_f32 v228, -v224, v227, v226
	v_fmac_f32_e32 v227, v228, v225
	v_fma_f32 v224, -v224, v227, v226
	v_div_fmas_f32 v224, v224, v225, v227
	v_div_fixup_f32 v88, v224, v88, 1.0
	v_div_scale_f32 v224, s[10:11], v89, v89, 1.0
	v_rcp_f32_e32 v225, v224
	s_nop 0
	v_fma_f32 v226, -v224, v225, 1.0
	v_fmac_f32_e32 v225, v226, v225
	v_div_scale_f32 v226, vcc, 1.0, v89, 1.0
	v_mul_f32_e32 v227, v226, v225
	v_fma_f32 v228, -v224, v227, v226
	v_fmac_f32_e32 v227, v228, v225
	v_fma_f32 v224, -v224, v227, v226
	v_div_fmas_f32 v224, v224, v225, v227
	v_div_fixup_f32 v89, v224, v89, 1.0
	v_div_scale_f32 v224, s[10:11], v90, v90, 1.0
	v_rcp_f32_e32 v225, v224
	s_nop 0
	v_fma_f32 v226, -v224, v225, 1.0
	v_fmac_f32_e32 v225, v226, v225
	v_div_scale_f32 v226, vcc, 1.0, v90, 1.0
	v_mul_f32_e32 v227, v226, v225
	v_fma_f32 v228, -v224, v227, v226
	v_fmac_f32_e32 v227, v228, v225
	v_fma_f32 v224, -v224, v227, v226
	v_div_fmas_f32 v224, v224, v225, v227
	v_div_fixup_f32 v90, v224, v90, 1.0
	v_div_scale_f32 v224, s[10:11], v91, v91, 1.0
	v_rcp_f32_e32 v225, v224
	s_nop 0
	v_fma_f32 v226, -v224, v225, 1.0
	v_fmac_f32_e32 v225, v226, v225
	v_div_scale_f32 v226, vcc, 1.0, v91, 1.0
	v_mul_f32_e32 v227, v226, v225
	v_fma_f32 v228, -v224, v227, v226
	v_fmac_f32_e32 v227, v228, v225
	v_fma_f32 v224, -v224, v227, v226
	v_div_fmas_f32 v224, v224, v225, v227
	v_div_fixup_f32 v91, v224, v91, 1.0
	v_lshlrev_b32_e32 v236, 16, v186
	v_and_b32_e32 v237, 0xffff0000, v186
	v_lshlrev_b32_e32 v238, 16, v187
	v_and_b32_e32 v239, 0xffff0000, v187
	v_pk_fma_f32 v[88:89], v[88:89], v[236:237], v[172:173]
	v_pk_fma_f32 v[90:91], v[90:91], v[238:239], v[174:175]
	v_cvt_pk_bf16_f32 v159, v90, v91
	v_cvt_pk_bf16_f32 v158, v88, v89
	global_store_dwordx4 v[150:151], v[88:91], off offset:64
	global_store_dwordx2 v[156:157], v[158:159], off offset:32
	s_nop 0
	v_mul_f32_e32 v89, v89, v89
	v_mul_f32_e32 v91, v91, v91
	v_fmac_f32_e32 v89, v88, v88
	v_fmac_f32_e32 v91, v90, v90
	v_add_f32_e32 v88, v89, v91
	v_add_f32_e32 v229, v229, v88
	v_pk_mul_f32 v[84:85], v[84:85], v[234:235] op_sel_hi:[1,0]
	v_pk_mul_f32 v[86:87], v[86:87], v[234:235] op_sel_hi:[1,0]
	v_mul_f32_e32 v84, 0xbfb8aa3b, v84
	v_mul_f32_e32 v85, 0xbfb8aa3b, v85
	v_mul_f32_e32 v86, 0xbfb8aa3b, v86
	v_mul_f32_e32 v87, 0xbfb8aa3b, v87
	v_exp_f32_e32 v84, v84
	v_exp_f32_e32 v85, v85
	v_exp_f32_e32 v86, v86
	v_exp_f32_e32 v87, v87
	v_pk_add_f32 v[84:85], v[84:85], 1.0 op_sel_hi:[1,0]
	v_pk_add_f32 v[86:87], v[86:87], 1.0 op_sel_hi:[1,0]
	v_div_scale_f32 v224, s[10:11], v84, v84, 1.0
	v_rcp_f32_e32 v225, v224
	s_nop 0
	v_fma_f32 v226, -v224, v225, 1.0
	v_fmac_f32_e32 v225, v226, v225
	v_div_scale_f32 v226, vcc, 1.0, v84, 1.0
	v_mul_f32_e32 v227, v226, v225
	v_fma_f32 v228, -v224, v227, v226
	v_fmac_f32_e32 v227, v228, v225
	v_fma_f32 v224, -v224, v227, v226
	v_div_fmas_f32 v224, v224, v225, v227
	v_div_fixup_f32 v84, v224, v84, 1.0
	v_div_scale_f32 v224, s[10:11], v85, v85, 1.0
	v_rcp_f32_e32 v225, v224
	s_nop 0
	v_fma_f32 v226, -v224, v225, 1.0
	v_fmac_f32_e32 v225, v226, v225
	v_div_scale_f32 v226, vcc, 1.0, v85, 1.0
	v_mul_f32_e32 v227, v226, v225
	v_fma_f32 v228, -v224, v227, v226
	v_fmac_f32_e32 v227, v228, v225
	v_fma_f32 v224, -v224, v227, v226
	v_div_fmas_f32 v224, v224, v225, v227
	v_div_fixup_f32 v85, v224, v85, 1.0
	v_div_scale_f32 v224, s[10:11], v86, v86, 1.0
	v_rcp_f32_e32 v225, v224
	s_nop 0
	v_fma_f32 v226, -v224, v225, 1.0
	v_fmac_f32_e32 v225, v226, v225
	v_div_scale_f32 v226, vcc, 1.0, v86, 1.0
	v_mul_f32_e32 v227, v226, v225
	v_fma_f32 v228, -v224, v227, v226
	v_fmac_f32_e32 v227, v228, v225
	v_fma_f32 v224, -v224, v227, v226
	v_div_fmas_f32 v224, v224, v225, v227
	v_div_fixup_f32 v86, v224, v86, 1.0
	v_div_scale_f32 v224, s[10:11], v87, v87, 1.0
	v_rcp_f32_e32 v225, v224
	s_nop 0
	v_fma_f32 v226, -v224, v225, 1.0
	v_fmac_f32_e32 v225, v226, v225
	v_div_scale_f32 v226, vcc, 1.0, v87, 1.0
	v_mul_f32_e32 v227, v226, v225
	v_fma_f32 v228, -v224, v227, v226
	v_fmac_f32_e32 v227, v228, v225
	v_fma_f32 v224, -v224, v227, v226
	v_div_fmas_f32 v224, v224, v225, v227
	v_div_fixup_f32 v87, v224, v87, 1.0
	v_lshlrev_b32_e32 v236, 16, v188
	v_and_b32_e32 v237, 0xffff0000, v188
	v_lshlrev_b32_e32 v238, 16, v189
	v_and_b32_e32 v239, 0xffff0000, v189
	v_pk_fma_f32 v[84:85], v[84:85], v[236:237], v[176:177]
	v_pk_fma_f32 v[86:87], v[86:87], v[238:239], v[178:179]
	v_cvt_pk_bf16_f32 v159, v86, v87
	v_cvt_pk_bf16_f32 v158, v84, v85
	global_store_dwordx4 v[150:151], v[84:87], off offset:512
	global_store_dwordx2 v[156:157], v[158:159], off offset:256
	s_nop 0
	v_mul_f32_e32 v85, v85, v85
	v_mul_f32_e32 v87, v87, v87
	v_fmac_f32_e32 v85, v84, v84
	v_fmac_f32_e32 v87, v86, v86
	v_add_f32_e32 v84, v85, v87
	v_add_f32_e32 v229, v229, v84
	v_pk_mul_f32 v[80:81], v[80:81], v[234:235] op_sel_hi:[1,0]
	v_pk_mul_f32 v[82:83], v[82:83], v[234:235] op_sel_hi:[1,0]
	v_mul_f32_e32 v80, 0xbfb8aa3b, v80
	v_mul_f32_e32 v81, 0xbfb8aa3b, v81
	v_mul_f32_e32 v82, 0xbfb8aa3b, v82
	v_mul_f32_e32 v83, 0xbfb8aa3b, v83
	v_exp_f32_e32 v80, v80
	v_exp_f32_e32 v81, v81
	v_exp_f32_e32 v82, v82
	v_exp_f32_e32 v83, v83
	v_pk_add_f32 v[80:81], v[80:81], 1.0 op_sel_hi:[1,0]
	v_pk_add_f32 v[82:83], v[82:83], 1.0 op_sel_hi:[1,0]
	v_div_scale_f32 v224, s[10:11], v80, v80, 1.0
	v_rcp_f32_e32 v225, v224
	s_nop 0
	v_fma_f32 v226, -v224, v225, 1.0
	v_fmac_f32_e32 v225, v226, v225
	v_div_scale_f32 v226, vcc, 1.0, v80, 1.0
	v_mul_f32_e32 v227, v226, v225
	v_fma_f32 v228, -v224, v227, v226
	v_fmac_f32_e32 v227, v228, v225
	v_fma_f32 v224, -v224, v227, v226
	v_div_fmas_f32 v224, v224, v225, v227
	v_div_fixup_f32 v80, v224, v80, 1.0
	v_div_scale_f32 v224, s[10:11], v81, v81, 1.0
	v_rcp_f32_e32 v225, v224
	s_nop 0
	v_fma_f32 v226, -v224, v225, 1.0
	v_fmac_f32_e32 v225, v226, v225
	v_div_scale_f32 v226, vcc, 1.0, v81, 1.0
	v_mul_f32_e32 v227, v226, v225
	v_fma_f32 v228, -v224, v227, v226
	v_fmac_f32_e32 v227, v228, v225
	v_fma_f32 v224, -v224, v227, v226
	v_div_fmas_f32 v224, v224, v225, v227
	v_div_fixup_f32 v81, v224, v81, 1.0
	v_div_scale_f32 v224, s[10:11], v82, v82, 1.0
	v_rcp_f32_e32 v225, v224
	s_nop 0
	v_fma_f32 v226, -v224, v225, 1.0
	v_fmac_f32_e32 v225, v226, v225
	v_div_scale_f32 v226, vcc, 1.0, v82, 1.0
	v_mul_f32_e32 v227, v226, v225
	v_fma_f32 v228, -v224, v227, v226
	v_fmac_f32_e32 v227, v228, v225
	v_fma_f32 v224, -v224, v227, v226
	v_div_fmas_f32 v224, v224, v225, v227
	v_div_fixup_f32 v82, v224, v82, 1.0
	v_div_scale_f32 v224, s[10:11], v83, v83, 1.0
	v_rcp_f32_e32 v225, v224
	s_nop 0
	v_fma_f32 v226, -v224, v225, 1.0
	v_fmac_f32_e32 v225, v226, v225
	v_div_scale_f32 v226, vcc, 1.0, v83, 1.0
	v_mul_f32_e32 v227, v226, v225
	v_fma_f32 v228, -v224, v227, v226
	v_fmac_f32_e32 v227, v228, v225
	v_fma_f32 v224, -v224, v227, v226
	v_div_fmas_f32 v224, v224, v225, v227
	v_div_fixup_f32 v83, v224, v83, 1.0
	v_lshlrev_b32_e32 v236, 16, v190
	v_and_b32_e32 v237, 0xffff0000, v190
	v_lshlrev_b32_e32 v238, 16, v191
	v_and_b32_e32 v239, 0xffff0000, v191
	v_pk_fma_f32 v[80:81], v[80:81], v[236:237], v[180:181]
	v_pk_fma_f32 v[82:83], v[82:83], v[238:239], v[182:183]
	v_cvt_pk_bf16_f32 v159, v82, v83
	v_cvt_pk_bf16_f32 v158, v80, v81
	global_store_dwordx4 v[150:151], v[80:83], off offset:576
	global_store_dwordx2 v[156:157], v[158:159], off offset:288
	s_nop 0
	v_mul_f32_e32 v81, v81, v81
	v_mul_f32_e32 v83, v83, v83
	v_fmac_f32_e32 v81, v80, v80
	v_fmac_f32_e32 v83, v82, v82
	v_add_f32_e32 v80, v81, v83
	v_add_f32_e32 v229, v229, v80
	v_mov_b32_e32 v230, v229
	s_nop 1
	v_permlane16_swap_b32_e32 v229, v230
	v_add_f32_e32 v229, v229, v230
	v_mov_b32_e32 v230, v229
	s_nop 1
	v_permlane32_swap_b32_e32 v229, v230
	s_and_saveexec_b64 s[10:11], s[6:7]
	v_lshl_add_u64 v[156:157], v[144:145], 2, s[18:19]
	v_add_f32_e32 v229, v229, v230
	global_atomic_add_f32 v[156:157], v229, off
	s_or_b64 exec, exec, s[10:11]
	v_add_u32_e32 v144, 0x80, v154
	v_mov_b32_e32 v145, v155
	v_lshlrev_b64 v[148:149], 11, v[144:145]
	v_lshl_add_u64 v[148:149], v[148:149], 0, v[146:147]
	v_lshl_add_u64 v[150:151], v[148:149], 2, s[28:29]
	v_lshl_add_u64 v[152:153], v[148:149], 1, s[42:43]
	global_load_dwordx2 v[184:185], v[152:153], off
	global_load_dwordx4 v[168:171], v[150:151], off
	global_load_dwordx2 v[186:187], v[152:153], off offset:32
	global_load_dwordx4 v[172:175], v[150:151], off offset:64
	global_load_dwordx2 v[188:189], v[152:153], off offset:256
	global_load_dwordx4 v[176:179], v[150:151], off offset:512
	global_load_dwordx2 v[190:191], v[152:153], off offset:288
	global_load_dwordx4 v[180:183], v[150:151], off offset:576
	s_waitcnt vmcnt(17)
	v_fmamk_f32 v219, v219, 0x3a000000, v164
	v_mul_f32_e32 v235, 0x4b800000, v219
	v_cmp_gt_f32_e32 vcc, s61, v219
	s_nop 1
	v_cndmask_b32_e32 v219, v219, v235, vcc
	v_rsq_f32_e32 v219, v219
	s_nop 0
	v_mul_f32_e32 v235, 0x45800000, v219
	v_cndmask_b32_e32 v234, v219, v235, vcc
	v_add_u32_e32 v144, 0x30, v154
	v_mov_b32_e32 v145, v155
	v_lshlrev_b64 v[148:149], 11, v[144:145]
	v_lshl_add_u64 v[148:149], v[148:149], 0, v[146:147]
	v_lshl_add_u64 v[150:151], v[148:149], 2, s[28:29]
	v_lshl_add_u64 v[156:157], v[148:149], 1, s[24:25]
	v_pk_mul_f32 v[76:77], v[76:77], v[234:235] op_sel_hi:[1,0]
	v_pk_mul_f32 v[78:79], v[78:79], v[234:235] op_sel_hi:[1,0]
	v_mul_f32_e32 v76, 0xbfb8aa3b, v76
	v_mul_f32_e32 v77, 0xbfb8aa3b, v77
	v_mul_f32_e32 v78, 0xbfb8aa3b, v78
	v_mul_f32_e32 v79, 0xbfb8aa3b, v79
	v_exp_f32_e32 v76, v76
	v_exp_f32_e32 v77, v77
	v_exp_f32_e32 v78, v78
	v_exp_f32_e32 v79, v79
	v_pk_add_f32 v[76:77], v[76:77], 1.0 op_sel_hi:[1,0]
	v_pk_add_f32 v[78:79], v[78:79], 1.0 op_sel_hi:[1,0]
	v_div_scale_f32 v224, s[10:11], v76, v76, 1.0
	v_rcp_f32_e32 v225, v224
	s_nop 0
	v_fma_f32 v226, -v224, v225, 1.0
	v_fmac_f32_e32 v225, v226, v225
	v_div_scale_f32 v226, vcc, 1.0, v76, 1.0
	v_mul_f32_e32 v227, v226, v225
	v_fma_f32 v228, -v224, v227, v226
	v_fmac_f32_e32 v227, v228, v225
	v_fma_f32 v224, -v224, v227, v226
	v_div_fmas_f32 v224, v224, v225, v227
	v_div_fixup_f32 v76, v224, v76, 1.0
	v_div_scale_f32 v224, s[10:11], v77, v77, 1.0
	v_rcp_f32_e32 v225, v224
	s_nop 0
	v_fma_f32 v226, -v224, v225, 1.0
	v_fmac_f32_e32 v225, v226, v225
	v_div_scale_f32 v226, vcc, 1.0, v77, 1.0
	v_mul_f32_e32 v227, v226, v225
	v_fma_f32 v228, -v224, v227, v226
	v_fmac_f32_e32 v227, v228, v225
	v_fma_f32 v224, -v224, v227, v226
	v_div_fmas_f32 v224, v224, v225, v227
	v_div_fixup_f32 v77, v224, v77, 1.0
	v_div_scale_f32 v224, s[10:11], v78, v78, 1.0
	v_rcp_f32_e32 v225, v224
	s_nop 0
	v_fma_f32 v226, -v224, v225, 1.0
	v_fmac_f32_e32 v225, v226, v225
	v_div_scale_f32 v226, vcc, 1.0, v78, 1.0
	v_mul_f32_e32 v227, v226, v225
	v_fma_f32 v228, -v224, v227, v226
	v_fmac_f32_e32 v227, v228, v225
	v_fma_f32 v224, -v224, v227, v226
	v_div_fmas_f32 v224, v224, v225, v227
	v_div_fixup_f32 v78, v224, v78, 1.0
	v_div_scale_f32 v224, s[10:11], v79, v79, 1.0
	v_rcp_f32_e32 v225, v224
	s_nop 0
	v_fma_f32 v226, -v224, v225, 1.0
	v_fmac_f32_e32 v225, v226, v225
	v_div_scale_f32 v226, vcc, 1.0, v79, 1.0
	v_mul_f32_e32 v227, v226, v225
	v_fma_f32 v228, -v224, v227, v226
	v_fmac_f32_e32 v227, v228, v225
	v_fma_f32 v224, -v224, v227, v226
	v_div_fmas_f32 v224, v224, v225, v227
	v_div_fixup_f32 v79, v224, v79, 1.0
	v_lshlrev_b32_e32 v236, 16, v208
	v_and_b32_e32 v237, 0xffff0000, v208
	v_lshlrev_b32_e32 v238, 16, v209
	v_and_b32_e32 v239, 0xffff0000, v209
	v_pk_fma_f32 v[76:77], v[76:77], v[236:237], v[192:193]
	v_pk_fma_f32 v[78:79], v[78:79], v[238:239], v[194:195]
	v_cvt_pk_bf16_f32 v159, v78, v79
	v_cvt_pk_bf16_f32 v158, v76, v77
	global_store_dwordx4 v[150:151], v[76:79], off
	global_store_dwordx2 v[156:157], v[158:159], off
	s_nop 0
	v_mul_f32_e32 v77, v77, v77
	v_mul_f32_e32 v79, v79, v79
	v_fmac_f32_e32 v77, v76, v76
	v_fmac_f32_e32 v79, v78, v78
	v_add_f32_e32 v229, v77, v79
	v_pk_mul_f32 v[72:73], v[72:73], v[234:235] op_sel_hi:[1,0]
	v_pk_mul_f32 v[74:75], v[74:75], v[234:235] op_sel_hi:[1,0]
	v_mul_f32_e32 v72, 0xbfb8aa3b, v72
	v_mul_f32_e32 v73, 0xbfb8aa3b, v73
	v_mul_f32_e32 v74, 0xbfb8aa3b, v74
	v_mul_f32_e32 v75, 0xbfb8aa3b, v75
	v_exp_f32_e32 v72, v72
	v_exp_f32_e32 v73, v73
	v_exp_f32_e32 v74, v74
	v_exp_f32_e32 v75, v75
	v_pk_add_f32 v[72:73], v[72:73], 1.0 op_sel_hi:[1,0]
	v_pk_add_f32 v[74:75], v[74:75], 1.0 op_sel_hi:[1,0]
	v_div_scale_f32 v224, s[10:11], v72, v72, 1.0
	v_rcp_f32_e32 v225, v224
	s_nop 0
	v_fma_f32 v226, -v224, v225, 1.0
	v_fmac_f32_e32 v225, v226, v225
	v_div_scale_f32 v226, vcc, 1.0, v72, 1.0
	v_mul_f32_e32 v227, v226, v225
	v_fma_f32 v228, -v224, v227, v226
	v_fmac_f32_e32 v227, v228, v225
	v_fma_f32 v224, -v224, v227, v226
	v_div_fmas_f32 v224, v224, v225, v227
	v_div_fixup_f32 v72, v224, v72, 1.0
	v_div_scale_f32 v224, s[10:11], v73, v73, 1.0
	v_rcp_f32_e32 v225, v224
	s_nop 0
	v_fma_f32 v226, -v224, v225, 1.0
	v_fmac_f32_e32 v225, v226, v225
	v_div_scale_f32 v226, vcc, 1.0, v73, 1.0
	v_mul_f32_e32 v227, v226, v225
	v_fma_f32 v228, -v224, v227, v226
	v_fmac_f32_e32 v227, v228, v225
	v_fma_f32 v224, -v224, v227, v226
	v_div_fmas_f32 v224, v224, v225, v227
	v_div_fixup_f32 v73, v224, v73, 1.0
	v_div_scale_f32 v224, s[10:11], v74, v74, 1.0
	v_rcp_f32_e32 v225, v224
	s_nop 0
	v_fma_f32 v226, -v224, v225, 1.0
	v_fmac_f32_e32 v225, v226, v225
	v_div_scale_f32 v226, vcc, 1.0, v74, 1.0
	v_mul_f32_e32 v227, v226, v225
	v_fma_f32 v228, -v224, v227, v226
	v_fmac_f32_e32 v227, v228, v225
	v_fma_f32 v224, -v224, v227, v226
	v_div_fmas_f32 v224, v224, v225, v227
	v_div_fixup_f32 v74, v224, v74, 1.0
	v_div_scale_f32 v224, s[10:11], v75, v75, 1.0
	v_rcp_f32_e32 v225, v224
	s_nop 0
	v_fma_f32 v226, -v224, v225, 1.0
	v_fmac_f32_e32 v225, v226, v225
	v_div_scale_f32 v226, vcc, 1.0, v75, 1.0
	v_mul_f32_e32 v227, v226, v225
	v_fma_f32 v228, -v224, v227, v226
	v_fmac_f32_e32 v227, v228, v225
	v_fma_f32 v224, -v224, v227, v226
	v_div_fmas_f32 v224, v224, v225, v227
	v_div_fixup_f32 v75, v224, v75, 1.0
	v_lshlrev_b32_e32 v236, 16, v210
	v_and_b32_e32 v237, 0xffff0000, v210
	v_lshlrev_b32_e32 v238, 16, v211
	v_and_b32_e32 v239, 0xffff0000, v211
	v_pk_fma_f32 v[72:73], v[72:73], v[236:237], v[196:197]
	v_pk_fma_f32 v[74:75], v[74:75], v[238:239], v[198:199]
	v_cvt_pk_bf16_f32 v159, v74, v75
	v_cvt_pk_bf16_f32 v158, v72, v73
	global_store_dwordx4 v[150:151], v[72:75], off offset:64
	global_store_dwordx2 v[156:157], v[158:159], off offset:32
	s_nop 0
	v_mul_f32_e32 v73, v73, v73
	v_mul_f32_e32 v75, v75, v75
	v_fmac_f32_e32 v73, v72, v72
	v_fmac_f32_e32 v75, v74, v74
	v_add_f32_e32 v72, v73, v75
	v_add_f32_e32 v229, v229, v72
	v_pk_mul_f32 v[68:69], v[68:69], v[234:235] op_sel_hi:[1,0]
	v_pk_mul_f32 v[70:71], v[70:71], v[234:235] op_sel_hi:[1,0]
	v_mul_f32_e32 v68, 0xbfb8aa3b, v68
	v_mul_f32_e32 v69, 0xbfb8aa3b, v69
	v_mul_f32_e32 v70, 0xbfb8aa3b, v70
	v_mul_f32_e32 v71, 0xbfb8aa3b, v71
	v_exp_f32_e32 v68, v68
	v_exp_f32_e32 v69, v69
	v_exp_f32_e32 v70, v70
	v_exp_f32_e32 v71, v71
	v_pk_add_f32 v[68:69], v[68:69], 1.0 op_sel_hi:[1,0]
	v_pk_add_f32 v[70:71], v[70:71], 1.0 op_sel_hi:[1,0]
	v_div_scale_f32 v224, s[10:11], v68, v68, 1.0
	v_rcp_f32_e32 v225, v224
	s_nop 0
	v_fma_f32 v226, -v224, v225, 1.0
	v_fmac_f32_e32 v225, v226, v225
	v_div_scale_f32 v226, vcc, 1.0, v68, 1.0
	v_mul_f32_e32 v227, v226, v225
	v_fma_f32 v228, -v224, v227, v226
	v_fmac_f32_e32 v227, v228, v225
	v_fma_f32 v224, -v224, v227, v226
	v_div_fmas_f32 v224, v224, v225, v227
	v_div_fixup_f32 v68, v224, v68, 1.0
	v_div_scale_f32 v224, s[10:11], v69, v69, 1.0
	v_rcp_f32_e32 v225, v224
	s_nop 0
	v_fma_f32 v226, -v224, v225, 1.0
	v_fmac_f32_e32 v225, v226, v225
	v_div_scale_f32 v226, vcc, 1.0, v69, 1.0
	v_mul_f32_e32 v227, v226, v225
	v_fma_f32 v228, -v224, v227, v226
	v_fmac_f32_e32 v227, v228, v225
	v_fma_f32 v224, -v224, v227, v226
	v_div_fmas_f32 v224, v224, v225, v227
	v_div_fixup_f32 v69, v224, v69, 1.0
	v_div_scale_f32 v224, s[10:11], v70, v70, 1.0
	v_rcp_f32_e32 v225, v224
	s_nop 0
	v_fma_f32 v226, -v224, v225, 1.0
	v_fmac_f32_e32 v225, v226, v225
	v_div_scale_f32 v226, vcc, 1.0, v70, 1.0
	v_mul_f32_e32 v227, v226, v225
	v_fma_f32 v228, -v224, v227, v226
	v_fmac_f32_e32 v227, v228, v225
	v_fma_f32 v224, -v224, v227, v226
	v_div_fmas_f32 v224, v224, v225, v227
	v_div_fixup_f32 v70, v224, v70, 1.0
	v_div_scale_f32 v224, s[10:11], v71, v71, 1.0
	v_rcp_f32_e32 v225, v224
	s_nop 0
	v_fma_f32 v226, -v224, v225, 1.0
	v_fmac_f32_e32 v225, v226, v225
	v_div_scale_f32 v226, vcc, 1.0, v71, 1.0
	v_mul_f32_e32 v227, v226, v225
	v_fma_f32 v228, -v224, v227, v226
	v_fmac_f32_e32 v227, v228, v225
	v_fma_f32 v224, -v224, v227, v226
	v_div_fmas_f32 v224, v224, v225, v227
	v_div_fixup_f32 v71, v224, v71, 1.0
	v_lshlrev_b32_e32 v236, 16, v212
	v_and_b32_e32 v237, 0xffff0000, v212
	v_lshlrev_b32_e32 v238, 16, v213
	v_and_b32_e32 v239, 0xffff0000, v213
	v_pk_fma_f32 v[68:69], v[68:69], v[236:237], v[200:201]
	v_pk_fma_f32 v[70:71], v[70:71], v[238:239], v[202:203]
	v_cvt_pk_bf16_f32 v159, v70, v71
	v_cvt_pk_bf16_f32 v158, v68, v69
	global_store_dwordx4 v[150:151], v[68:71], off offset:512
	global_store_dwordx2 v[156:157], v[158:159], off offset:256
	s_nop 0
	v_mul_f32_e32 v69, v69, v69
	v_mul_f32_e32 v71, v71, v71
	v_fmac_f32_e32 v69, v68, v68
	v_fmac_f32_e32 v71, v70, v70
	v_add_f32_e32 v68, v69, v71
	v_add_f32_e32 v229, v229, v68
	v_pk_mul_f32 v[64:65], v[64:65], v[234:235] op_sel_hi:[1,0]
	v_pk_mul_f32 v[66:67], v[66:67], v[234:235] op_sel_hi:[1,0]
	v_mul_f32_e32 v64, 0xbfb8aa3b, v64
	v_mul_f32_e32 v65, 0xbfb8aa3b, v65
	v_mul_f32_e32 v66, 0xbfb8aa3b, v66
	v_mul_f32_e32 v67, 0xbfb8aa3b, v67
	v_exp_f32_e32 v64, v64
	v_exp_f32_e32 v65, v65
	v_exp_f32_e32 v66, v66
	v_exp_f32_e32 v67, v67
	v_pk_add_f32 v[64:65], v[64:65], 1.0 op_sel_hi:[1,0]
	v_pk_add_f32 v[66:67], v[66:67], 1.0 op_sel_hi:[1,0]
	v_div_scale_f32 v224, s[10:11], v64, v64, 1.0
	v_rcp_f32_e32 v225, v224
	s_nop 0
	v_fma_f32 v226, -v224, v225, 1.0
	v_fmac_f32_e32 v225, v226, v225
	v_div_scale_f32 v226, vcc, 1.0, v64, 1.0
	v_mul_f32_e32 v227, v226, v225
	v_fma_f32 v228, -v224, v227, v226
	v_fmac_f32_e32 v227, v228, v225
	v_fma_f32 v224, -v224, v227, v226
	v_div_fmas_f32 v224, v224, v225, v227
	v_div_fixup_f32 v64, v224, v64, 1.0
	v_div_scale_f32 v224, s[10:11], v65, v65, 1.0
	v_rcp_f32_e32 v225, v224
	s_nop 0
	v_fma_f32 v226, -v224, v225, 1.0
	v_fmac_f32_e32 v225, v226, v225
	v_div_scale_f32 v226, vcc, 1.0, v65, 1.0
	v_mul_f32_e32 v227, v226, v225
	v_fma_f32 v228, -v224, v227, v226
	v_fmac_f32_e32 v227, v228, v225
	v_fma_f32 v224, -v224, v227, v226
	v_div_fmas_f32 v224, v224, v225, v227
	v_div_fixup_f32 v65, v224, v65, 1.0
	v_div_scale_f32 v224, s[10:11], v66, v66, 1.0
	v_rcp_f32_e32 v225, v224
	s_nop 0
	v_fma_f32 v226, -v224, v225, 1.0
	v_fmac_f32_e32 v225, v226, v225
	v_div_scale_f32 v226, vcc, 1.0, v66, 1.0
	v_mul_f32_e32 v227, v226, v225
	v_fma_f32 v228, -v224, v227, v226
	v_fmac_f32_e32 v227, v228, v225
	v_fma_f32 v224, -v224, v227, v226
	v_div_fmas_f32 v224, v224, v225, v227
	v_div_fixup_f32 v66, v224, v66, 1.0
	v_div_scale_f32 v224, s[10:11], v67, v67, 1.0
	v_rcp_f32_e32 v225, v224
	s_nop 0
	v_fma_f32 v226, -v224, v225, 1.0
	v_fmac_f32_e32 v225, v226, v225
	v_div_scale_f32 v226, vcc, 1.0, v67, 1.0
	v_mul_f32_e32 v227, v226, v225
	v_fma_f32 v228, -v224, v227, v226
	v_fmac_f32_e32 v227, v228, v225
	v_fma_f32 v224, -v224, v227, v226
	v_div_fmas_f32 v224, v224, v225, v227
	v_div_fixup_f32 v67, v224, v67, 1.0
	v_lshlrev_b32_e32 v236, 16, v214
	v_and_b32_e32 v237, 0xffff0000, v214
	v_lshlrev_b32_e32 v238, 16, v215
	v_and_b32_e32 v239, 0xffff0000, v215
	v_pk_fma_f32 v[64:65], v[64:65], v[236:237], v[204:205]
	v_pk_fma_f32 v[66:67], v[66:67], v[238:239], v[206:207]
	v_cvt_pk_bf16_f32 v159, v66, v67
	v_cvt_pk_bf16_f32 v158, v64, v65
	global_store_dwordx4 v[150:151], v[64:67], off offset:576
	global_store_dwordx2 v[156:157], v[158:159], off offset:288
	s_nop 0
	v_mul_f32_e32 v65, v65, v65
	v_mul_f32_e32 v67, v67, v67
	v_fmac_f32_e32 v65, v64, v64
	v_fmac_f32_e32 v67, v66, v66
	v_add_f32_e32 v64, v65, v67
	v_add_f32_e32 v229, v229, v64
	v_mov_b32_e32 v230, v229
	s_nop 1
	v_permlane16_swap_b32_e32 v229, v230
	v_add_f32_e32 v229, v229, v230
	v_mov_b32_e32 v230, v229
	s_nop 1
	v_permlane32_swap_b32_e32 v229, v230
	s_and_saveexec_b64 s[10:11], s[6:7]
	v_lshl_add_u64 v[156:157], v[144:145], 2, s[18:19]
	v_add_f32_e32 v229, v229, v230
	global_atomic_add_f32 v[156:157], v229, off
	s_or_b64 exec, exec, s[10:11]
	v_add_u32_e32 v144, 0x90, v154
	v_mov_b32_e32 v145, v155
	v_lshlrev_b64 v[148:149], 11, v[144:145]
	v_lshl_add_u64 v[148:149], v[148:149], 0, v[146:147]
	v_lshl_add_u64 v[150:151], v[148:149], 2, s[28:29]
	v_lshl_add_u64 v[152:153], v[148:149], 1, s[42:43]
	global_load_dwordx2 v[208:209], v[152:153], off
	global_load_dwordx4 v[192:195], v[150:151], off
	global_load_dwordx2 v[210:211], v[152:153], off offset:32
	global_load_dwordx4 v[196:199], v[150:151], off offset:64
	global_load_dwordx2 v[212:213], v[152:153], off offset:256
	global_load_dwordx4 v[200:203], v[150:151], off offset:512
	global_load_dwordx2 v[214:215], v[152:153], off offset:288
	global_load_dwordx4 v[204:207], v[150:151], off offset:576
	s_waitcnt vmcnt(17)
	v_fmamk_f32 v220, v220, 0x3a000000, v164
	v_mul_f32_e32 v235, 0x4b800000, v220
	v_cmp_gt_f32_e32 vcc, s61, v220
	s_nop 1
	v_cndmask_b32_e32 v220, v220, v235, vcc
	v_rsq_f32_e32 v220, v220
	s_nop 0
	v_mul_f32_e32 v235, 0x45800000, v220
	v_cndmask_b32_e32 v234, v220, v235, vcc
	v_add_u32_e32 v144, 0x80, v154
	v_mov_b32_e32 v145, v155
	v_lshlrev_b64 v[148:149], 11, v[144:145]
	v_lshl_add_u64 v[148:149], v[148:149], 0, v[146:147]
	v_lshl_add_u64 v[150:151], v[148:149], 2, s[28:29]
	v_lshl_add_u64 v[156:157], v[148:149], 1, s[24:25]
	v_pk_mul_f32 v[60:61], v[60:61], v[234:235] op_sel_hi:[1,0]
	v_pk_mul_f32 v[62:63], v[62:63], v[234:235] op_sel_hi:[1,0]
	v_mul_f32_e32 v60, 0xbfb8aa3b, v60
	v_mul_f32_e32 v61, 0xbfb8aa3b, v61
	v_mul_f32_e32 v62, 0xbfb8aa3b, v62
	v_mul_f32_e32 v63, 0xbfb8aa3b, v63
	v_exp_f32_e32 v60, v60
	v_exp_f32_e32 v61, v61
	v_exp_f32_e32 v62, v62
	v_exp_f32_e32 v63, v63
	v_pk_add_f32 v[60:61], v[60:61], 1.0 op_sel_hi:[1,0]
	v_pk_add_f32 v[62:63], v[62:63], 1.0 op_sel_hi:[1,0]
	v_div_scale_f32 v224, s[10:11], v60, v60, 1.0
	v_rcp_f32_e32 v225, v224
	s_nop 0
	v_fma_f32 v226, -v224, v225, 1.0
	v_fmac_f32_e32 v225, v226, v225
	v_div_scale_f32 v226, vcc, 1.0, v60, 1.0
	v_mul_f32_e32 v227, v226, v225
	v_fma_f32 v228, -v224, v227, v226
	v_fmac_f32_e32 v227, v228, v225
	v_fma_f32 v224, -v224, v227, v226
	v_div_fmas_f32 v224, v224, v225, v227
	v_div_fixup_f32 v60, v224, v60, 1.0
	v_div_scale_f32 v224, s[10:11], v61, v61, 1.0
	v_rcp_f32_e32 v225, v224
	s_nop 0
	v_fma_f32 v226, -v224, v225, 1.0
	v_fmac_f32_e32 v225, v226, v225
	v_div_scale_f32 v226, vcc, 1.0, v61, 1.0
	v_mul_f32_e32 v227, v226, v225
	v_fma_f32 v228, -v224, v227, v226
	v_fmac_f32_e32 v227, v228, v225
	v_fma_f32 v224, -v224, v227, v226
	v_div_fmas_f32 v224, v224, v225, v227
	v_div_fixup_f32 v61, v224, v61, 1.0
	v_div_scale_f32 v224, s[10:11], v62, v62, 1.0
	v_rcp_f32_e32 v225, v224
	s_nop 0
	v_fma_f32 v226, -v224, v225, 1.0
	v_fmac_f32_e32 v225, v226, v225
	v_div_scale_f32 v226, vcc, 1.0, v62, 1.0
	v_mul_f32_e32 v227, v226, v225
	v_fma_f32 v228, -v224, v227, v226
	v_fmac_f32_e32 v227, v228, v225
	v_fma_f32 v224, -v224, v227, v226
	v_div_fmas_f32 v224, v224, v225, v227
	v_div_fixup_f32 v62, v224, v62, 1.0
	v_div_scale_f32 v224, s[10:11], v63, v63, 1.0
	v_rcp_f32_e32 v225, v224
	s_nop 0
	v_fma_f32 v226, -v224, v225, 1.0
	v_fmac_f32_e32 v225, v226, v225
	v_div_scale_f32 v226, vcc, 1.0, v63, 1.0
	v_mul_f32_e32 v227, v226, v225
	v_fma_f32 v228, -v224, v227, v226
	v_fmac_f32_e32 v227, v228, v225
	v_fma_f32 v224, -v224, v227, v226
	v_div_fmas_f32 v224, v224, v225, v227
	v_div_fixup_f32 v63, v224, v63, 1.0
	v_lshlrev_b32_e32 v236, 16, v184
	v_and_b32_e32 v237, 0xffff0000, v184
	v_lshlrev_b32_e32 v238, 16, v185
	v_and_b32_e32 v239, 0xffff0000, v185
	v_pk_fma_f32 v[60:61], v[60:61], v[236:237], v[168:169]
	v_pk_fma_f32 v[62:63], v[62:63], v[238:239], v[170:171]
	v_cvt_pk_bf16_f32 v159, v62, v63
	v_cvt_pk_bf16_f32 v158, v60, v61
	global_store_dwordx4 v[150:151], v[60:63], off
	global_store_dwordx2 v[156:157], v[158:159], off
	s_nop 0
	v_mul_f32_e32 v61, v61, v61
	v_mul_f32_e32 v63, v63, v63
	v_fmac_f32_e32 v61, v60, v60
	v_fmac_f32_e32 v63, v62, v62
	v_add_f32_e32 v229, v61, v63
	v_pk_mul_f32 v[56:57], v[56:57], v[234:235] op_sel_hi:[1,0]
	v_pk_mul_f32 v[58:59], v[58:59], v[234:235] op_sel_hi:[1,0]
	v_mul_f32_e32 v56, 0xbfb8aa3b, v56
	v_mul_f32_e32 v57, 0xbfb8aa3b, v57
	v_mul_f32_e32 v58, 0xbfb8aa3b, v58
	v_mul_f32_e32 v59, 0xbfb8aa3b, v59
	v_exp_f32_e32 v56, v56
	v_exp_f32_e32 v57, v57
	v_exp_f32_e32 v58, v58
	v_exp_f32_e32 v59, v59
	v_pk_add_f32 v[56:57], v[56:57], 1.0 op_sel_hi:[1,0]
	v_pk_add_f32 v[58:59], v[58:59], 1.0 op_sel_hi:[1,0]
	v_div_scale_f32 v224, s[10:11], v56, v56, 1.0
	v_rcp_f32_e32 v225, v224
	s_nop 0
	v_fma_f32 v226, -v224, v225, 1.0
	v_fmac_f32_e32 v225, v226, v225
	v_div_scale_f32 v226, vcc, 1.0, v56, 1.0
	v_mul_f32_e32 v227, v226, v225
	v_fma_f32 v228, -v224, v227, v226
	v_fmac_f32_e32 v227, v228, v225
	v_fma_f32 v224, -v224, v227, v226
	v_div_fmas_f32 v224, v224, v225, v227
	v_div_fixup_f32 v56, v224, v56, 1.0
	v_div_scale_f32 v224, s[10:11], v57, v57, 1.0
	v_rcp_f32_e32 v225, v224
	s_nop 0
	v_fma_f32 v226, -v224, v225, 1.0
	v_fmac_f32_e32 v225, v226, v225
	v_div_scale_f32 v226, vcc, 1.0, v57, 1.0
	v_mul_f32_e32 v227, v226, v225
	v_fma_f32 v228, -v224, v227, v226
	v_fmac_f32_e32 v227, v228, v225
	v_fma_f32 v224, -v224, v227, v226
	v_div_fmas_f32 v224, v224, v225, v227
	v_div_fixup_f32 v57, v224, v57, 1.0
	v_div_scale_f32 v224, s[10:11], v58, v58, 1.0
	v_rcp_f32_e32 v225, v224
	s_nop 0
	v_fma_f32 v226, -v224, v225, 1.0
	v_fmac_f32_e32 v225, v226, v225
	v_div_scale_f32 v226, vcc, 1.0, v58, 1.0
	v_mul_f32_e32 v227, v226, v225
	v_fma_f32 v228, -v224, v227, v226
	v_fmac_f32_e32 v227, v228, v225
	v_fma_f32 v224, -v224, v227, v226
	v_div_fmas_f32 v224, v224, v225, v227
	v_div_fixup_f32 v58, v224, v58, 1.0
	v_div_scale_f32 v224, s[10:11], v59, v59, 1.0
	v_rcp_f32_e32 v225, v224
	s_nop 0
	v_fma_f32 v226, -v224, v225, 1.0
	v_fmac_f32_e32 v225, v226, v225
	v_div_scale_f32 v226, vcc, 1.0, v59, 1.0
	v_mul_f32_e32 v227, v226, v225
	v_fma_f32 v228, -v224, v227, v226
	v_fmac_f32_e32 v227, v228, v225
	v_fma_f32 v224, -v224, v227, v226
	v_div_fmas_f32 v224, v224, v225, v227
	v_div_fixup_f32 v59, v224, v59, 1.0
	v_lshlrev_b32_e32 v236, 16, v186
	v_and_b32_e32 v237, 0xffff0000, v186
	v_lshlrev_b32_e32 v238, 16, v187
	v_and_b32_e32 v239, 0xffff0000, v187
	v_pk_fma_f32 v[56:57], v[56:57], v[236:237], v[172:173]
	v_pk_fma_f32 v[58:59], v[58:59], v[238:239], v[174:175]
	v_cvt_pk_bf16_f32 v159, v58, v59
	v_cvt_pk_bf16_f32 v158, v56, v57
	global_store_dwordx4 v[150:151], v[56:59], off offset:64
	global_store_dwordx2 v[156:157], v[158:159], off offset:32
	s_nop 0
	v_mul_f32_e32 v57, v57, v57
	v_mul_f32_e32 v59, v59, v59
	v_fmac_f32_e32 v57, v56, v56
	v_fmac_f32_e32 v59, v58, v58
	v_add_f32_e32 v56, v57, v59
	v_add_f32_e32 v229, v229, v56
	v_pk_mul_f32 v[52:53], v[52:53], v[234:235] op_sel_hi:[1,0]
	v_pk_mul_f32 v[54:55], v[54:55], v[234:235] op_sel_hi:[1,0]
	v_mul_f32_e32 v52, 0xbfb8aa3b, v52
	v_mul_f32_e32 v53, 0xbfb8aa3b, v53
	v_mul_f32_e32 v54, 0xbfb8aa3b, v54
	v_mul_f32_e32 v55, 0xbfb8aa3b, v55
	v_exp_f32_e32 v52, v52
	v_exp_f32_e32 v53, v53
	v_exp_f32_e32 v54, v54
	v_exp_f32_e32 v55, v55
	v_pk_add_f32 v[52:53], v[52:53], 1.0 op_sel_hi:[1,0]
	v_pk_add_f32 v[54:55], v[54:55], 1.0 op_sel_hi:[1,0]
	v_div_scale_f32 v224, s[10:11], v52, v52, 1.0
	v_rcp_f32_e32 v225, v224
	s_nop 0
	v_fma_f32 v226, -v224, v225, 1.0
	v_fmac_f32_e32 v225, v226, v225
	v_div_scale_f32 v226, vcc, 1.0, v52, 1.0
	v_mul_f32_e32 v227, v226, v225
	v_fma_f32 v228, -v224, v227, v226
	v_fmac_f32_e32 v227, v228, v225
	v_fma_f32 v224, -v224, v227, v226
	v_div_fmas_f32 v224, v224, v225, v227
	v_div_fixup_f32 v52, v224, v52, 1.0
	v_div_scale_f32 v224, s[10:11], v53, v53, 1.0
	v_rcp_f32_e32 v225, v224
	s_nop 0
	v_fma_f32 v226, -v224, v225, 1.0
	v_fmac_f32_e32 v225, v226, v225
	v_div_scale_f32 v226, vcc, 1.0, v53, 1.0
	v_mul_f32_e32 v227, v226, v225
	v_fma_f32 v228, -v224, v227, v226
	v_fmac_f32_e32 v227, v228, v225
	v_fma_f32 v224, -v224, v227, v226
	v_div_fmas_f32 v224, v224, v225, v227
	v_div_fixup_f32 v53, v224, v53, 1.0
	v_div_scale_f32 v224, s[10:11], v54, v54, 1.0
	v_rcp_f32_e32 v225, v224
	s_nop 0
	v_fma_f32 v226, -v224, v225, 1.0
	v_fmac_f32_e32 v225, v226, v225
	v_div_scale_f32 v226, vcc, 1.0, v54, 1.0
	v_mul_f32_e32 v227, v226, v225
	v_fma_f32 v228, -v224, v227, v226
	v_fmac_f32_e32 v227, v228, v225
	v_fma_f32 v224, -v224, v227, v226
	v_div_fmas_f32 v224, v224, v225, v227
	v_div_fixup_f32 v54, v224, v54, 1.0
	v_div_scale_f32 v224, s[10:11], v55, v55, 1.0
	v_rcp_f32_e32 v225, v224
	s_nop 0
	v_fma_f32 v226, -v224, v225, 1.0
	v_fmac_f32_e32 v225, v226, v225
	v_div_scale_f32 v226, vcc, 1.0, v55, 1.0
	v_mul_f32_e32 v227, v226, v225
	v_fma_f32 v228, -v224, v227, v226
	v_fmac_f32_e32 v227, v228, v225
	v_fma_f32 v224, -v224, v227, v226
	v_div_fmas_f32 v224, v224, v225, v227
	v_div_fixup_f32 v55, v224, v55, 1.0
	v_lshlrev_b32_e32 v236, 16, v188
	v_and_b32_e32 v237, 0xffff0000, v188
	v_lshlrev_b32_e32 v238, 16, v189
	v_and_b32_e32 v239, 0xffff0000, v189
	v_pk_fma_f32 v[52:53], v[52:53], v[236:237], v[176:177]
	v_pk_fma_f32 v[54:55], v[54:55], v[238:239], v[178:179]
	v_cvt_pk_bf16_f32 v159, v54, v55
	v_cvt_pk_bf16_f32 v158, v52, v53
	global_store_dwordx4 v[150:151], v[52:55], off offset:512
	global_store_dwordx2 v[156:157], v[158:159], off offset:256
	s_nop 0
	v_mul_f32_e32 v53, v53, v53
	v_mul_f32_e32 v55, v55, v55
	v_fmac_f32_e32 v53, v52, v52
	v_fmac_f32_e32 v55, v54, v54
	v_add_f32_e32 v52, v53, v55
	v_add_f32_e32 v229, v229, v52
	v_pk_mul_f32 v[48:49], v[48:49], v[234:235] op_sel_hi:[1,0]
	v_pk_mul_f32 v[50:51], v[50:51], v[234:235] op_sel_hi:[1,0]
	v_mul_f32_e32 v48, 0xbfb8aa3b, v48
	v_mul_f32_e32 v49, 0xbfb8aa3b, v49
	v_mul_f32_e32 v50, 0xbfb8aa3b, v50
	v_mul_f32_e32 v51, 0xbfb8aa3b, v51
	v_exp_f32_e32 v48, v48
	v_exp_f32_e32 v49, v49
	v_exp_f32_e32 v50, v50
	v_exp_f32_e32 v51, v51
	v_pk_add_f32 v[48:49], v[48:49], 1.0 op_sel_hi:[1,0]
	v_pk_add_f32 v[50:51], v[50:51], 1.0 op_sel_hi:[1,0]
	v_div_scale_f32 v224, s[10:11], v48, v48, 1.0
	v_rcp_f32_e32 v225, v224
	s_nop 0
	v_fma_f32 v226, -v224, v225, 1.0
	v_fmac_f32_e32 v225, v226, v225
	v_div_scale_f32 v226, vcc, 1.0, v48, 1.0
	v_mul_f32_e32 v227, v226, v225
	v_fma_f32 v228, -v224, v227, v226
	v_fmac_f32_e32 v227, v228, v225
	v_fma_f32 v224, -v224, v227, v226
	v_div_fmas_f32 v224, v224, v225, v227
	v_div_fixup_f32 v48, v224, v48, 1.0
	v_div_scale_f32 v224, s[10:11], v49, v49, 1.0
	v_rcp_f32_e32 v225, v224
	s_nop 0
	v_fma_f32 v226, -v224, v225, 1.0
	v_fmac_f32_e32 v225, v226, v225
	v_div_scale_f32 v226, vcc, 1.0, v49, 1.0
	v_mul_f32_e32 v227, v226, v225
	v_fma_f32 v228, -v224, v227, v226
	v_fmac_f32_e32 v227, v228, v225
	v_fma_f32 v224, -v224, v227, v226
	v_div_fmas_f32 v224, v224, v225, v227
	v_div_fixup_f32 v49, v224, v49, 1.0
	v_div_scale_f32 v224, s[10:11], v50, v50, 1.0
	v_rcp_f32_e32 v225, v224
	s_nop 0
	v_fma_f32 v226, -v224, v225, 1.0
	v_fmac_f32_e32 v225, v226, v225
	v_div_scale_f32 v226, vcc, 1.0, v50, 1.0
	v_mul_f32_e32 v227, v226, v225
	v_fma_f32 v228, -v224, v227, v226
	v_fmac_f32_e32 v227, v228, v225
	v_fma_f32 v224, -v224, v227, v226
	v_div_fmas_f32 v224, v224, v225, v227
	v_div_fixup_f32 v50, v224, v50, 1.0
	v_div_scale_f32 v224, s[10:11], v51, v51, 1.0
	v_rcp_f32_e32 v225, v224
	s_nop 0
	v_fma_f32 v226, -v224, v225, 1.0
	v_fmac_f32_e32 v225, v226, v225
	v_div_scale_f32 v226, vcc, 1.0, v51, 1.0
	v_mul_f32_e32 v227, v226, v225
	v_fma_f32 v228, -v224, v227, v226
	v_fmac_f32_e32 v227, v228, v225
	v_fma_f32 v224, -v224, v227, v226
	v_div_fmas_f32 v224, v224, v225, v227
	v_div_fixup_f32 v51, v224, v51, 1.0
	v_lshlrev_b32_e32 v236, 16, v190
	v_and_b32_e32 v237, 0xffff0000, v190
	v_lshlrev_b32_e32 v238, 16, v191
	v_and_b32_e32 v239, 0xffff0000, v191
	v_pk_fma_f32 v[48:49], v[48:49], v[236:237], v[180:181]
	v_pk_fma_f32 v[50:51], v[50:51], v[238:239], v[182:183]
	v_cvt_pk_bf16_f32 v159, v50, v51
	v_cvt_pk_bf16_f32 v158, v48, v49
	global_store_dwordx4 v[150:151], v[48:51], off offset:576
	global_store_dwordx2 v[156:157], v[158:159], off offset:288
	s_nop 0
	v_mul_f32_e32 v49, v49, v49
	v_mul_f32_e32 v51, v51, v51
	v_fmac_f32_e32 v49, v48, v48
	v_fmac_f32_e32 v51, v50, v50
	v_add_f32_e32 v48, v49, v51
	v_add_f32_e32 v229, v229, v48
	v_mov_b32_e32 v230, v229
	s_nop 1
	v_permlane16_swap_b32_e32 v229, v230
	v_add_f32_e32 v229, v229, v230
	v_mov_b32_e32 v230, v229
	s_nop 1
	v_permlane32_swap_b32_e32 v229, v230
	s_and_saveexec_b64 s[10:11], s[6:7]
	v_lshl_add_u64 v[156:157], v[144:145], 2, s[18:19]
	v_add_f32_e32 v229, v229, v230
	global_atomic_add_f32 v[156:157], v229, off
	s_or_b64 exec, exec, s[10:11]
	v_add_u32_e32 v144, 0xa0, v154
	v_mov_b32_e32 v145, v155
	v_lshlrev_b64 v[148:149], 11, v[144:145]
	v_lshl_add_u64 v[148:149], v[148:149], 0, v[146:147]
	v_lshl_add_u64 v[150:151], v[148:149], 2, s[28:29]
	v_lshl_add_u64 v[152:153], v[148:149], 1, s[42:43]
	global_load_dwordx2 v[184:185], v[152:153], off
	global_load_dwordx4 v[168:171], v[150:151], off
	global_load_dwordx2 v[186:187], v[152:153], off offset:32
	global_load_dwordx4 v[172:175], v[150:151], off offset:64
	global_load_dwordx2 v[188:189], v[152:153], off offset:256
	global_load_dwordx4 v[176:179], v[150:151], off offset:512
	global_load_dwordx2 v[190:191], v[152:153], off offset:288
	global_load_dwordx4 v[180:183], v[150:151], off offset:576
	s_waitcnt vmcnt(17)
	v_fmamk_f32 v221, v221, 0x3a000000, v164
	v_mul_f32_e32 v235, 0x4b800000, v221
	v_cmp_gt_f32_e32 vcc, s61, v221
	s_nop 1
	v_cndmask_b32_e32 v221, v221, v235, vcc
	v_rsq_f32_e32 v221, v221
	s_nop 0
	v_mul_f32_e32 v235, 0x45800000, v221
	v_cndmask_b32_e32 v234, v221, v235, vcc
	v_add_u32_e32 v144, 0x90, v154
	v_mov_b32_e32 v145, v155
	v_lshlrev_b64 v[148:149], 11, v[144:145]
	v_lshl_add_u64 v[148:149], v[148:149], 0, v[146:147]
	v_lshl_add_u64 v[150:151], v[148:149], 2, s[28:29]
	v_lshl_add_u64 v[156:157], v[148:149], 1, s[24:25]
	v_pk_mul_f32 v[44:45], v[44:45], v[234:235] op_sel_hi:[1,0]
	v_pk_mul_f32 v[46:47], v[46:47], v[234:235] op_sel_hi:[1,0]
	v_mul_f32_e32 v44, 0xbfb8aa3b, v44
	v_mul_f32_e32 v45, 0xbfb8aa3b, v45
	v_mul_f32_e32 v46, 0xbfb8aa3b, v46
	v_mul_f32_e32 v47, 0xbfb8aa3b, v47
	v_exp_f32_e32 v44, v44
	v_exp_f32_e32 v45, v45
	v_exp_f32_e32 v46, v46
	v_exp_f32_e32 v47, v47
	v_pk_add_f32 v[44:45], v[44:45], 1.0 op_sel_hi:[1,0]
	v_pk_add_f32 v[46:47], v[46:47], 1.0 op_sel_hi:[1,0]
	v_div_scale_f32 v224, s[10:11], v44, v44, 1.0
	v_rcp_f32_e32 v225, v224
	s_nop 0
	v_fma_f32 v226, -v224, v225, 1.0
	v_fmac_f32_e32 v225, v226, v225
	v_div_scale_f32 v226, vcc, 1.0, v44, 1.0
	v_mul_f32_e32 v227, v226, v225
	v_fma_f32 v228, -v224, v227, v226
	v_fmac_f32_e32 v227, v228, v225
	v_fma_f32 v224, -v224, v227, v226
	v_div_fmas_f32 v224, v224, v225, v227
	v_div_fixup_f32 v44, v224, v44, 1.0
	v_div_scale_f32 v224, s[10:11], v45, v45, 1.0
	v_rcp_f32_e32 v225, v224
	s_nop 0
	v_fma_f32 v226, -v224, v225, 1.0
	v_fmac_f32_e32 v225, v226, v225
	v_div_scale_f32 v226, vcc, 1.0, v45, 1.0
	v_mul_f32_e32 v227, v226, v225
	v_fma_f32 v228, -v224, v227, v226
	v_fmac_f32_e32 v227, v228, v225
	v_fma_f32 v224, -v224, v227, v226
	v_div_fmas_f32 v224, v224, v225, v227
	v_div_fixup_f32 v45, v224, v45, 1.0
	v_div_scale_f32 v224, s[10:11], v46, v46, 1.0
	v_rcp_f32_e32 v225, v224
	s_nop 0
	v_fma_f32 v226, -v224, v225, 1.0
	v_fmac_f32_e32 v225, v226, v225
	v_div_scale_f32 v226, vcc, 1.0, v46, 1.0
	v_mul_f32_e32 v227, v226, v225
	v_fma_f32 v228, -v224, v227, v226
	v_fmac_f32_e32 v227, v228, v225
	v_fma_f32 v224, -v224, v227, v226
	v_div_fmas_f32 v224, v224, v225, v227
	v_div_fixup_f32 v46, v224, v46, 1.0
	v_div_scale_f32 v224, s[10:11], v47, v47, 1.0
	v_rcp_f32_e32 v225, v224
	s_nop 0
	v_fma_f32 v226, -v224, v225, 1.0
	v_fmac_f32_e32 v225, v226, v225
	v_div_scale_f32 v226, vcc, 1.0, v47, 1.0
	v_mul_f32_e32 v227, v226, v225
	v_fma_f32 v228, -v224, v227, v226
	v_fmac_f32_e32 v227, v228, v225
	v_fma_f32 v224, -v224, v227, v226
	v_div_fmas_f32 v224, v224, v225, v227
	v_div_fixup_f32 v47, v224, v47, 1.0
	v_lshlrev_b32_e32 v236, 16, v208
	v_and_b32_e32 v237, 0xffff0000, v208
	v_lshlrev_b32_e32 v238, 16, v209
	v_and_b32_e32 v239, 0xffff0000, v209
	v_pk_fma_f32 v[44:45], v[44:45], v[236:237], v[192:193]
	v_pk_fma_f32 v[46:47], v[46:47], v[238:239], v[194:195]
	v_cvt_pk_bf16_f32 v159, v46, v47
	v_cvt_pk_bf16_f32 v158, v44, v45
	global_store_dwordx4 v[150:151], v[44:47], off
	global_store_dwordx2 v[156:157], v[158:159], off
	s_nop 0
	v_mul_f32_e32 v45, v45, v45
	v_mul_f32_e32 v47, v47, v47
	v_fmac_f32_e32 v45, v44, v44
	v_fmac_f32_e32 v47, v46, v46
	v_add_f32_e32 v229, v45, v47
	v_pk_mul_f32 v[40:41], v[40:41], v[234:235] op_sel_hi:[1,0]
	v_pk_mul_f32 v[42:43], v[42:43], v[234:235] op_sel_hi:[1,0]
	v_mul_f32_e32 v40, 0xbfb8aa3b, v40
	v_mul_f32_e32 v41, 0xbfb8aa3b, v41
	v_mul_f32_e32 v42, 0xbfb8aa3b, v42
	v_mul_f32_e32 v43, 0xbfb8aa3b, v43
	v_exp_f32_e32 v40, v40
	v_exp_f32_e32 v41, v41
	v_exp_f32_e32 v42, v42
	v_exp_f32_e32 v43, v43
	v_pk_add_f32 v[40:41], v[40:41], 1.0 op_sel_hi:[1,0]
	v_pk_add_f32 v[42:43], v[42:43], 1.0 op_sel_hi:[1,0]
	v_div_scale_f32 v224, s[10:11], v40, v40, 1.0
	v_rcp_f32_e32 v225, v224
	s_nop 0
	v_fma_f32 v226, -v224, v225, 1.0
	v_fmac_f32_e32 v225, v226, v225
	v_div_scale_f32 v226, vcc, 1.0, v40, 1.0
	v_mul_f32_e32 v227, v226, v225
	v_fma_f32 v228, -v224, v227, v226
	v_fmac_f32_e32 v227, v228, v225
	v_fma_f32 v224, -v224, v227, v226
	v_div_fmas_f32 v224, v224, v225, v227
	v_div_fixup_f32 v40, v224, v40, 1.0
	v_div_scale_f32 v224, s[10:11], v41, v41, 1.0
	v_rcp_f32_e32 v225, v224
	s_nop 0
	v_fma_f32 v226, -v224, v225, 1.0
	v_fmac_f32_e32 v225, v226, v225
	v_div_scale_f32 v226, vcc, 1.0, v41, 1.0
	v_mul_f32_e32 v227, v226, v225
	v_fma_f32 v228, -v224, v227, v226
	v_fmac_f32_e32 v227, v228, v225
	v_fma_f32 v224, -v224, v227, v226
	v_div_fmas_f32 v224, v224, v225, v227
	v_div_fixup_f32 v41, v224, v41, 1.0
	v_div_scale_f32 v224, s[10:11], v42, v42, 1.0
	v_rcp_f32_e32 v225, v224
	s_nop 0
	v_fma_f32 v226, -v224, v225, 1.0
	v_fmac_f32_e32 v225, v226, v225
	v_div_scale_f32 v226, vcc, 1.0, v42, 1.0
	v_mul_f32_e32 v227, v226, v225
	v_fma_f32 v228, -v224, v227, v226
	v_fmac_f32_e32 v227, v228, v225
	v_fma_f32 v224, -v224, v227, v226
	v_div_fmas_f32 v224, v224, v225, v227
	v_div_fixup_f32 v42, v224, v42, 1.0
	v_div_scale_f32 v224, s[10:11], v43, v43, 1.0
	v_rcp_f32_e32 v225, v224
	s_nop 0
	v_fma_f32 v226, -v224, v225, 1.0
	v_fmac_f32_e32 v225, v226, v225
	v_div_scale_f32 v226, vcc, 1.0, v43, 1.0
	v_mul_f32_e32 v227, v226, v225
	v_fma_f32 v228, -v224, v227, v226
	v_fmac_f32_e32 v227, v228, v225
	v_fma_f32 v224, -v224, v227, v226
	v_div_fmas_f32 v224, v224, v225, v227
	v_div_fixup_f32 v43, v224, v43, 1.0
	v_lshlrev_b32_e32 v236, 16, v210
	v_and_b32_e32 v237, 0xffff0000, v210
	v_lshlrev_b32_e32 v238, 16, v211
	v_and_b32_e32 v239, 0xffff0000, v211
	v_pk_fma_f32 v[40:41], v[40:41], v[236:237], v[196:197]
	v_pk_fma_f32 v[42:43], v[42:43], v[238:239], v[198:199]
	v_cvt_pk_bf16_f32 v159, v42, v43
	v_cvt_pk_bf16_f32 v158, v40, v41
	global_store_dwordx4 v[150:151], v[40:43], off offset:64
	global_store_dwordx2 v[156:157], v[158:159], off offset:32
	s_nop 0
	v_mul_f32_e32 v41, v41, v41
	v_mul_f32_e32 v43, v43, v43
	v_fmac_f32_e32 v41, v40, v40
	v_fmac_f32_e32 v43, v42, v42
	v_add_f32_e32 v40, v41, v43
	v_add_f32_e32 v229, v229, v40
	v_pk_mul_f32 v[36:37], v[36:37], v[234:235] op_sel_hi:[1,0]
	v_pk_mul_f32 v[38:39], v[38:39], v[234:235] op_sel_hi:[1,0]
	v_mul_f32_e32 v36, 0xbfb8aa3b, v36
	v_mul_f32_e32 v37, 0xbfb8aa3b, v37
	v_mul_f32_e32 v38, 0xbfb8aa3b, v38
	v_mul_f32_e32 v39, 0xbfb8aa3b, v39
	v_exp_f32_e32 v36, v36
	v_exp_f32_e32 v37, v37
	v_exp_f32_e32 v38, v38
	v_exp_f32_e32 v39, v39
	v_pk_add_f32 v[36:37], v[36:37], 1.0 op_sel_hi:[1,0]
	v_pk_add_f32 v[38:39], v[38:39], 1.0 op_sel_hi:[1,0]
	v_div_scale_f32 v224, s[10:11], v36, v36, 1.0
	v_rcp_f32_e32 v225, v224
	s_nop 0
	v_fma_f32 v226, -v224, v225, 1.0
	v_fmac_f32_e32 v225, v226, v225
	v_div_scale_f32 v226, vcc, 1.0, v36, 1.0
	v_mul_f32_e32 v227, v226, v225
	v_fma_f32 v228, -v224, v227, v226
	v_fmac_f32_e32 v227, v228, v225
	v_fma_f32 v224, -v224, v227, v226
	v_div_fmas_f32 v224, v224, v225, v227
	v_div_fixup_f32 v36, v224, v36, 1.0
	v_div_scale_f32 v224, s[10:11], v37, v37, 1.0
	v_rcp_f32_e32 v225, v224
	s_nop 0
	v_fma_f32 v226, -v224, v225, 1.0
	v_fmac_f32_e32 v225, v226, v225
	v_div_scale_f32 v226, vcc, 1.0, v37, 1.0
	v_mul_f32_e32 v227, v226, v225
	v_fma_f32 v228, -v224, v227, v226
	v_fmac_f32_e32 v227, v228, v225
	v_fma_f32 v224, -v224, v227, v226
	v_div_fmas_f32 v224, v224, v225, v227
	v_div_fixup_f32 v37, v224, v37, 1.0
	v_div_scale_f32 v224, s[10:11], v38, v38, 1.0
	v_rcp_f32_e32 v225, v224
	s_nop 0
	v_fma_f32 v226, -v224, v225, 1.0
	v_fmac_f32_e32 v225, v226, v225
	v_div_scale_f32 v226, vcc, 1.0, v38, 1.0
	v_mul_f32_e32 v227, v226, v225
	v_fma_f32 v228, -v224, v227, v226
	v_fmac_f32_e32 v227, v228, v225
	v_fma_f32 v224, -v224, v227, v226
	v_div_fmas_f32 v224, v224, v225, v227
	v_div_fixup_f32 v38, v224, v38, 1.0
	v_div_scale_f32 v224, s[10:11], v39, v39, 1.0
	v_rcp_f32_e32 v225, v224
	s_nop 0
	v_fma_f32 v226, -v224, v225, 1.0
	v_fmac_f32_e32 v225, v226, v225
	v_div_scale_f32 v226, vcc, 1.0, v39, 1.0
	v_mul_f32_e32 v227, v226, v225
	v_fma_f32 v228, -v224, v227, v226
	v_fmac_f32_e32 v227, v228, v225
	v_fma_f32 v224, -v224, v227, v226
	v_div_fmas_f32 v224, v224, v225, v227
	v_div_fixup_f32 v39, v224, v39, 1.0
	v_lshlrev_b32_e32 v236, 16, v212
	v_and_b32_e32 v237, 0xffff0000, v212
	v_lshlrev_b32_e32 v238, 16, v213
	v_and_b32_e32 v239, 0xffff0000, v213
	v_pk_fma_f32 v[36:37], v[36:37], v[236:237], v[200:201]
	v_pk_fma_f32 v[38:39], v[38:39], v[238:239], v[202:203]
	v_cvt_pk_bf16_f32 v159, v38, v39
	v_cvt_pk_bf16_f32 v158, v36, v37
	global_store_dwordx4 v[150:151], v[36:39], off offset:512
	global_store_dwordx2 v[156:157], v[158:159], off offset:256
	s_nop 0
	v_mul_f32_e32 v37, v37, v37
	v_mul_f32_e32 v39, v39, v39
	v_fmac_f32_e32 v37, v36, v36
	v_fmac_f32_e32 v39, v38, v38
	v_add_f32_e32 v36, v37, v39
	v_add_f32_e32 v229, v229, v36
	v_pk_mul_f32 v[32:33], v[32:33], v[234:235] op_sel_hi:[1,0]
	v_pk_mul_f32 v[34:35], v[34:35], v[234:235] op_sel_hi:[1,0]
	v_mul_f32_e32 v32, 0xbfb8aa3b, v32
	v_mul_f32_e32 v33, 0xbfb8aa3b, v33
	v_mul_f32_e32 v34, 0xbfb8aa3b, v34
	v_mul_f32_e32 v35, 0xbfb8aa3b, v35
	v_exp_f32_e32 v32, v32
	v_exp_f32_e32 v33, v33
	v_exp_f32_e32 v34, v34
	v_exp_f32_e32 v35, v35
	v_pk_add_f32 v[32:33], v[32:33], 1.0 op_sel_hi:[1,0]
	v_pk_add_f32 v[34:35], v[34:35], 1.0 op_sel_hi:[1,0]
	v_div_scale_f32 v224, s[10:11], v32, v32, 1.0
	v_rcp_f32_e32 v225, v224
	s_nop 0
	v_fma_f32 v226, -v224, v225, 1.0
	v_fmac_f32_e32 v225, v226, v225
	v_div_scale_f32 v226, vcc, 1.0, v32, 1.0
	v_mul_f32_e32 v227, v226, v225
	v_fma_f32 v228, -v224, v227, v226
	v_fmac_f32_e32 v227, v228, v225
	v_fma_f32 v224, -v224, v227, v226
	v_div_fmas_f32 v224, v224, v225, v227
	v_div_fixup_f32 v32, v224, v32, 1.0
	v_div_scale_f32 v224, s[10:11], v33, v33, 1.0
	v_rcp_f32_e32 v225, v224
	s_nop 0
	v_fma_f32 v226, -v224, v225, 1.0
	v_fmac_f32_e32 v225, v226, v225
	v_div_scale_f32 v226, vcc, 1.0, v33, 1.0
	v_mul_f32_e32 v227, v226, v225
	v_fma_f32 v228, -v224, v227, v226
	v_fmac_f32_e32 v227, v228, v225
	v_fma_f32 v224, -v224, v227, v226
	v_div_fmas_f32 v224, v224, v225, v227
	v_div_fixup_f32 v33, v224, v33, 1.0
	v_div_scale_f32 v224, s[10:11], v34, v34, 1.0
	v_rcp_f32_e32 v225, v224
	s_nop 0
	v_fma_f32 v226, -v224, v225, 1.0
	v_fmac_f32_e32 v225, v226, v225
	v_div_scale_f32 v226, vcc, 1.0, v34, 1.0
	v_mul_f32_e32 v227, v226, v225
	v_fma_f32 v228, -v224, v227, v226
	v_fmac_f32_e32 v227, v228, v225
	v_fma_f32 v224, -v224, v227, v226
	v_div_fmas_f32 v224, v224, v225, v227
	v_div_fixup_f32 v34, v224, v34, 1.0
	v_div_scale_f32 v224, s[10:11], v35, v35, 1.0
	v_rcp_f32_e32 v225, v224
	s_nop 0
	v_fma_f32 v226, -v224, v225, 1.0
	v_fmac_f32_e32 v225, v226, v225
	v_div_scale_f32 v226, vcc, 1.0, v35, 1.0
	v_mul_f32_e32 v227, v226, v225
	v_fma_f32 v228, -v224, v227, v226
	v_fmac_f32_e32 v227, v228, v225
	v_fma_f32 v224, -v224, v227, v226
	v_div_fmas_f32 v224, v224, v225, v227
	v_div_fixup_f32 v35, v224, v35, 1.0
	v_lshlrev_b32_e32 v236, 16, v214
	v_and_b32_e32 v237, 0xffff0000, v214
	v_lshlrev_b32_e32 v238, 16, v215
	v_and_b32_e32 v239, 0xffff0000, v215
	v_pk_fma_f32 v[32:33], v[32:33], v[236:237], v[204:205]
	v_pk_fma_f32 v[34:35], v[34:35], v[238:239], v[206:207]
	v_cvt_pk_bf16_f32 v159, v34, v35
	v_cvt_pk_bf16_f32 v158, v32, v33
	global_store_dwordx4 v[150:151], v[32:35], off offset:576
	global_store_dwordx2 v[156:157], v[158:159], off offset:288
	s_nop 0
	v_mul_f32_e32 v33, v33, v33
	v_mul_f32_e32 v35, v35, v35
	v_fmac_f32_e32 v33, v32, v32
	v_fmac_f32_e32 v35, v34, v34
	v_add_f32_e32 v32, v33, v35
	v_add_f32_e32 v229, v229, v32
	v_mov_b32_e32 v230, v229
	s_nop 1
	v_permlane16_swap_b32_e32 v229, v230
	v_add_f32_e32 v229, v229, v230
	v_mov_b32_e32 v230, v229
	s_nop 1
	v_permlane32_swap_b32_e32 v229, v230
	s_and_saveexec_b64 s[10:11], s[6:7]
	v_lshl_add_u64 v[156:157], v[144:145], 2, s[18:19]
	v_add_f32_e32 v229, v229, v230
	global_atomic_add_f32 v[156:157], v229, off
	s_or_b64 exec, exec, s[10:11]
	v_add_u32_e32 v144, 0xb0, v154
	v_mov_b32_e32 v145, v155
	v_lshlrev_b64 v[148:149], 11, v[144:145]
	v_lshl_add_u64 v[148:149], v[148:149], 0, v[146:147]
	v_lshl_add_u64 v[150:151], v[148:149], 2, s[28:29]
	v_lshl_add_u64 v[152:153], v[148:149], 1, s[42:43]
	global_load_dwordx2 v[208:209], v[152:153], off
	global_load_dwordx4 v[192:195], v[150:151], off
	global_load_dwordx2 v[210:211], v[152:153], off offset:32
	global_load_dwordx4 v[196:199], v[150:151], off offset:64
	global_load_dwordx2 v[212:213], v[152:153], off offset:256
	global_load_dwordx4 v[200:203], v[150:151], off offset:512
	global_load_dwordx2 v[214:215], v[152:153], off offset:288
	global_load_dwordx4 v[204:207], v[150:151], off offset:576
	s_waitcnt vmcnt(17)
	v_fmamk_f32 v222, v222, 0x3a000000, v164
	v_mul_f32_e32 v235, 0x4b800000, v222
	v_cmp_gt_f32_e32 vcc, s61, v222
	s_nop 1
	v_cndmask_b32_e32 v222, v222, v235, vcc
	v_rsq_f32_e32 v222, v222
	s_nop 0
	v_mul_f32_e32 v235, 0x45800000, v222
	v_cndmask_b32_e32 v234, v222, v235, vcc
	v_add_u32_e32 v144, 0xa0, v154
	v_mov_b32_e32 v145, v155
	v_lshlrev_b64 v[148:149], 11, v[144:145]
	v_lshl_add_u64 v[148:149], v[148:149], 0, v[146:147]
	v_lshl_add_u64 v[150:151], v[148:149], 2, s[28:29]
	v_lshl_add_u64 v[156:157], v[148:149], 1, s[24:25]
	v_pk_mul_f32 v[28:29], v[28:29], v[234:235] op_sel_hi:[1,0]
	v_pk_mul_f32 v[30:31], v[30:31], v[234:235] op_sel_hi:[1,0]
	v_mul_f32_e32 v28, 0xbfb8aa3b, v28
	v_mul_f32_e32 v29, 0xbfb8aa3b, v29
	v_mul_f32_e32 v30, 0xbfb8aa3b, v30
	v_mul_f32_e32 v31, 0xbfb8aa3b, v31
	v_exp_f32_e32 v28, v28
	v_exp_f32_e32 v29, v29
	v_exp_f32_e32 v30, v30
	v_exp_f32_e32 v31, v31
	v_pk_add_f32 v[28:29], v[28:29], 1.0 op_sel_hi:[1,0]
	v_pk_add_f32 v[30:31], v[30:31], 1.0 op_sel_hi:[1,0]
	v_div_scale_f32 v224, s[10:11], v28, v28, 1.0
	v_rcp_f32_e32 v225, v224
	s_nop 0
	v_fma_f32 v226, -v224, v225, 1.0
	v_fmac_f32_e32 v225, v226, v225
	v_div_scale_f32 v226, vcc, 1.0, v28, 1.0
	v_mul_f32_e32 v227, v226, v225
	v_fma_f32 v228, -v224, v227, v226
	v_fmac_f32_e32 v227, v228, v225
	v_fma_f32 v224, -v224, v227, v226
	v_div_fmas_f32 v224, v224, v225, v227
	v_div_fixup_f32 v28, v224, v28, 1.0
	v_div_scale_f32 v224, s[10:11], v29, v29, 1.0
	v_rcp_f32_e32 v225, v224
	s_nop 0
	v_fma_f32 v226, -v224, v225, 1.0
	v_fmac_f32_e32 v225, v226, v225
	v_div_scale_f32 v226, vcc, 1.0, v29, 1.0
	v_mul_f32_e32 v227, v226, v225
	v_fma_f32 v228, -v224, v227, v226
	v_fmac_f32_e32 v227, v228, v225
	v_fma_f32 v224, -v224, v227, v226
	v_div_fmas_f32 v224, v224, v225, v227
	v_div_fixup_f32 v29, v224, v29, 1.0
	v_div_scale_f32 v224, s[10:11], v30, v30, 1.0
	v_rcp_f32_e32 v225, v224
	s_nop 0
	v_fma_f32 v226, -v224, v225, 1.0
	v_fmac_f32_e32 v225, v226, v225
	v_div_scale_f32 v226, vcc, 1.0, v30, 1.0
	v_mul_f32_e32 v227, v226, v225
	v_fma_f32 v228, -v224, v227, v226
	v_fmac_f32_e32 v227, v228, v225
	v_fma_f32 v224, -v224, v227, v226
	v_div_fmas_f32 v224, v224, v225, v227
	v_div_fixup_f32 v30, v224, v30, 1.0
	v_div_scale_f32 v224, s[10:11], v31, v31, 1.0
	v_rcp_f32_e32 v225, v224
	s_nop 0
	v_fma_f32 v226, -v224, v225, 1.0
	v_fmac_f32_e32 v225, v226, v225
	v_div_scale_f32 v226, vcc, 1.0, v31, 1.0
	v_mul_f32_e32 v227, v226, v225
	v_fma_f32 v228, -v224, v227, v226
	v_fmac_f32_e32 v227, v228, v225
	v_fma_f32 v224, -v224, v227, v226
	v_div_fmas_f32 v224, v224, v225, v227
	v_div_fixup_f32 v31, v224, v31, 1.0
	v_lshlrev_b32_e32 v236, 16, v184
	v_and_b32_e32 v237, 0xffff0000, v184
	v_lshlrev_b32_e32 v238, 16, v185
	v_and_b32_e32 v239, 0xffff0000, v185
	v_pk_fma_f32 v[28:29], v[28:29], v[236:237], v[168:169]
	v_pk_fma_f32 v[30:31], v[30:31], v[238:239], v[170:171]
	v_cvt_pk_bf16_f32 v159, v30, v31
	v_cvt_pk_bf16_f32 v158, v28, v29
	global_store_dwordx4 v[150:151], v[28:31], off
	global_store_dwordx2 v[156:157], v[158:159], off
	s_nop 0
	v_mul_f32_e32 v29, v29, v29
	v_mul_f32_e32 v31, v31, v31
	v_fmac_f32_e32 v29, v28, v28
	v_fmac_f32_e32 v31, v30, v30
	v_add_f32_e32 v229, v29, v31
	v_pk_mul_f32 v[24:25], v[24:25], v[234:235] op_sel_hi:[1,0]
	v_pk_mul_f32 v[26:27], v[26:27], v[234:235] op_sel_hi:[1,0]
	v_mul_f32_e32 v24, 0xbfb8aa3b, v24
	v_mul_f32_e32 v25, 0xbfb8aa3b, v25
	v_mul_f32_e32 v26, 0xbfb8aa3b, v26
	v_mul_f32_e32 v27, 0xbfb8aa3b, v27
	v_exp_f32_e32 v24, v24
	v_exp_f32_e32 v25, v25
	v_exp_f32_e32 v26, v26
	v_exp_f32_e32 v27, v27
	v_pk_add_f32 v[24:25], v[24:25], 1.0 op_sel_hi:[1,0]
	v_pk_add_f32 v[26:27], v[26:27], 1.0 op_sel_hi:[1,0]
	v_div_scale_f32 v224, s[10:11], v24, v24, 1.0
	v_rcp_f32_e32 v225, v224
	s_nop 0
	v_fma_f32 v226, -v224, v225, 1.0
	v_fmac_f32_e32 v225, v226, v225
	v_div_scale_f32 v226, vcc, 1.0, v24, 1.0
	v_mul_f32_e32 v227, v226, v225
	v_fma_f32 v228, -v224, v227, v226
	v_fmac_f32_e32 v227, v228, v225
	v_fma_f32 v224, -v224, v227, v226
	v_div_fmas_f32 v224, v224, v225, v227
	v_div_fixup_f32 v24, v224, v24, 1.0
	v_div_scale_f32 v224, s[10:11], v25, v25, 1.0
	v_rcp_f32_e32 v225, v224
	s_nop 0
	v_fma_f32 v226, -v224, v225, 1.0
	v_fmac_f32_e32 v225, v226, v225
	v_div_scale_f32 v226, vcc, 1.0, v25, 1.0
	v_mul_f32_e32 v227, v226, v225
	v_fma_f32 v228, -v224, v227, v226
	v_fmac_f32_e32 v227, v228, v225
	v_fma_f32 v224, -v224, v227, v226
	v_div_fmas_f32 v224, v224, v225, v227
	v_div_fixup_f32 v25, v224, v25, 1.0
	v_div_scale_f32 v224, s[10:11], v26, v26, 1.0
	v_rcp_f32_e32 v225, v224
	s_nop 0
	v_fma_f32 v226, -v224, v225, 1.0
	v_fmac_f32_e32 v225, v226, v225
	v_div_scale_f32 v226, vcc, 1.0, v26, 1.0
	v_mul_f32_e32 v227, v226, v225
	v_fma_f32 v228, -v224, v227, v226
	v_fmac_f32_e32 v227, v228, v225
	v_fma_f32 v224, -v224, v227, v226
	v_div_fmas_f32 v224, v224, v225, v227
	v_div_fixup_f32 v26, v224, v26, 1.0
	v_div_scale_f32 v224, s[10:11], v27, v27, 1.0
	v_rcp_f32_e32 v225, v224
	s_nop 0
	v_fma_f32 v226, -v224, v225, 1.0
	v_fmac_f32_e32 v225, v226, v225
	v_div_scale_f32 v226, vcc, 1.0, v27, 1.0
	v_mul_f32_e32 v227, v226, v225
	v_fma_f32 v228, -v224, v227, v226
	v_fmac_f32_e32 v227, v228, v225
	v_fma_f32 v224, -v224, v227, v226
	v_div_fmas_f32 v224, v224, v225, v227
	v_div_fixup_f32 v27, v224, v27, 1.0
	v_lshlrev_b32_e32 v236, 16, v186
	v_and_b32_e32 v237, 0xffff0000, v186
	v_lshlrev_b32_e32 v238, 16, v187
	v_and_b32_e32 v239, 0xffff0000, v187
	v_pk_fma_f32 v[24:25], v[24:25], v[236:237], v[172:173]
	v_pk_fma_f32 v[26:27], v[26:27], v[238:239], v[174:175]
	v_cvt_pk_bf16_f32 v159, v26, v27
	v_cvt_pk_bf16_f32 v158, v24, v25
	global_store_dwordx4 v[150:151], v[24:27], off offset:64
	global_store_dwordx2 v[156:157], v[158:159], off offset:32
	s_nop 0
	v_mul_f32_e32 v25, v25, v25
	v_mul_f32_e32 v27, v27, v27
	v_fmac_f32_e32 v25, v24, v24
	v_fmac_f32_e32 v27, v26, v26
	v_add_f32_e32 v24, v25, v27
	v_add_f32_e32 v229, v229, v24
	v_pk_mul_f32 v[20:21], v[20:21], v[234:235] op_sel_hi:[1,0]
	v_pk_mul_f32 v[22:23], v[22:23], v[234:235] op_sel_hi:[1,0]
	v_mul_f32_e32 v20, 0xbfb8aa3b, v20
	v_mul_f32_e32 v21, 0xbfb8aa3b, v21
	v_mul_f32_e32 v22, 0xbfb8aa3b, v22
	v_mul_f32_e32 v23, 0xbfb8aa3b, v23
	v_exp_f32_e32 v20, v20
	v_exp_f32_e32 v21, v21
	v_exp_f32_e32 v22, v22
	v_exp_f32_e32 v23, v23
	v_pk_add_f32 v[20:21], v[20:21], 1.0 op_sel_hi:[1,0]
	v_pk_add_f32 v[22:23], v[22:23], 1.0 op_sel_hi:[1,0]
	v_div_scale_f32 v224, s[10:11], v20, v20, 1.0
	v_rcp_f32_e32 v225, v224
	s_nop 0
	v_fma_f32 v226, -v224, v225, 1.0
	v_fmac_f32_e32 v225, v226, v225
	v_div_scale_f32 v226, vcc, 1.0, v20, 1.0
	v_mul_f32_e32 v227, v226, v225
	v_fma_f32 v228, -v224, v227, v226
	v_fmac_f32_e32 v227, v228, v225
	v_fma_f32 v224, -v224, v227, v226
	v_div_fmas_f32 v224, v224, v225, v227
	v_div_fixup_f32 v20, v224, v20, 1.0
	v_div_scale_f32 v224, s[10:11], v21, v21, 1.0
	v_rcp_f32_e32 v225, v224
	s_nop 0
	v_fma_f32 v226, -v224, v225, 1.0
	v_fmac_f32_e32 v225, v226, v225
	v_div_scale_f32 v226, vcc, 1.0, v21, 1.0
	v_mul_f32_e32 v227, v226, v225
	v_fma_f32 v228, -v224, v227, v226
	v_fmac_f32_e32 v227, v228, v225
	v_fma_f32 v224, -v224, v227, v226
	v_div_fmas_f32 v224, v224, v225, v227
	v_div_fixup_f32 v21, v224, v21, 1.0
	v_div_scale_f32 v224, s[10:11], v22, v22, 1.0
	v_rcp_f32_e32 v225, v224
	s_nop 0
	v_fma_f32 v226, -v224, v225, 1.0
	v_fmac_f32_e32 v225, v226, v225
	v_div_scale_f32 v226, vcc, 1.0, v22, 1.0
	v_mul_f32_e32 v227, v226, v225
	v_fma_f32 v228, -v224, v227, v226
	v_fmac_f32_e32 v227, v228, v225
	v_fma_f32 v224, -v224, v227, v226
	v_div_fmas_f32 v224, v224, v225, v227
	v_div_fixup_f32 v22, v224, v22, 1.0
	v_div_scale_f32 v224, s[10:11], v23, v23, 1.0
	v_rcp_f32_e32 v225, v224
	s_nop 0
	v_fma_f32 v226, -v224, v225, 1.0
	v_fmac_f32_e32 v225, v226, v225
	v_div_scale_f32 v226, vcc, 1.0, v23, 1.0
	v_mul_f32_e32 v227, v226, v225
	v_fma_f32 v228, -v224, v227, v226
	v_fmac_f32_e32 v227, v228, v225
	v_fma_f32 v224, -v224, v227, v226
	v_div_fmas_f32 v224, v224, v225, v227
	v_div_fixup_f32 v23, v224, v23, 1.0
	v_lshlrev_b32_e32 v236, 16, v188
	v_and_b32_e32 v237, 0xffff0000, v188
	v_lshlrev_b32_e32 v238, 16, v189
	v_and_b32_e32 v239, 0xffff0000, v189
	v_pk_fma_f32 v[20:21], v[20:21], v[236:237], v[176:177]
	v_pk_fma_f32 v[22:23], v[22:23], v[238:239], v[178:179]
	v_cvt_pk_bf16_f32 v159, v22, v23
	v_cvt_pk_bf16_f32 v158, v20, v21
	global_store_dwordx4 v[150:151], v[20:23], off offset:512
	global_store_dwordx2 v[156:157], v[158:159], off offset:256
	s_nop 0
	v_mul_f32_e32 v21, v21, v21
	v_mul_f32_e32 v23, v23, v23
	v_fmac_f32_e32 v21, v20, v20
	v_fmac_f32_e32 v23, v22, v22
	v_add_f32_e32 v20, v21, v23
	v_add_f32_e32 v229, v229, v20
	v_pk_mul_f32 v[16:17], v[16:17], v[234:235] op_sel_hi:[1,0]
	v_pk_mul_f32 v[18:19], v[18:19], v[234:235] op_sel_hi:[1,0]
	v_mul_f32_e32 v16, 0xbfb8aa3b, v16
	v_mul_f32_e32 v17, 0xbfb8aa3b, v17
	v_mul_f32_e32 v18, 0xbfb8aa3b, v18
	v_mul_f32_e32 v19, 0xbfb8aa3b, v19
	v_exp_f32_e32 v16, v16
	v_exp_f32_e32 v17, v17
	v_exp_f32_e32 v18, v18
	v_exp_f32_e32 v19, v19
	v_pk_add_f32 v[16:17], v[16:17], 1.0 op_sel_hi:[1,0]
	v_pk_add_f32 v[18:19], v[18:19], 1.0 op_sel_hi:[1,0]
	v_div_scale_f32 v224, s[10:11], v16, v16, 1.0
	v_rcp_f32_e32 v225, v224
	s_nop 0
	v_fma_f32 v226, -v224, v225, 1.0
	v_fmac_f32_e32 v225, v226, v225
	v_div_scale_f32 v226, vcc, 1.0, v16, 1.0
	v_mul_f32_e32 v227, v226, v225
	v_fma_f32 v228, -v224, v227, v226
	v_fmac_f32_e32 v227, v228, v225
	v_fma_f32 v224, -v224, v227, v226
	v_div_fmas_f32 v224, v224, v225, v227
	v_div_fixup_f32 v16, v224, v16, 1.0
	v_div_scale_f32 v224, s[10:11], v17, v17, 1.0
	v_rcp_f32_e32 v225, v224
	s_nop 0
	v_fma_f32 v226, -v224, v225, 1.0
	v_fmac_f32_e32 v225, v226, v225
	v_div_scale_f32 v226, vcc, 1.0, v17, 1.0
	v_mul_f32_e32 v227, v226, v225
	v_fma_f32 v228, -v224, v227, v226
	v_fmac_f32_e32 v227, v228, v225
	v_fma_f32 v224, -v224, v227, v226
	v_div_fmas_f32 v224, v224, v225, v227
	v_div_fixup_f32 v17, v224, v17, 1.0
	v_div_scale_f32 v224, s[10:11], v18, v18, 1.0
	v_rcp_f32_e32 v225, v224
	s_nop 0
	v_fma_f32 v226, -v224, v225, 1.0
	v_fmac_f32_e32 v225, v226, v225
	v_div_scale_f32 v226, vcc, 1.0, v18, 1.0
	v_mul_f32_e32 v227, v226, v225
	v_fma_f32 v228, -v224, v227, v226
	v_fmac_f32_e32 v227, v228, v225
	v_fma_f32 v224, -v224, v227, v226
	v_div_fmas_f32 v224, v224, v225, v227
	v_div_fixup_f32 v18, v224, v18, 1.0
	v_div_scale_f32 v224, s[10:11], v19, v19, 1.0
	v_rcp_f32_e32 v225, v224
	s_nop 0
	v_fma_f32 v226, -v224, v225, 1.0
	v_fmac_f32_e32 v225, v226, v225
	v_div_scale_f32 v226, vcc, 1.0, v19, 1.0
	v_mul_f32_e32 v227, v226, v225
	v_fma_f32 v228, -v224, v227, v226
	v_fmac_f32_e32 v227, v228, v225
	v_fma_f32 v224, -v224, v227, v226
	v_div_fmas_f32 v224, v224, v225, v227
	v_div_fixup_f32 v19, v224, v19, 1.0
	v_lshlrev_b32_e32 v236, 16, v190
	v_and_b32_e32 v237, 0xffff0000, v190
	v_lshlrev_b32_e32 v238, 16, v191
	v_and_b32_e32 v239, 0xffff0000, v191
	v_pk_fma_f32 v[16:17], v[16:17], v[236:237], v[180:181]
	v_pk_fma_f32 v[18:19], v[18:19], v[238:239], v[182:183]
	v_cvt_pk_bf16_f32 v159, v18, v19
	v_cvt_pk_bf16_f32 v158, v16, v17
	global_store_dwordx4 v[150:151], v[16:19], off offset:576
	global_store_dwordx2 v[156:157], v[158:159], off offset:288
	s_nop 0
	v_mul_f32_e32 v17, v17, v17
	v_mul_f32_e32 v19, v19, v19
	v_fmac_f32_e32 v17, v16, v16
	v_fmac_f32_e32 v19, v18, v18
	v_add_f32_e32 v16, v17, v19
	v_add_f32_e32 v229, v229, v16
	v_mov_b32_e32 v230, v229
	s_nop 1
	v_permlane16_swap_b32_e32 v229, v230
	v_add_f32_e32 v229, v229, v230
	v_mov_b32_e32 v230, v229
	s_nop 1
	v_permlane32_swap_b32_e32 v229, v230
	s_and_saveexec_b64 s[10:11], s[6:7]
	v_lshl_add_u64 v[156:157], v[144:145], 2, s[18:19]
	v_add_f32_e32 v229, v229, v230
	global_atomic_add_f32 v[156:157], v229, off
	s_or_b64 exec, exec, s[10:11]
	s_waitcnt vmcnt(9)
	v_fmamk_f32 v223, v223, 0x3a000000, v164
	v_mul_f32_e32 v235, 0x4b800000, v223
	v_cmp_gt_f32_e32 vcc, s61, v223
	s_nop 1
	v_cndmask_b32_e32 v223, v223, v235, vcc
	v_rsq_f32_e32 v223, v223
	s_nop 0
	v_mul_f32_e32 v235, 0x45800000, v223
	v_cndmask_b32_e32 v234, v223, v235, vcc
	v_add_u32_e32 v144, 0xb0, v154
	v_mov_b32_e32 v145, v155
	v_lshlrev_b64 v[148:149], 11, v[144:145]
	v_lshl_add_u64 v[148:149], v[148:149], 0, v[146:147]
	v_lshl_add_u64 v[150:151], v[148:149], 2, s[28:29]
	v_lshl_add_u64 v[156:157], v[148:149], 1, s[24:25]
	v_pk_mul_f32 v[12:13], v[12:13], v[234:235] op_sel_hi:[1,0]
	v_pk_mul_f32 v[14:15], v[14:15], v[234:235] op_sel_hi:[1,0]
	v_mul_f32_e32 v12, 0xbfb8aa3b, v12
	v_mul_f32_e32 v13, 0xbfb8aa3b, v13
	v_mul_f32_e32 v14, 0xbfb8aa3b, v14
	v_mul_f32_e32 v15, 0xbfb8aa3b, v15
	v_exp_f32_e32 v12, v12
	v_exp_f32_e32 v13, v13
	v_exp_f32_e32 v14, v14
	v_exp_f32_e32 v15, v15
	v_pk_add_f32 v[12:13], v[12:13], 1.0 op_sel_hi:[1,0]
	v_pk_add_f32 v[14:15], v[14:15], 1.0 op_sel_hi:[1,0]
	v_div_scale_f32 v224, s[10:11], v12, v12, 1.0
	v_rcp_f32_e32 v225, v224
	s_nop 0
	v_fma_f32 v226, -v224, v225, 1.0
	v_fmac_f32_e32 v225, v226, v225
	v_div_scale_f32 v226, vcc, 1.0, v12, 1.0
	v_mul_f32_e32 v227, v226, v225
	v_fma_f32 v228, -v224, v227, v226
	v_fmac_f32_e32 v227, v228, v225
	v_fma_f32 v224, -v224, v227, v226
	v_div_fmas_f32 v224, v224, v225, v227
	v_div_fixup_f32 v12, v224, v12, 1.0
	v_div_scale_f32 v224, s[10:11], v13, v13, 1.0
	v_rcp_f32_e32 v225, v224
	s_nop 0
	v_fma_f32 v226, -v224, v225, 1.0
	v_fmac_f32_e32 v225, v226, v225
	v_div_scale_f32 v226, vcc, 1.0, v13, 1.0
	v_mul_f32_e32 v227, v226, v225
	v_fma_f32 v228, -v224, v227, v226
	v_fmac_f32_e32 v227, v228, v225
	v_fma_f32 v224, -v224, v227, v226
	v_div_fmas_f32 v224, v224, v225, v227
	v_div_fixup_f32 v13, v224, v13, 1.0
	v_div_scale_f32 v224, s[10:11], v14, v14, 1.0
	v_rcp_f32_e32 v225, v224
	s_nop 0
	v_fma_f32 v226, -v224, v225, 1.0
	v_fmac_f32_e32 v225, v226, v225
	v_div_scale_f32 v226, vcc, 1.0, v14, 1.0
	v_mul_f32_e32 v227, v226, v225
	v_fma_f32 v228, -v224, v227, v226
	v_fmac_f32_e32 v227, v228, v225
	v_fma_f32 v224, -v224, v227, v226
	v_div_fmas_f32 v224, v224, v225, v227
	v_div_fixup_f32 v14, v224, v14, 1.0
	v_div_scale_f32 v224, s[10:11], v15, v15, 1.0
	v_rcp_f32_e32 v225, v224
	s_nop 0
	v_fma_f32 v226, -v224, v225, 1.0
	v_fmac_f32_e32 v225, v226, v225
	v_div_scale_f32 v226, vcc, 1.0, v15, 1.0
	v_mul_f32_e32 v227, v226, v225
	v_fma_f32 v228, -v224, v227, v226
	v_fmac_f32_e32 v227, v228, v225
	v_fma_f32 v224, -v224, v227, v226
	v_div_fmas_f32 v224, v224, v225, v227
	v_div_fixup_f32 v15, v224, v15, 1.0
	v_lshlrev_b32_e32 v236, 16, v208
	v_and_b32_e32 v237, 0xffff0000, v208
	v_lshlrev_b32_e32 v238, 16, v209
	v_and_b32_e32 v239, 0xffff0000, v209
	v_pk_fma_f32 v[12:13], v[12:13], v[236:237], v[192:193]
	v_pk_fma_f32 v[14:15], v[14:15], v[238:239], v[194:195]
	v_cvt_pk_bf16_f32 v159, v14, v15
	v_cvt_pk_bf16_f32 v158, v12, v13
	global_store_dwordx4 v[150:151], v[12:15], off
	global_store_dwordx2 v[156:157], v[158:159], off
	s_nop 0
	v_mul_f32_e32 v13, v13, v13
	v_mul_f32_e32 v15, v15, v15
	v_fmac_f32_e32 v13, v12, v12
	v_fmac_f32_e32 v15, v14, v14
	v_add_f32_e32 v229, v13, v15
	v_pk_mul_f32 v[8:9], v[8:9], v[234:235] op_sel_hi:[1,0]
	v_pk_mul_f32 v[10:11], v[10:11], v[234:235] op_sel_hi:[1,0]
	v_mul_f32_e32 v8, 0xbfb8aa3b, v8
	v_mul_f32_e32 v9, 0xbfb8aa3b, v9
	v_mul_f32_e32 v10, 0xbfb8aa3b, v10
	v_mul_f32_e32 v11, 0xbfb8aa3b, v11
	v_exp_f32_e32 v8, v8
	v_exp_f32_e32 v9, v9
	v_exp_f32_e32 v10, v10
	v_exp_f32_e32 v11, v11
	v_pk_add_f32 v[8:9], v[8:9], 1.0 op_sel_hi:[1,0]
	v_pk_add_f32 v[10:11], v[10:11], 1.0 op_sel_hi:[1,0]
	v_div_scale_f32 v224, s[10:11], v8, v8, 1.0
	v_rcp_f32_e32 v225, v224
	s_nop 0
	v_fma_f32 v226, -v224, v225, 1.0
	v_fmac_f32_e32 v225, v226, v225
	v_div_scale_f32 v226, vcc, 1.0, v8, 1.0
	v_mul_f32_e32 v227, v226, v225
	v_fma_f32 v228, -v224, v227, v226
	v_fmac_f32_e32 v227, v228, v225
	v_fma_f32 v224, -v224, v227, v226
	v_div_fmas_f32 v224, v224, v225, v227
	v_div_fixup_f32 v8, v224, v8, 1.0
	v_div_scale_f32 v224, s[10:11], v9, v9, 1.0
	v_rcp_f32_e32 v225, v224
	s_nop 0
	v_fma_f32 v226, -v224, v225, 1.0
	v_fmac_f32_e32 v225, v226, v225
	v_div_scale_f32 v226, vcc, 1.0, v9, 1.0
	v_mul_f32_e32 v227, v226, v225
	v_fma_f32 v228, -v224, v227, v226
	v_fmac_f32_e32 v227, v228, v225
	v_fma_f32 v224, -v224, v227, v226
	v_div_fmas_f32 v224, v224, v225, v227
	v_div_fixup_f32 v9, v224, v9, 1.0
	v_div_scale_f32 v224, s[10:11], v10, v10, 1.0
	v_rcp_f32_e32 v225, v224
	s_nop 0
	v_fma_f32 v226, -v224, v225, 1.0
	v_fmac_f32_e32 v225, v226, v225
	v_div_scale_f32 v226, vcc, 1.0, v10, 1.0
	v_mul_f32_e32 v227, v226, v225
	v_fma_f32 v228, -v224, v227, v226
	v_fmac_f32_e32 v227, v228, v225
	v_fma_f32 v224, -v224, v227, v226
	v_div_fmas_f32 v224, v224, v225, v227
	v_div_fixup_f32 v10, v224, v10, 1.0
	v_div_scale_f32 v224, s[10:11], v11, v11, 1.0
	v_rcp_f32_e32 v225, v224
	s_nop 0
	v_fma_f32 v226, -v224, v225, 1.0
	v_fmac_f32_e32 v225, v226, v225
	v_div_scale_f32 v226, vcc, 1.0, v11, 1.0
	v_mul_f32_e32 v227, v226, v225
	v_fma_f32 v228, -v224, v227, v226
	v_fmac_f32_e32 v227, v228, v225
	v_fma_f32 v224, -v224, v227, v226
	v_div_fmas_f32 v224, v224, v225, v227
	v_div_fixup_f32 v11, v224, v11, 1.0
	v_lshlrev_b32_e32 v236, 16, v210
	v_and_b32_e32 v237, 0xffff0000, v210
	v_lshlrev_b32_e32 v238, 16, v211
	v_and_b32_e32 v239, 0xffff0000, v211
	v_pk_fma_f32 v[8:9], v[8:9], v[236:237], v[196:197]
	v_pk_fma_f32 v[10:11], v[10:11], v[238:239], v[198:199]
	v_cvt_pk_bf16_f32 v159, v10, v11
	v_cvt_pk_bf16_f32 v158, v8, v9
	global_store_dwordx4 v[150:151], v[8:11], off offset:64
	global_store_dwordx2 v[156:157], v[158:159], off offset:32
	s_nop 0
	v_mul_f32_e32 v9, v9, v9
	v_mul_f32_e32 v11, v11, v11
	v_fmac_f32_e32 v9, v8, v8
	v_fmac_f32_e32 v11, v10, v10
	v_add_f32_e32 v8, v9, v11
	v_add_f32_e32 v229, v229, v8
	v_pk_mul_f32 v[4:5], v[4:5], v[234:235] op_sel_hi:[1,0]
	v_pk_mul_f32 v[6:7], v[6:7], v[234:235] op_sel_hi:[1,0]
	v_mul_f32_e32 v4, 0xbfb8aa3b, v4
	v_mul_f32_e32 v5, 0xbfb8aa3b, v5
	v_mul_f32_e32 v6, 0xbfb8aa3b, v6
	v_mul_f32_e32 v7, 0xbfb8aa3b, v7
	v_exp_f32_e32 v4, v4
	v_exp_f32_e32 v5, v5
	v_exp_f32_e32 v6, v6
	v_exp_f32_e32 v7, v7
	v_pk_add_f32 v[4:5], v[4:5], 1.0 op_sel_hi:[1,0]
	v_pk_add_f32 v[6:7], v[6:7], 1.0 op_sel_hi:[1,0]
	v_div_scale_f32 v224, s[10:11], v4, v4, 1.0
	v_rcp_f32_e32 v225, v224
	s_nop 0
	v_fma_f32 v226, -v224, v225, 1.0
	v_fmac_f32_e32 v225, v226, v225
	v_div_scale_f32 v226, vcc, 1.0, v4, 1.0
	v_mul_f32_e32 v227, v226, v225
	v_fma_f32 v228, -v224, v227, v226
	v_fmac_f32_e32 v227, v228, v225
	v_fma_f32 v224, -v224, v227, v226
	v_div_fmas_f32 v224, v224, v225, v227
	v_div_fixup_f32 v4, v224, v4, 1.0
	v_div_scale_f32 v224, s[10:11], v5, v5, 1.0
	v_rcp_f32_e32 v225, v224
	s_nop 0
	v_fma_f32 v226, -v224, v225, 1.0
	v_fmac_f32_e32 v225, v226, v225
	v_div_scale_f32 v226, vcc, 1.0, v5, 1.0
	v_mul_f32_e32 v227, v226, v225
	v_fma_f32 v228, -v224, v227, v226
	v_fmac_f32_e32 v227, v228, v225
	v_fma_f32 v224, -v224, v227, v226
	v_div_fmas_f32 v224, v224, v225, v227
	v_div_fixup_f32 v5, v224, v5, 1.0
	v_div_scale_f32 v224, s[10:11], v6, v6, 1.0
	v_rcp_f32_e32 v225, v224
	s_nop 0
	v_fma_f32 v226, -v224, v225, 1.0
	v_fmac_f32_e32 v225, v226, v225
	v_div_scale_f32 v226, vcc, 1.0, v6, 1.0
	v_mul_f32_e32 v227, v226, v225
	v_fma_f32 v228, -v224, v227, v226
	v_fmac_f32_e32 v227, v228, v225
	v_fma_f32 v224, -v224, v227, v226
	v_div_fmas_f32 v224, v224, v225, v227
	v_div_fixup_f32 v6, v224, v6, 1.0
	v_div_scale_f32 v224, s[10:11], v7, v7, 1.0
	v_rcp_f32_e32 v225, v224
	s_nop 0
	v_fma_f32 v226, -v224, v225, 1.0
	v_fmac_f32_e32 v225, v226, v225
	v_div_scale_f32 v226, vcc, 1.0, v7, 1.0
	v_mul_f32_e32 v227, v226, v225
	v_fma_f32 v228, -v224, v227, v226
	v_fmac_f32_e32 v227, v228, v225
	v_fma_f32 v224, -v224, v227, v226
	v_div_fmas_f32 v224, v224, v225, v227
	v_div_fixup_f32 v7, v224, v7, 1.0
	v_lshlrev_b32_e32 v236, 16, v212
	v_and_b32_e32 v237, 0xffff0000, v212
	v_lshlrev_b32_e32 v238, 16, v213
	v_and_b32_e32 v239, 0xffff0000, v213
	v_pk_fma_f32 v[4:5], v[4:5], v[236:237], v[200:201]
	v_pk_fma_f32 v[6:7], v[6:7], v[238:239], v[202:203]
	v_cvt_pk_bf16_f32 v159, v6, v7
	v_cvt_pk_bf16_f32 v158, v4, v5
	global_store_dwordx4 v[150:151], v[4:7], off offset:512
	global_store_dwordx2 v[156:157], v[158:159], off offset:256
	s_nop 0
	v_mul_f32_e32 v5, v5, v5
	v_mul_f32_e32 v7, v7, v7
	v_fmac_f32_e32 v5, v4, v4
	v_fmac_f32_e32 v7, v6, v6
	v_add_f32_e32 v4, v5, v7
	v_add_f32_e32 v229, v229, v4
	v_pk_mul_f32 v[0:1], v[0:1], v[234:235] op_sel_hi:[1,0]
	v_pk_mul_f32 v[2:3], v[2:3], v[234:235] op_sel_hi:[1,0]
	v_mul_f32_e32 v0, 0xbfb8aa3b, v0
	v_mul_f32_e32 v1, 0xbfb8aa3b, v1
	v_mul_f32_e32 v2, 0xbfb8aa3b, v2
	v_mul_f32_e32 v3, 0xbfb8aa3b, v3
	v_exp_f32_e32 v0, v0
	v_exp_f32_e32 v1, v1
	v_exp_f32_e32 v2, v2
	v_exp_f32_e32 v3, v3
	v_pk_add_f32 v[0:1], v[0:1], 1.0 op_sel_hi:[1,0]
	v_pk_add_f32 v[2:3], v[2:3], 1.0 op_sel_hi:[1,0]
	v_div_scale_f32 v224, s[10:11], v0, v0, 1.0
	v_rcp_f32_e32 v225, v224
	s_nop 0
	v_fma_f32 v226, -v224, v225, 1.0
	v_fmac_f32_e32 v225, v226, v225
	v_div_scale_f32 v226, vcc, 1.0, v0, 1.0
	v_mul_f32_e32 v227, v226, v225
	v_fma_f32 v228, -v224, v227, v226
	v_fmac_f32_e32 v227, v228, v225
	v_fma_f32 v224, -v224, v227, v226
	v_div_fmas_f32 v224, v224, v225, v227
	v_div_fixup_f32 v0, v224, v0, 1.0
	v_div_scale_f32 v224, s[10:11], v1, v1, 1.0
	v_rcp_f32_e32 v225, v224
	s_nop 0
	v_fma_f32 v226, -v224, v225, 1.0
	v_fmac_f32_e32 v225, v226, v225
	v_div_scale_f32 v226, vcc, 1.0, v1, 1.0
	v_mul_f32_e32 v227, v226, v225
	v_fma_f32 v228, -v224, v227, v226
	v_fmac_f32_e32 v227, v228, v225
	v_fma_f32 v224, -v224, v227, v226
	v_div_fmas_f32 v224, v224, v225, v227
	v_div_fixup_f32 v1, v224, v1, 1.0
	v_div_scale_f32 v224, s[10:11], v2, v2, 1.0
	v_rcp_f32_e32 v225, v224
	s_nop 0
	v_fma_f32 v226, -v224, v225, 1.0
	v_fmac_f32_e32 v225, v226, v225
	v_div_scale_f32 v226, vcc, 1.0, v2, 1.0
	v_mul_f32_e32 v227, v226, v225
	v_fma_f32 v228, -v224, v227, v226
	v_fmac_f32_e32 v227, v228, v225
	v_fma_f32 v224, -v224, v227, v226
	v_div_fmas_f32 v224, v224, v225, v227
	v_div_fixup_f32 v2, v224, v2, 1.0
	v_div_scale_f32 v224, s[10:11], v3, v3, 1.0
	v_rcp_f32_e32 v225, v224
	s_nop 0
	v_fma_f32 v226, -v224, v225, 1.0
	v_fmac_f32_e32 v225, v226, v225
	v_div_scale_f32 v226, vcc, 1.0, v3, 1.0
	v_mul_f32_e32 v227, v226, v225
	v_fma_f32 v228, -v224, v227, v226
	v_fmac_f32_e32 v227, v228, v225
	v_fma_f32 v224, -v224, v227, v226
	v_div_fmas_f32 v224, v224, v225, v227
	v_div_fixup_f32 v3, v224, v3, 1.0
	v_lshlrev_b32_e32 v236, 16, v214
	v_and_b32_e32 v237, 0xffff0000, v214
	v_lshlrev_b32_e32 v238, 16, v215
	v_and_b32_e32 v239, 0xffff0000, v215
	v_pk_fma_f32 v[0:1], v[0:1], v[236:237], v[204:205]
	v_pk_fma_f32 v[2:3], v[2:3], v[238:239], v[206:207]
	v_cvt_pk_bf16_f32 v159, v2, v3
	v_cvt_pk_bf16_f32 v158, v0, v1
	global_store_dwordx4 v[150:151], v[0:3], off offset:576
	global_store_dwordx2 v[156:157], v[158:159], off offset:288
	s_nop 0
	v_mul_f32_e32 v1, v1, v1
	v_mul_f32_e32 v3, v3, v3
	v_fmac_f32_e32 v1, v0, v0
	v_fmac_f32_e32 v3, v2, v2
	v_add_f32_e32 v0, v1, v3
	v_add_f32_e32 v229, v229, v0
	v_mov_b32_e32 v230, v229
	s_nop 1
	v_permlane16_swap_b32_e32 v229, v230
	v_add_f32_e32 v229, v229, v230
	v_mov_b32_e32 v230, v229
	s_nop 1
	v_permlane32_swap_b32_e32 v229, v230
	s_and_saveexec_b64 s[10:11], s[6:7]
	v_lshl_add_u64 v[156:157], v[144:145], 2, s[18:19]
	v_add_f32_e32 v229, v229, v230
	global_atomic_add_f32 v[156:157], v229, off
	s_or_b64 exec, exec, s[10:11]
	s_branch .LBB0_1885
